# per-unit wave-group re-sync applied to all six GEMM instances
# speedup vs baseline: 1.0325x; 1.0023x over previous
; #define LAS __attribute__((address_space(3)))
;     __device__ __forceinline__ bool next(int i, Unit& u) const {
;         const long L = (long)i * G + c; if (L >= total) return false;
;         const int z = (int)(L / per); int wgid = (int)(L % per);
;         { const int q = per / NXCD, r = per % NXCD, xcd = wgid % NXCD, off = wgid / NXCD; wgid = (xcd < r ? xcd * (q + 1) : r * (q + 1) + (xcd - r) * q) + off; }
;         const int nig = WGM * nN, gid = wgid / nig, fm = gid * WGM, gsz = (nM - fm) < WGM ? (nM - fm) : WGM;
;         u.pm = fm + ((wgid % nig) % gsz); u.pn = (wgid % nig) / gsz; u.zb = z / nh; u.zh = z % nh;
;         u.ao = u.zb * sAb + u.zh * sAh + u.pm * tA; u.bo = u.zb * sBb + u.zh * sBh + u.pn * tB; return true;
;     }
; template <class Epi>
; __device__ __forceinline__ void gemm_phase(LAS unsigned char* lds, const Gemm g, const Sched& S, const Epi& E) {
;     const int tid = otid(), wid = __builtin_amdgcn_readfirstlane(tid >> 6), lane = tid & 63, wr = wid >> 2, wc = wid & 3, fr = lane & 15, fq = lane >> 4;
;     const int nt = g.K / BK;
;     unsigned voffA[2], voffB[2];
; #pragma unroll
;     for (int i = 0; i < 2; ++i) { int R, C; stage_rc(tid * 16 + i * 8192, R, C); const int Rb = Epi::PERM ? ((R & ~31) + perm32(R & 31)) : R;
;         voffA[i] = (unsigned)(R * g.lda + C) * 2u; voffB[i] = (unsigned)(Rb * g.ldb + C) * 2u; }
;     const size_t kstep = (size_t)(BK * 2);
;     const size_t hstepA = (size_t)HALF * g.lda * 2, hstepB = (size_t)HALF * g.ldb * 2;
;     const unsigned ldsw = (unsigned)wid * 1024u;
;     const int aoff = lds_byte(wr * 64 + fr, fq * 8), boff = lds_byte(wc * 32 + fr, fq * 8);
;     ...
;     Unit cur, nxt; int ui = 0;
;     if (!S.next(0, cur)) return;
;     f32x4 acc[2][2][4][2];
; #pragma unroll
;     for (int a = 0; a < 2; ++a)
; #pragma unroll
;         for (int b = 0; b < 2; ++b)
; #pragma unroll
;             for (int m = 0; m < 4; ++m)
; #pragma unroll
;                 for (int n = 0; n < 2; ++n) acc[a][b][m][n] = (f32x4){0.f, 0.f, 0.f, 0.f};
;     bf16x8 At[4][2], B0[2][2], B1[2][2];
;     const char* cA = (const char*)g.A + cur.ao; const char* cB = (const char*)g.Bt + cur.bo;
;     PG8_STAGE(PG8_SB(0, 0), cB, voffB); PG8_STAGE(PG8_SA(0, 0), cA, voffA); PG8_STAGE(PG8_SB(0, 1), cB + hstepB, voffB); PG8_STAGE(PG8_SA(0, 1), cA + hstepA, voffA);
.LBB0_383:
	s_andn2_b64 vcc, exec, s[0:1]
	s_cbranch_vccnz .LBB0_437
	v_bfe_i32 v3, v17, 27, 1
	v_lshlrev_b32_e32 v2, 4, v17
	v_lshrrev_b32_e32 v3, 22, v3
	v_add_u32_e32 v3, v2, v3
	v_and_b32_e32 v3, 0xfffffc00, v3
	v_ashrrev_i32_e32 v0, 31, v17
	v_sub_u32_e32 v3, v2, v3
	v_lshrrev_b32_e32 v0, 26, v0
	v_lshrrev_b32_e32 v4, 4, v3
	v_add_u32_e32 v0, v17, v0
	v_bitop3_b32 v4, v4, v3, 32 bitop3:0x6c
	v_ashrrev_i32_e32 v3, 31, v3
	v_ashrrev_i32_e32 v0, 6, v0
	v_lshrrev_b32_e32 v3, 26, v3
	v_lshlrev_b32_e32 v5, 3, v0
	v_add_u32_e32 v3, v4, v3
	v_and_b32_e32 v5, -16, v5
	v_ashrrev_i32_e32 v3, 6, v3
	v_add_u32_e32 v5, v3, v5
	v_mul_i32_i24_e32 v6, 64, v3
	v_sub_u32_e32 v4, v4, v6
	v_mov_b32_e32 v8, 1
	v_lshlrev_b32_e32 v6, 1, v5
	v_lshrrev_b32_e32 v7, 2, v5
	v_and_b32_e32 v3, 3, v3
	s_mov_b32 s1, 0x7fffffe0
	v_lshlrev_b32_e32 v0, 5, v0
	v_ashrrev_i16_sdwa v4, v8, sext(v4) dst_sel:DWORD dst_unused:UNUSED_PAD src0_sel:DWORD src1_sel:BYTE_0
	v_and_b32_e32 v6, 24, v6
	v_and_b32_e32 v7, 4, v7
	v_and_or_b32 v3, v5, s1, v3
	v_and_b32_e32 v0, 32, v0
	v_bfe_i32 v14, v4, 0, 16
	v_or3_b32 v3, v3, v7, v6
	v_add_u32_e32 v4, v0, v14
	v_mul_lo_u32 v3, v3, s66
	v_add_u32_e32 v2, 0x2000, v2
	v_add_lshl_u32 v132, v3, v4, 1
	v_ashrrev_i32_e32 v3, 31, v2
	v_lshrrev_b32_e32 v3, 22, v3
	v_add_u32_e32 v3, v2, v3
	v_mul_lo_u32 v15, v5, s82
	v_ashrrev_i32_e32 v3, 10, v3
	v_add_lshl_u32 v130, v4, v15, 1
	v_mul_i32_i24_e32 v4, 0x400, v3
	v_sub_u32_e32 v2, v2, v4
	v_lshrrev_b32_e32 v4, 4, v2
	v_bitop3_b32 v2, v4, v2, 32 bitop3:0x6c
	v_writelane_b32 v254, s53, 57
	v_ashrrev_i32_e32 v5, 31, v2
	v_writelane_b32 v254, s51, 55
	v_lshrrev_b32_e32 v5, 26, v5
	v_writelane_b32 v254, s48, 53
	v_lshlrev_b32_e32 v4, 3, v3
	v_add_u32_e32 v5, v2, v5
	v_writelane_b32 v254, s84, 49
	v_and_b32_e32 v4, -16, v4
	v_ashrrev_i32_e32 v6, 6, v5
	v_lshlrev_b32_e32 v3, 5, v3
	v_writelane_b32 v254, s85, 50
	v_add_u32_e32 v4, v6, v4
	v_and_b32_e32 v16, 32, v3
	v_and_b32_e32 v3, 0xc0, v5
	v_writelane_b32 v254, s57, 37
	v_sub_u32_e32 v2, v2, v3
	v_lshlrev_b32_e32 v3, 1, v4
	v_lshrrev_b32_e32 v5, 2, v4
	v_and_b32_e32 v6, 3, v6
	v_readlane_b32 s2, v254, 51
	v_and_b32_e32 v3, 24, v3
	v_and_b32_e32 v5, 4, v5
	v_and_or_b32 v6, v4, s1, v6
	v_mul_lo_u32 v19, v4, s82
	v_writelane_b32 v254, s82, 43
	s_ashr_i32 s0, s2, 6
	v_or3_b32 v3, v6, v5, v3
	v_writelane_b32 v254, s83, 44
	v_mul_lo_u32 v3, v3, s66
	s_ashr_i32 s1, s2, 8
	s_lshl_b64 s[4:5], s[82:83], 8
	v_writelane_b32 v254, s66, 45
	s_lshl_b64 s[78:79], s[66:67], 8
	s_lshl_b32 s39, s0, 10
	s_add_u32 s94, s10, s80
	v_ashrrev_i16_sdwa v2, v8, sext(v2) dst_sel:DWORD dst_unused:UNUSED_PAD src0_sel:DWORD src1_sel:BYTE_0
	s_addc_u32 s95, s11, s81
	s_add_i32 s42, s39, 0
	v_bfe_i32 v18, v2, 0, 16
	v_writelane_b32 v254, s67, 46
	s_add_i32 m0, s42, 0x10000
	v_add_u32_e32 v2, v16, v18
	global_load_lds_dwordx4 v132, s[94:95]
	s_add_i32 m0, s42, 0x12000
	v_readlane_b32 s2, v254, 11
	v_add_lshl_u32 v136, v3, v2, 1
	v_readlane_b32 s3, v254, 12
	s_add_u32 s92, s2, s36
	global_load_lds_dwordx4 v136, s[94:95]
	s_addc_u32 s93, s3, s37
	s_mov_b32 m0, s42
	s_add_i32 s43, s42, 0x2000
	v_add_lshl_u32 v134, v2, v19, 1
	global_load_lds_dwordx4 v130, s[92:93]
	s_mov_b32 m0, s43
	s_add_u32 s2, s94, s78
	global_load_lds_dwordx4 v134, s[92:93]
	s_addc_u32 s3, s95, s79
	s_add_i32 m0, s42, 0x14000
	v_mov_b32_e32 v133, v1
	v_mov_b32_e32 v137, v1
	global_load_lds_dwordx4 v132, s[2:3]
	s_add_i32 m0, s42, 0x16000
	v_lshl_add_u64 v[10:11], s[2:3], 0, v[132:133]
	v_lshl_add_u64 v[12:13], s[2:3], 0, v[136:137]
	global_load_lds_dwordx4 v136, s[2:3]
	s_add_u32 s2, s92, s4
	s_addc_u32 s3, s93, s5
	s_add_i32 s52, s42, 0x4000
	s_mov_b32 m0, s52
	s_add_i32 s53, s42, 0x6000
	global_load_lds_dwordx4 v130, s[2:3]
	s_mov_b32 m0, s53
	v_mov_b32_e32 v131, v1
	global_load_lds_dwordx4 v134, s[2:3]
	v_mov_b32_e32 v135, v1
	v_lshl_add_u64 v[2:3], s[94:95], 0, v[132:133]
	v_lshl_add_u64 v[4:5], s[94:95], 0, v[136:137]
	v_lshl_add_u64 v[6:7], s[92:93], 0, v[130:131]
	v_lshl_add_u64 v[8:9], s[92:93], 0, v[134:135]
	s_cmp_lg_u32 s1, 1
	s_cbranch_scc1 .LBB0_386
; #define PG8_STAGE(bufoff, gbase, voff) do { _Pragma("unroll") for (int _i = 0; _i < 2; ++_i) \
;         __builtin_amdgcn_global_load_lds((const unsigned*)((const char*)(gbase) + (voff)[_i]), (LAS unsigned*)(lds + (bufoff) + ldsw + _i * 8192), 16, 0, 0); } while (0)
; #define PG8_WAIT_V(n) asm volatile("s_waitcnt vmcnt(" #n ")" ::: "memory")
; #define PG8_BAR __builtin_amdgcn_s_barrier()
;     __device__ __forceinline__ Pre prefetch(const Unit& u, int wr, int fr) const { return pre_rows(ss, u.pm * 256 + wr * 64 + (int)(threadIdx.x & 63)); }
;     __device__ __forceinline__ Pre prefetch(const Unit& u, int wr, int fr) const { return pre_rows(ss, u.pm * 256 + wr * 64 + (int)(threadIdx.x & 63)); }
;     __device__ __forceinline__ Pre prefetch(const Unit& u, int wr, int fr) const { return pre_rows(ss, u.pm * 256 + wr * 64 + (int)(threadIdx.x & 63)); }
; template <class Epi>
; __device__ __forceinline__ void gemm_phase(LAS unsigned char* lds, const Gemm g, const Sched& S, const Epi& E) {
;     ...
;     PG8_STAGE(PG8_SB(0, 0), cB, voffB); PG8_STAGE(PG8_SA(0, 0), cA, voffA); PG8_STAGE(PG8_SB(0, 1), cB + hstepB, voffB); PG8_STAGE(PG8_SA(0, 1), cA + hstepA, voffA);
;     if (wr == 1) PG8_BAR;
;     PG8_WAIT_V(4); PG8_BAR;
;     PG8_STAGE(PG8_SB(1, 0), cB + kstep, voffB); PG8_STAGE(PG8_SA(1, 0), cA + kstep, voffA); PG8_STAGE(PG8_SB(1, 1), cB + hstepB + kstep, voffB);
;     PG8_WAIT_V(6); PG8_BAR;
;     for (;;) {
;         const Pre pre = E.prefetch(cur, wr, fr);
;         const bool has_next = S.next(ui + 1, nxt);
;         const char* nA = has_next ? (const char*)g.A + nxt.ao : cA; const char* nB = has_next ? (const char*)g.Bt + nxt.bo : cB;
;     __device__ __forceinline__ Pre prefetch(const Unit& u, int wr, int fr) const { return pre_rows(ss, u.zb * zrow + u.pm * 256 + wr * 64 + (int)(threadIdx.x & 63)); }
;     __device__ __forceinline__ void operator()(const Acc& acc, const Unit& u, int wr, int wc, int fr, int fq, const Pre& pre) const {
;         const int row0 = u.pm * 256 + wr * 64 + fr, col0 = wc * 32 + 8 * fq;
.LBB0_386:
	s_add_i32 m0, s42, 0x18000
	v_lshl_add_u64 v[2:3], v[2:3], 0, s[60:61]
	s_waitcnt vmcnt(0)
	s_barrier
	global_load_lds_dwordx4 v[2:3], off
	v_lshl_add_u64 v[2:3], v[4:5], 0, s[60:61]
	s_add_i32 m0, s42, 0x1a000
	s_add_i32 s67, s42, 0x8000
	global_load_lds_dwordx4 v[2:3], off
	v_lshl_add_u64 v[2:3], v[6:7], 0, s[60:61]
	s_mov_b32 m0, s67
	s_add_i32 s2, s42, 0xa000
	global_load_lds_dwordx4 v[2:3], off
	v_lshl_add_u64 v[2:3], v[8:9], 0, s[60:61]
	s_mov_b32 m0, s2
	v_bfe_u32 v20, v17, 4, 2
	global_load_lds_dwordx4 v[2:3], off
	s_add_i32 m0, s42, 0x1c000
	v_lshl_add_u64 v[2:3], v[10:11], 0, s[60:61]
	global_load_lds_dwordx4 v[2:3], off
	v_lshl_add_u64 v[2:3], v[12:13], 0, s[60:61]
	s_add_i32 m0, s42, 0x1e000
	v_and_b32_e32 v150, 15, v17
	global_load_lds_dwordx4 v[2:3], off
	v_lshlrev_b32_e32 v22, 4, v20
	v_lshlrev_b32_e32 v17, 2, v17
	s_and_b32 s3, s0, 3
	s_lshl_b32 s0, s1, 6
	v_lshl_or_b32 v22, v150, 6, v22
	s_lshl_b32 s1, s1, 13
	v_and_b32_e32 v17, 32, v17
	v_readlane_b32 s8, v253, 61
	v_bitop3_b32 v23, v22, s1, v17 bitop3:0xde
	s_lshl_b32 s1, s3, 12
	s_add_i32 s71, s73, -2
	v_readlane_b32 s9, v253, 62
	s_cmp_eq_u64 s[8:9], 0
	s_cselect_b64 s[80:81], -1, 0
	s_cmp_lg_u64 s[8:9], 0
	v_readlane_b32 s8, v254, 13
	s_cselect_b64 s[82:83], -1, 0
	s_ashr_i32 s40, s8, 31
	v_readlane_b32 s8, v253, 30
	s_lshr_b32 s8, s54, 3
	v_readlane_b32 s9, v253, 31
	v_writelane_b32 v254, s8, 47
	s_add_i32 s8, s8, 1
	v_writelane_b32 v254, s8, 31
	s_mov_b32 s27, s9
	v_readlane_b32 s8, v254, 5
	v_readlane_b32 s9, v254, 37
	s_mul_i32 s56, s8, s9
	v_cvt_f32_u32_e32 v3, s56
	v_or_b32_e32 v151, s0, v150
	v_lshlrev_b32_e32 v21, 3, v20
	v_and_b32_e32 v2, 63, v219
	v_rcp_iflag_f32_e32 v3, v3
	v_or_b32_e32 v153, s0, v2
	v_lshlrev_b32_e32 v154, 4, v151
	v_lshl_or_b32 v2, s3, 5, v21
	s_add_i32 s8, 0, 0x20000
	s_lshl_b32 s3, s3, 2
	s_add_i32 s51, s8, s3
	v_add_u32_e32 v155, s8, v154
	v_readlane_b32 s8, v253, 21
	v_mul_f32_e32 v3, 0x4f7ffffe, v3
	v_cvt_u32_f32_e32 v3, v3
	v_add_u32_e32 v157, s8, v154
	v_readlane_b32 s8, v253, 22
	v_add_u32_e32 v156, s3, v155
	v_add_u32_e32 v158, s3, v157
	v_add_u32_e32 v159, s8, v154
	v_readlane_b32 s8, v253, 23
	v_add_u32_e32 v160, s3, v159
	v_add_u32_e32 v0, v15, v0
	v_add_u32_e32 v161, s8, v154
	v_readlane_b32 s8, v253, 24
	v_add_u32_e32 v162, s3, v161
	v_add_lshl_u32 v0, v0, v14, 1
	v_add_u32_e32 v163, s8, v154
	v_readlane_b32 s8, v253, 25
	v_add_u32_e32 v164, s3, v163
	s_waitcnt vmcnt(6)
	v_lshl_add_u64 v[138:139], s[4:5], 0, v[0:1]
	v_add_u32_e32 v165, s8, v154
	v_readlane_b32 s8, v253, 26
	v_add_u32_e32 v166, s3, v165
	v_add_u32_e32 v0, v19, v16
	v_add_u32_e32 v167, s8, v154
	v_readlane_b32 s8, v253, 27
	v_add_u32_e32 v168, s3, v167
	v_add_lshl_u32 v0, v0, v18, 1
	v_add_u32_e32 v169, s8, v154
	v_readfirstlane_b32 s8, v3
	v_cvt_f32_u32_e32 v3, s25
	v_add_u32_e32 v170, s3, v169
	s_sub_i32 s3, 0, s56
	s_mul_i32 s3, s3, s8
	v_rcp_iflag_f32_e32 v3, v3
	s_mul_hi_u32 s3, s8, s3
	s_add_i32 s3, s8, s3
	v_writelane_b32 v254, s3, 33
	v_mul_f32_e32 v3, 0x4f7ffffe, v3
	v_cvt_u32_f32_e32 v3, v3
	s_sub_i32 s3, 0, s25
	v_bitop3_b32 v152, v22, s1, v17 bitop3:0xde
	s_mov_b32 s38, 0
	v_readfirstlane_b32 s8, v3
	s_mul_i32 s3, s3, s8
	s_mul_hi_u32 s3, s8, s3
	s_add_i32 s3, s8, s3
	v_cmp_eq_u32_e64 s[0:1], 0, v20
	s_and_b32 s41, s54, 7
	v_writelane_b32 v254, s3, 35
	v_lshl_add_u64 v[140:141], s[4:5], 0, v[0:1]
	v_add_u32_e32 v171, 0, v23
	v_lshlrev_b32_e32 v0, 1, v2
	s_barrier
	s_branch .LBB0_388

; #define PG8_STAGE(bufoff, gbase, voff) do { _Pragma("unroll") for (int _i = 0; _i < 2; ++_i) \
;         __builtin_amdgcn_global_load_lds((const unsigned*)((const char*)(gbase) + (voff)[_i]), (LAS unsigned*)(lds + (bufoff) + ldsw + _i * 8192), 16, 0, 0); } while (0)
; #define PG8_LDA(dst, b, h) do { _Pragma("unroll") for (int m = 0; m < 4; ++m) _Pragma("unroll") for (int k = 0; k < 2; ++k) dst[m][k] = *(const LAS bf16x8*)(lds + PG8_SA(b, h) + aoff + m * 2048 + k * 1024); } while (0)
; #define PG8_LDB(dst, b, h) do { _Pragma("unroll") for (int n = 0; n < 2; ++n) _Pragma("unroll") for (int k = 0; k < 2; ++k) dst[n][k] = *(const LAS bf16x8*)(lds + PG8_SB(b, h) + boff + n * 2048 + k * 1024); } while (0)
; #define PG8_MMA(ai, bj, At, Bt) do { __builtin_amdgcn_s_setprio(1); _Pragma("unroll") for (int m = 0; m < 4; ++m) _Pragma("unroll") for (int n = 0; n < 2; ++n) _Pragma("unroll") for (int k = 0; k < 2; ++k) \
;         acc[ai][bj][m][n] = __builtin_amdgcn_mfma_f32_16x16x32_bf16(Bt[n][k], At[m][k], acc[ai][bj][m][n], 0, 0, 0); __builtin_amdgcn_s_setprio(0); } while (0)
; #define PG8_WAIT_L(n) asm volatile("s_waitcnt lgkmcnt(" #n ")" ::: "memory")
; #define PG8_BAR __builtin_amdgcn_s_barrier()
; #define PG8_SCHED __builtin_amdgcn_sched_barrier(0)
; template <class Epi>
; __device__ __forceinline__ void gemm_phase(LAS unsigned char* lds, const Gemm g, const Sched& S, const Epi& E) {
;     ...
;         const bool has_next = S.next(ui + 1, nxt);
;         const char* nA = has_next ? (const char*)g.A + nxt.ao : cA; const char* nB = has_next ? (const char*)g.Bt + nxt.bo : cB;
;         for (int t = 0; t < nt; t += 2) {
;             const bool last = (t == nt - 2);
;             const char* a1 = cA + (size_t)(t + 1) * kstep;
;             const char* a2 = last ? nA : cA + (size_t)(t + 2) * kstep; const char* b2 = last ? nB : cB + (size_t)(t + 2) * kstep;
;             const char* a3 = a2 + kstep; const char* b3 = b2 + kstep;
;             PG8_LDB(B0, 0, 0); PG8_SCHED; PG8_LDA(At, 0, 0); PG8_STAGE(PG8_SA(1, 1), a1 + hstepA, voffA);
;             PG8_WAIT_L(8); PG8_BAR; PG8_WAIT_L(0); PG8_MMA(0, 0, At, B0); PG8_BAR; PG8_SCHED;
;             PG8_LDB(B1, 0, 1); PG8_STAGE(PG8_SB(0, 0), b2, voffB);
;             PG8_BAR; PG8_WAIT_L(0); PG8_MMA(0, 1, At, B1); PG8_BAR;
;     ...
;                     for (int n = 0; n < 2; ++n) acc[a][b][m][n] = (f32x4){0.f, 0.f, 0.f, 0.f};
.LBB0_399:
	v_mov_b64_e32 v[2:3], s[26:27]
	v_readlane_b32 s8, v254, 11
	v_cmp_lt_i64_e32 vcc, s[88:89], v[2:3]
	v_readlane_b32 s9, v254, 12
	s_add_u32 s88, s8, s84
	s_addc_u32 s89, s9, s85
	s_and_b64 s[14:15], vcc, exec
	s_cselect_b32 s55, s89, s93
	s_cselect_b32 s57, s88, s92
	s_add_u32 s90, s10, s86
	s_addc_u32 s91, s11, s87
	s_and_b64 s[14:15], vcc, exec
	s_cselect_b32 s59, s91, s95
	s_cselect_b32 s65, s90, s94
	s_add_u32 s92, s92, 0x80
	s_addc_u32 s93, s93, 0
	s_add_u32 s34, s94, 0x100
	v_mov_b32_e32 v2, 0
	s_addc_u32 s35, s95, 0
	s_mov_b32 s66, 0
	v_mov_b32_e32 v3, v2
	v_mov_b32_e32 v4, v2
	v_mov_b32_e32 v5, v2
	v_mov_b32_e32 v6, v2
	v_mov_b32_e32 v7, v2
	v_mov_b32_e32 v8, v2
	v_mov_b32_e32 v9, v2
	v_mov_b32_e32 v14, v2
	v_mov_b32_e32 v15, v2
	v_mov_b32_e32 v16, v2
	v_mov_b32_e32 v17, v2
	v_mov_b32_e32 v22, v2
	v_mov_b32_e32 v23, v2
	v_mov_b32_e32 v24, v2
	v_mov_b32_e32 v25, v2
	v_mov_b32_e32 v30, v2
	v_mov_b32_e32 v31, v2
	v_mov_b32_e32 v32, v2
	v_mov_b32_e32 v33, v2
	v_mov_b32_e32 v38, v2
	v_mov_b32_e32 v39, v2
	v_mov_b32_e32 v40, v2
	v_mov_b32_e32 v41, v2
	v_mov_b32_e32 v46, v2
	s_waitcnt lgkmcnt(0)
	v_mov_b32_e32 v47, v2
	v_mov_b32_e32 v48, v2
	v_mov_b32_e32 v49, v2
	v_mov_b32_e32 v54, v2
	v_mov_b32_e32 v55, v2
	v_mov_b32_e32 v56, v2
	v_mov_b32_e32 v57, v2
	v_mov_b32_e32 v10, v2
	v_mov_b32_e32 v11, v2
	v_mov_b32_e32 v12, v2
	v_mov_b32_e32 v13, v2
	v_mov_b32_e32 v18, v2
	v_mov_b32_e32 v19, v2
	v_mov_b32_e32 v20, v2
	v_mov_b32_e32 v21, v2
	v_mov_b32_e32 v26, v2
	v_mov_b32_e32 v27, v2
	v_mov_b32_e32 v28, v2
	v_mov_b32_e32 v29, v2
	v_mov_b32_e32 v34, v2
	v_mov_b32_e32 v35, v2
	v_mov_b32_e32 v36, v2
	v_mov_b32_e32 v37, v2
	v_mov_b32_e32 v42, v2
	v_mov_b32_e32 v43, v2
	v_mov_b32_e32 v44, v2
	v_mov_b32_e32 v45, v2
	v_mov_b32_e32 v50, v2
	v_mov_b32_e32 v51, v2
	v_mov_b32_e32 v52, v2
	v_mov_b32_e32 v53, v2
	v_mov_b32_e32 v58, v2
	v_mov_b32_e32 v59, v2
	v_mov_b32_e32 v60, v2
	v_mov_b32_e32 v61, v2
	v_mov_b32_e32 v62, v2
	v_mov_b32_e32 v63, v2
	v_mov_b32_e32 v64, v2
	v_mov_b32_e32 v65, v2
	v_mov_b32_e32 v66, v2
	v_mov_b32_e32 v67, v2
	v_mov_b32_e32 v68, v2
	v_mov_b32_e32 v69, v2
	v_mov_b32_e32 v70, v2
	v_mov_b32_e32 v71, v2
	v_mov_b32_e32 v72, v2
	v_mov_b32_e32 v73, v2
	v_mov_b32_e32 v82, v2
	v_mov_b32_e32 v83, v2
	v_mov_b32_e32 v84, v2
	v_mov_b32_e32 v85, v2
	v_mov_b32_e32 v86, v2
	v_mov_b32_e32 v87, v2
	v_mov_b32_e32 v88, v2
	v_mov_b32_e32 v89, v2
	v_mov_b32_e32 v98, v2
	v_mov_b32_e32 v99, v2
	v_mov_b32_e32 v100, v2
	v_mov_b32_e32 v101, v2
	v_mov_b32_e32 v102, v2
	v_mov_b32_e32 v103, v2
	v_mov_b32_e32 v104, v2
	v_mov_b32_e32 v105, v2
	v_mov_b32_e32 v114, v2
	v_mov_b32_e32 v115, v2
	v_mov_b32_e32 v116, v2
	v_mov_b32_e32 v117, v2
	v_mov_b32_e32 v118, v2
	v_mov_b32_e32 v119, v2
	v_mov_b32_e32 v120, v2
	v_mov_b32_e32 v121, v2
	v_mov_b32_e32 v74, v2
	v_mov_b32_e32 v75, v2
	v_mov_b32_e32 v76, v2
	v_mov_b32_e32 v77, v2
	v_mov_b32_e32 v78, v2
	v_mov_b32_e32 v79, v2
	v_mov_b32_e32 v80, v2
	v_mov_b32_e32 v81, v2
	v_mov_b32_e32 v90, v2
	v_mov_b32_e32 v91, v2
	v_mov_b32_e32 v92, v2
	v_mov_b32_e32 v93, v2
	v_mov_b32_e32 v94, v2
	v_mov_b32_e32 v95, v2
	v_mov_b32_e32 v96, v2
	v_mov_b32_e32 v97, v2
	v_mov_b32_e32 v106, v2
	v_mov_b32_e32 v107, v2
	v_mov_b32_e32 v108, v2
	v_mov_b32_e32 v109, v2
	v_mov_b32_e32 v110, v2
	v_mov_b32_e32 v111, v2
	v_mov_b32_e32 v112, v2
	v_mov_b32_e32 v113, v2
	v_mov_b32_e32 v122, v2
	v_mov_b32_e32 v123, v2
	v_mov_b32_e32 v124, v2
	v_mov_b32_e32 v125, v2
	v_mov_b32_e32 v126, v2
	v_mov_b32_e32 v127, v2
	v_mov_b32_e32 v128, v2
	v_mov_b32_e32 v129, v2
	v_readfirstlane_b32 s98, v219
	s_nop 1
	s_bitcmp1_b32 s98, 8
	s_cbranch_scc0 .Lresync_y_400
	s_barrier
.Lresync_y_400:
.LBB0_400:
	s_add_i32 s14, s66, 2
	s_add_u32 s8, s92, 0x80
	s_addc_u32 s9, s93, 0
	s_add_i32 s15, 0, 0x10000
	v_add_u32_e32 v148, s15, v152
	ds_read_b128 v[144:147], v148
	ds_read_b128 v[172:175], v148 offset:1024
	ds_read_b128 v[176:179], v148 offset:2048
	ds_read_b128 v[180:183], v148 offset:3072
	s_cmp_eq_u32 s71, s66
	s_cselect_b32 s95, s55, s9
	s_cselect_b32 s94, s57, s8
	s_cselect_b32 s97, s59, s35
	s_cselect_b32 s96, s65, s34
	v_lshl_add_u64 v[148:149], s[92:93], 0, v[138:139]
	s_add_i32 m0, s42, 0xc000
	ds_read_b128 v[184:187], v171
	ds_read_b128 v[188:191], v171 offset:1024
	ds_read_b128 v[196:199], v171 offset:2048
	ds_read_b128 v[200:203], v171 offset:3072
	ds_read_b128 v[204:207], v171 offset:4096
	ds_read_b128 v[208:211], v171 offset:5120
	ds_read_b128 v[212:215], v171 offset:6144
	ds_read_b128 v[222:225], v171 offset:7168
	global_load_lds_dwordx4 v[148:149], off
	v_lshl_add_u64 v[148:149], s[92:93], 0, v[140:141]
	s_add_i32 m0, s42, 0xe000
	s_nop 0
	global_load_lds_dwordx4 v[148:149], off
	s_add_i32 s8, 0, 0x14000
	v_add_u32_e32 v148, s8, v152
	ds_read_b128 v[226:229], v148
	ds_read_b128 v[230:233], v148 offset:1024
	ds_read_b128 v[234:237], v148 offset:2048
	ds_read_b128 v[238:241], v148 offset:3072
	s_waitcnt vmcnt(8)
	s_waitcnt lgkmcnt(0)
	v_mfma_f32_16x16x32_bf16 v[126:129], v[144:147], v[184:187], v[126:129]
	v_mfma_f32_16x16x32_bf16 v[122:125], v[176:179], v[184:187], v[122:125]
	v_mfma_f32_16x16x32_bf16 v[110:113], v[144:147], v[196:199], v[110:113]
	v_mfma_f32_16x16x32_bf16 v[106:109], v[176:179], v[196:199], v[106:109]
	s_barrier
; #define PG8_STAGE(bufoff, gbase, voff) do { _Pragma("unroll") for (int _i = 0; _i < 2; ++_i) \
;         __builtin_amdgcn_global_load_lds((const unsigned*)((const char*)(gbase) + (voff)[_i]), (LAS unsigned*)(lds + (bufoff) + ldsw + _i * 8192), 16, 0, 0); } while (0)
; #define PG8_LDA(dst, b, h) do { _Pragma("unroll") for (int m = 0; m < 4; ++m) _Pragma("unroll") for (int k = 0; k < 2; ++k) dst[m][k] = *(const LAS bf16x8*)(lds + PG8_SA(b, h) + aoff + m * 2048 + k * 1024); } while (0)
; #define PG8_LDB(dst, b, h) do { _Pragma("unroll") for (int n = 0; n < 2; ++n) _Pragma("unroll") for (int k = 0; k < 2; ++k) dst[n][k] = *(const LAS bf16x8*)(lds + PG8_SB(b, h) + boff + n * 2048 + k * 1024); } while (0)
; #define PG8_MMA(ai, bj, At, Bt) do { __builtin_amdgcn_s_setprio(1); _Pragma("unroll") for (int m = 0; m < 4; ++m) _Pragma("unroll") for (int n = 0; n < 2; ++n) _Pragma("unroll") for (int k = 0; k < 2; ++k) \
;         acc[ai][bj][m][n] = __builtin_amdgcn_mfma_f32_16x16x32_bf16(Bt[n][k], At[m][k], acc[ai][bj][m][n], 0, 0, 0); __builtin_amdgcn_s_setprio(0); } while (0)
; #define PG8_WAIT_V(n) asm volatile("s_waitcnt vmcnt(" #n ")" ::: "memory")
; #define PG8_WAIT_L(n) asm volatile("s_waitcnt lgkmcnt(" #n ")" ::: "memory")
; #define PG8_BAR __builtin_amdgcn_s_barrier()
; #define PG8_SCHED __builtin_amdgcn_sched_barrier(0)
; template <class Epi>
; __device__ __forceinline__ void gemm_phase(LAS unsigned char* lds, const Gemm g, const Sched& S, const Epi& E) {
;     ...
;             PG8_WAIT_L(8); PG8_BAR; PG8_WAIT_L(0); PG8_MMA(0, 0, At, B0); PG8_BAR; PG8_SCHED;
;             PG8_LDB(B1, 0, 1); PG8_STAGE(PG8_SB(0, 0), b2, voffB);
;             PG8_BAR; PG8_WAIT_L(0); PG8_MMA(0, 1, At, B1); PG8_BAR;
;             PG8_LDA(At, 0, 1); PG8_STAGE(PG8_SA(0, 0), a2, voffA);
;             PG8_BAR; PG8_WAIT_L(0); PG8_MMA(1, 0, At, B0); PG8_BAR; PG8_SCHED;
;             PG8_STAGE(PG8_SB(0, 1), b2 + hstepB, voffB);
;             PG8_WAIT_V(6); PG8_BAR; PG8_MMA(1, 1, At, B1); PG8_BAR;
	s_setprio 1
	v_mfma_f32_16x16x32_bf16 v[94:97], v[144:147], v[204:207], v[94:97]
	v_mfma_f32_16x16x32_bf16 v[90:93], v[176:179], v[204:207], v[90:93]
	v_mfma_f32_16x16x32_bf16 v[78:81], v[144:147], v[212:215], v[78:81]
	v_mfma_f32_16x16x32_bf16 v[74:77], v[176:179], v[212:215], v[74:77]
	v_mfma_f32_16x16x32_bf16 v[126:129], v[172:175], v[188:191], v[126:129]
	v_mfma_f32_16x16x32_bf16 v[122:125], v[180:183], v[188:191], v[122:125]
	v_mfma_f32_16x16x32_bf16 v[110:113], v[172:175], v[200:203], v[110:113]
	v_mfma_f32_16x16x32_bf16 v[106:109], v[180:183], v[200:203], v[106:109]
	v_mfma_f32_16x16x32_bf16 v[94:97], v[172:175], v[208:211], v[94:97]
	v_mfma_f32_16x16x32_bf16 v[90:93], v[180:183], v[208:211], v[90:93]
	v_mfma_f32_16x16x32_bf16 v[78:81], v[172:175], v[222:225], v[78:81]
	v_mfma_f32_16x16x32_bf16 v[74:77], v[180:183], v[222:225], v[74:77]
	v_mfma_f32_16x16x32_bf16 v[118:121], v[226:229], v[184:187], v[118:121]
	v_mfma_f32_16x16x32_bf16 v[114:117], v[234:237], v[184:187], v[114:117]
	v_mfma_f32_16x16x32_bf16 v[102:105], v[226:229], v[196:199], v[102:105]
	v_mfma_f32_16x16x32_bf16 v[98:101], v[234:237], v[196:199], v[98:101]
	v_mfma_f32_16x16x32_bf16 v[86:89], v[226:229], v[204:207], v[86:89]
	v_mfma_f32_16x16x32_bf16 v[82:85], v[234:237], v[204:207], v[82:85]
	v_mfma_f32_16x16x32_bf16 v[70:73], v[226:229], v[212:215], v[70:73]
	v_mfma_f32_16x16x32_bf16 v[66:69], v[234:237], v[212:215], v[66:69]
	v_mfma_f32_16x16x32_bf16 v[118:121], v[230:233], v[188:191], v[118:121]
	v_mfma_f32_16x16x32_bf16 v[114:117], v[238:241], v[188:191], v[114:117]
	v_mfma_f32_16x16x32_bf16 v[102:105], v[230:233], v[200:203], v[102:105]
	v_mfma_f32_16x16x32_bf16 v[98:101], v[238:241], v[200:203], v[98:101]
	v_mfma_f32_16x16x32_bf16 v[86:89], v[230:233], v[208:211], v[86:89]
	v_mfma_f32_16x16x32_bf16 v[82:85], v[238:241], v[208:211], v[82:85]
	v_mfma_f32_16x16x32_bf16 v[70:73], v[230:233], v[222:225], v[70:73]
	v_mfma_f32_16x16x32_bf16 v[66:69], v[238:241], v[222:225], v[66:69]
	s_setprio 0
	s_barrier
	s_add_i32 s9, s15, s39
	v_lshl_add_u64 v[148:149], s[96:97], 0, v[132:133]
	s_mov_b32 m0, s9
	v_lshl_add_u64 v[192:193], s[96:97], 0, v[136:137]
	global_load_lds_dwordx4 v[148:149], off
	s_add_i32 m0, s9, 0x2000
	s_nop 0
	global_load_lds_dwordx4 v[192:193], off
	s_mov_b32 m0, s42
	v_lshl_add_u64 v[194:195], s[94:95], 0, v[130:131]
	ds_read_b128 v[184:187], v171 offset:16384
	ds_read_b128 v[188:191], v171 offset:17408
	ds_read_b128 v[196:199], v171 offset:18432
	ds_read_b128 v[200:203], v171 offset:19456
	ds_read_b128 v[204:207], v171 offset:20480
	ds_read_b128 v[208:211], v171 offset:21504
	ds_read_b128 v[212:215], v171 offset:22528
	ds_read_b128 v[222:225], v171 offset:23552
	global_load_lds_dwordx4 v[194:195], off
	v_lshl_add_u64 v[216:217], s[94:95], 0, v[134:135]
	s_mov_b32 m0, s43
	s_nop 0
	global_load_lds_dwordx4 v[216:217], off
	s_add_u32 s96, s96, s78
	s_addc_u32 s97, s97, s79
	s_add_i32 s8, s8, s39
	v_lshl_add_u64 v[242:243], s[96:97], 0, v[132:133]
	s_mov_b32 m0, s8
	v_lshl_add_u64 v[244:245], s[96:97], 0, v[136:137]
	global_load_lds_dwordx4 v[242:243], off
	s_add_i32 m0, s8, 0x2000
	s_nop 0
	global_load_lds_dwordx4 v[244:245], off
	s_waitcnt vmcnt(8)
	s_waitcnt lgkmcnt(0)
	v_mfma_f32_16x16x32_bf16 v[62:65], v[144:147], v[184:187], v[62:65]
	v_mfma_f32_16x16x32_bf16 v[58:61], v[176:179], v[184:187], v[58:61]
	v_mfma_f32_16x16x32_bf16 v[50:53], v[144:147], v[196:199], v[50:53]
	v_mfma_f32_16x16x32_bf16 v[42:45], v[176:179], v[196:199], v[42:45]
	s_barrier
	s_setprio 1
	v_mfma_f32_16x16x32_bf16 v[34:37], v[144:147], v[204:207], v[34:37]
	v_mfma_f32_16x16x32_bf16 v[26:29], v[176:179], v[204:207], v[26:29]
	v_mfma_f32_16x16x32_bf16 v[18:21], v[144:147], v[212:215], v[18:21]
	v_mfma_f32_16x16x32_bf16 v[10:13], v[176:179], v[212:215], v[10:13]
	v_mfma_f32_16x16x32_bf16 v[62:65], v[172:175], v[188:191], v[62:65]
	v_mfma_f32_16x16x32_bf16 v[58:61], v[180:183], v[188:191], v[58:61]
	v_mfma_f32_16x16x32_bf16 v[50:53], v[172:175], v[200:203], v[50:53]
	v_mfma_f32_16x16x32_bf16 v[42:45], v[180:183], v[200:203], v[42:45]
	v_mfma_f32_16x16x32_bf16 v[34:37], v[172:175], v[208:211], v[34:37]
	v_mfma_f32_16x16x32_bf16 v[26:29], v[180:183], v[208:211], v[26:29]
	v_mfma_f32_16x16x32_bf16 v[18:21], v[172:175], v[222:225], v[18:21]
	v_mfma_f32_16x16x32_bf16 v[10:13], v[180:183], v[222:225], v[10:13]
	v_mfma_f32_16x16x32_bf16 v[54:57], v[226:229], v[184:187], v[54:57]
	v_mfma_f32_16x16x32_bf16 v[46:49], v[234:237], v[184:187], v[46:49]
	v_mfma_f32_16x16x32_bf16 v[38:41], v[226:229], v[196:199], v[38:41]
	v_mfma_f32_16x16x32_bf16 v[30:33], v[234:237], v[196:199], v[30:33]
	v_mfma_f32_16x16x32_bf16 v[22:25], v[226:229], v[204:207], v[22:25]
	v_mfma_f32_16x16x32_bf16 v[14:17], v[234:237], v[204:207], v[14:17]
	v_mfma_f32_16x16x32_bf16 v[6:9], v[226:229], v[212:215], v[6:9]
	v_mfma_f32_16x16x32_bf16 v[2:5], v[234:237], v[212:215], v[2:5]
	v_mfma_f32_16x16x32_bf16 v[54:57], v[230:233], v[188:191], v[54:57]
	v_mfma_f32_16x16x32_bf16 v[46:49], v[238:241], v[188:191], v[46:49]
	v_mfma_f32_16x16x32_bf16 v[38:41], v[230:233], v[200:203], v[38:41]
	v_mfma_f32_16x16x32_bf16 v[30:33], v[238:241], v[200:203], v[30:33]
	v_mfma_f32_16x16x32_bf16 v[22:25], v[230:233], v[208:211], v[22:25]
	v_mfma_f32_16x16x32_bf16 v[14:17], v[238:241], v[208:211], v[14:17]
	v_mfma_f32_16x16x32_bf16 v[6:9], v[230:233], v[222:225], v[6:9]
	v_mfma_f32_16x16x32_bf16 v[2:5], v[238:241], v[222:225], v[2:5]
	s_setprio 0
	s_barrier
; #define PG8_STAGE(bufoff, gbase, voff) do { _Pragma("unroll") for (int _i = 0; _i < 2; ++_i) \
;         __builtin_amdgcn_global_load_lds((const unsigned*)((const char*)(gbase) + (voff)[_i]), (LAS unsigned*)(lds + (bufoff) + ldsw + _i * 8192), 16, 0, 0); } while (0)
; #define PG8_LDA(dst, b, h) do { _Pragma("unroll") for (int m = 0; m < 4; ++m) _Pragma("unroll") for (int k = 0; k < 2; ++k) dst[m][k] = *(const LAS bf16x8*)(lds + PG8_SA(b, h) + aoff + m * 2048 + k * 1024); } while (0)
; #define PG8_LDB(dst, b, h) do { _Pragma("unroll") for (int n = 0; n < 2; ++n) _Pragma("unroll") for (int k = 0; k < 2; ++k) dst[n][k] = *(const LAS bf16x8*)(lds + PG8_SB(b, h) + boff + n * 2048 + k * 1024); } while (0)
; #define PG8_MMA(ai, bj, At, Bt) do { __builtin_amdgcn_s_setprio(1); _Pragma("unroll") for (int m = 0; m < 4; ++m) _Pragma("unroll") for (int n = 0; n < 2; ++n) _Pragma("unroll") for (int k = 0; k < 2; ++k) \
;         acc[ai][bj][m][n] = __builtin_amdgcn_mfma_f32_16x16x32_bf16(Bt[n][k], At[m][k], acc[ai][bj][m][n], 0, 0, 0); __builtin_amdgcn_s_setprio(0); } while (0)
; #define PG8_WAIT_L(n) asm volatile("s_waitcnt lgkmcnt(" #n ")" ::: "memory")
; #define PG8_BAR __builtin_amdgcn_s_barrier()
; #define PG8_SCHED __builtin_amdgcn_sched_barrier(0)
; template <class Epi>
; __device__ __forceinline__ void gemm_phase(LAS unsigned char* lds, const Gemm g, const Sched& S, const Epi& E) {
;     ...
;             PG8_LDB(B0, 1, 0); PG8_SCHED; PG8_LDA(At, 1, 0); PG8_STAGE(PG8_SA(0, 1), a2 + hstepA, voffA);
;             PG8_WAIT_L(8); PG8_BAR; PG8_WAIT_L(0); PG8_MMA(0, 0, At, B0); PG8_BAR; PG8_SCHED;
;             PG8_LDB(B1, 1, 1); PG8_STAGE(PG8_SB(1, 0), b3, voffB);
;             PG8_BAR; PG8_WAIT_L(0); PG8_MMA(0, 1, At, B1); PG8_BAR;
;             PG8_LDA(At, 1, 1); PG8_STAGE(PG8_SA(1, 0), a3, voffA);
;             PG8_BAR; PG8_WAIT_L(0); PG8_MMA(1, 0, At, B0); PG8_BAR; PG8_SCHED;
	s_add_i32 s8, 0, 0x18000
	v_add_u32_e32 v180, s8, v152
	ds_read_b128 v[144:147], v180
	ds_read_b128 v[172:175], v180 offset:1024
	ds_read_b128 v[176:179], v180 offset:2048
	ds_read_b128 v[180:183], v180 offset:3072
	s_add_u32 s94, s94, s4
	s_addc_u32 s95, s95, s5
	s_mov_b32 m0, s52
	v_lshl_add_u64 v[226:227], s[94:95], 0, v[130:131]
	ds_read_b128 v[184:187], v171 offset:32768
	ds_read_b128 v[188:191], v171 offset:33792
	ds_read_b128 v[196:199], v171 offset:34816
	ds_read_b128 v[200:203], v171 offset:35840
	ds_read_b128 v[204:207], v171 offset:36864
	ds_read_b128 v[208:211], v171 offset:37888
	ds_read_b128 v[212:215], v171 offset:38912
	ds_read_b128 v[222:225], v171 offset:39936
	global_load_lds_dwordx4 v[226:227], off
	v_lshl_add_u64 v[226:227], s[94:95], 0, v[134:135]
	s_mov_b32 m0, s53
	s_nop 0
	global_load_lds_dwordx4 v[226:227], off
	s_add_i32 s9, 0, 0x1c000
	v_add_u32_e32 v218, s9, v152
	ds_read_b128 v[226:229], v218
	ds_read_b128 v[230:233], v218 offset:1024
	ds_read_b128 v[234:237], v218 offset:2048
	ds_read_b128 v[238:241], v218 offset:3072
	s_waitcnt vmcnt(8)
	s_waitcnt lgkmcnt(0)
	v_mfma_f32_16x16x32_bf16 v[126:129], v[144:147], v[184:187], v[126:129]
	v_mfma_f32_16x16x32_bf16 v[122:125], v[176:179], v[184:187], v[122:125]
	v_mfma_f32_16x16x32_bf16 v[110:113], v[144:147], v[196:199], v[110:113]
	v_mfma_f32_16x16x32_bf16 v[106:109], v[176:179], v[196:199], v[106:109]
	s_barrier
	s_setprio 1
	v_mfma_f32_16x16x32_bf16 v[94:97], v[144:147], v[204:207], v[94:97]
	v_mfma_f32_16x16x32_bf16 v[90:93], v[176:179], v[204:207], v[90:93]
	v_mfma_f32_16x16x32_bf16 v[78:81], v[144:147], v[212:215], v[78:81]
	v_mfma_f32_16x16x32_bf16 v[74:77], v[176:179], v[212:215], v[74:77]
	v_mfma_f32_16x16x32_bf16 v[126:129], v[172:175], v[188:191], v[126:129]
	v_mfma_f32_16x16x32_bf16 v[122:125], v[180:183], v[188:191], v[122:125]
	v_mfma_f32_16x16x32_bf16 v[110:113], v[172:175], v[200:203], v[110:113]
	v_mfma_f32_16x16x32_bf16 v[106:109], v[180:183], v[200:203], v[106:109]
	v_mfma_f32_16x16x32_bf16 v[94:97], v[172:175], v[208:211], v[94:97]
	v_mfma_f32_16x16x32_bf16 v[90:93], v[180:183], v[208:211], v[90:93]
	v_mfma_f32_16x16x32_bf16 v[78:81], v[172:175], v[222:225], v[78:81]
	v_mfma_f32_16x16x32_bf16 v[74:77], v[180:183], v[222:225], v[74:77]
	v_mfma_f32_16x16x32_bf16 v[118:121], v[226:229], v[184:187], v[118:121]
	v_mfma_f32_16x16x32_bf16 v[114:117], v[234:237], v[184:187], v[114:117]
	v_mfma_f32_16x16x32_bf16 v[102:105], v[226:229], v[196:199], v[102:105]
	v_mfma_f32_16x16x32_bf16 v[98:101], v[234:237], v[196:199], v[98:101]
	v_mfma_f32_16x16x32_bf16 v[86:89], v[226:229], v[204:207], v[86:89]
	v_mfma_f32_16x16x32_bf16 v[82:85], v[234:237], v[204:207], v[82:85]
	v_mfma_f32_16x16x32_bf16 v[70:73], v[226:229], v[212:215], v[70:73]
	v_mfma_f32_16x16x32_bf16 v[66:69], v[234:237], v[212:215], v[66:69]
	v_mfma_f32_16x16x32_bf16 v[118:121], v[230:233], v[188:191], v[118:121]
	v_mfma_f32_16x16x32_bf16 v[114:117], v[238:241], v[188:191], v[114:117]
	v_mfma_f32_16x16x32_bf16 v[102:105], v[230:233], v[200:203], v[102:105]
	v_mfma_f32_16x16x32_bf16 v[98:101], v[238:241], v[200:203], v[98:101]
	v_mfma_f32_16x16x32_bf16 v[86:89], v[230:233], v[208:211], v[86:89]
	v_mfma_f32_16x16x32_bf16 v[82:85], v[238:241], v[208:211], v[82:85]
	v_mfma_f32_16x16x32_bf16 v[70:73], v[230:233], v[222:225], v[70:73]
	v_mfma_f32_16x16x32_bf16 v[66:69], v[238:241], v[222:225], v[66:69]
	s_setprio 0
	s_barrier
	s_add_i32 s8, s8, s39
	v_lshl_add_u64 v[148:149], v[148:149], 0, s[60:61]
	s_mov_b32 m0, s8
	s_nop 0
	global_load_lds_dwordx4 v[148:149], off
	v_lshl_add_u64 v[148:149], v[192:193], 0, s[60:61]
	s_add_i32 m0, s8, 0x2000
	s_nop 0
	global_load_lds_dwordx4 v[148:149], off
	s_mov_b32 m0, s67
	v_lshl_add_u64 v[148:149], v[194:195], 0, s[60:61]
	ds_read_b128 v[184:187], v171 offset:49152
	ds_read_b128 v[188:191], v171 offset:50176
	ds_read_b128 v[196:199], v171 offset:51200
	ds_read_b128 v[200:203], v171 offset:52224
	ds_read_b128 v[204:207], v171 offset:53248
	ds_read_b128 v[208:211], v171 offset:54272
	ds_read_b128 v[212:215], v171 offset:55296
	ds_read_b128 v[222:225], v171 offset:56320
	global_load_lds_dwordx4 v[148:149], off
	v_lshl_add_u64 v[148:149], v[216:217], 0, s[60:61]
	s_mov_b32 m0, s2
	s_nop 0
	global_load_lds_dwordx4 v[148:149], off
	s_add_i32 s8, s9, s39
	v_lshl_add_u64 v[148:149], v[242:243], 0, s[60:61]
	s_mov_b32 m0, s8
	s_nop 0
	global_load_lds_dwordx4 v[148:149], off
	v_lshl_add_u64 v[148:149], v[244:245], 0, s[60:61]
	s_add_i32 m0, s8, 0x2000
	s_nop 0
	global_load_lds_dwordx4 v[148:149], off
	s_waitcnt vmcnt(8)
	s_waitcnt lgkmcnt(0)
	v_mfma_f32_16x16x32_bf16 v[62:65], v[144:147], v[184:187], v[62:65]
	v_mfma_f32_16x16x32_bf16 v[58:61], v[176:179], v[184:187], v[58:61]
	v_mfma_f32_16x16x32_bf16 v[50:53], v[144:147], v[196:199], v[50:53]
	v_mfma_f32_16x16x32_bf16 v[42:45], v[176:179], v[196:199], v[42:45]
	s_barrier
; __device__ __forceinline__ float pre_get(const Pre& p, int ai, int m, int fr) { return __shfl(p.v[ai], m * 16 + fr); }
; __device__ __forceinline__ float rstd_pre(const float* ss, float v) { return ss ? rsqrtf(v * (1.0f / 2048.0f) + 1e-6f) : 1.0f; }
; #define PG8_STAGE(bufoff, gbase, voff) do { _Pragma("unroll") for (int _i = 0; _i < 2; ++_i) \
;         __builtin_amdgcn_global_load_lds((const unsigned*)((const char*)(gbase) + (voff)[_i]), (LAS unsigned*)(lds + (bufoff) + ldsw + _i * 8192), 16, 0, 0); } while (0)
; #define PG8_MMA(ai, bj, At, Bt) do { __builtin_amdgcn_s_setprio(1); _Pragma("unroll") for (int m = 0; m < 4; ++m) _Pragma("unroll") for (int n = 0; n < 2; ++n) _Pragma("unroll") for (int k = 0; k < 2; ++k) \
;         acc[ai][bj][m][n] = __builtin_amdgcn_mfma_f32_16x16x32_bf16(Bt[n][k], At[m][k], acc[ai][bj][m][n], 0, 0, 0); __builtin_amdgcn_s_setprio(0); } while (0)
; #define PG8_WAIT_V(n) asm volatile("s_waitcnt vmcnt(" #n ")" ::: "memory")
; #define PG8_BAR __builtin_amdgcn_s_barrier()
; template <class Epi>
; __device__ __forceinline__ void gemm_phase(LAS unsigned char* lds, const Gemm g, const Sched& S, const Epi& E) {
;     ...
;             PG8_STAGE(PG8_SB(1, 1), b3 + hstepB, voffB);
;             PG8_WAIT_V(6); PG8_BAR; PG8_MMA(1, 1, At, B1); PG8_BAR;
;         }
;         E(acc, cur, wr, wc, fr, fq, pre);
;         if (!has_next) break;
;     __device__ __forceinline__ void operator()(const Acc& acc, const Unit& u, int wr, int wc, int fr, int fq, const Pre& pre) const {
;     ...
;         for (int ai = 0; ai < 2; ++ai)
; #pragma unroll
;             for (int m = 0; m < 4; ++m) rs[ai][m] = rstd_pre(ss, pre_get(pre, ai, m, fr));
; #pragma unroll
;         for (int ai = 0; ai < 2; ++ai)
; #pragma unroll
;             for (int m = 0; m < 4; ++m) { float mx = -INFINITY;
; #pragma unroll
;                 for (int bj = 0; bj < 2; ++bj)
; #pragma unroll
;                     for (int n = 0; n < 2; ++n) { const f32x4 a = acc[ai][bj][m][n]; mx = fmaxf(mx, fmaxf(fmaxf(a[0], a[1]), fmaxf(a[2], a[3]))); }
;                 mx *= rs[ai][m];
;                 mx = fmaxf(mx, __shfl_xor(mx, 16)); mx = fmaxf(mx, __shfl_xor(mx, 32));
;                 if (fq == 0) X[(ai * 128 + wr * 64 + m * 16 + fr) * 4 + wc] = mx; }
	s_setprio 1
	v_mfma_f32_16x16x32_bf16 v[34:37], v[144:147], v[204:207], v[34:37]
	v_mfma_f32_16x16x32_bf16 v[26:29], v[176:179], v[204:207], v[26:29]
	v_mfma_f32_16x16x32_bf16 v[18:21], v[144:147], v[212:215], v[18:21]
	v_mfma_f32_16x16x32_bf16 v[10:13], v[176:179], v[212:215], v[10:13]
	v_mfma_f32_16x16x32_bf16 v[62:65], v[172:175], v[188:191], v[62:65]
	v_mfma_f32_16x16x32_bf16 v[58:61], v[180:183], v[188:191], v[58:61]
	v_mfma_f32_16x16x32_bf16 v[50:53], v[172:175], v[200:203], v[50:53]
	v_mfma_f32_16x16x32_bf16 v[42:45], v[180:183], v[200:203], v[42:45]
	v_mfma_f32_16x16x32_bf16 v[34:37], v[172:175], v[208:211], v[34:37]
	v_mfma_f32_16x16x32_bf16 v[26:29], v[180:183], v[208:211], v[26:29]
	v_mfma_f32_16x16x32_bf16 v[18:21], v[172:175], v[222:225], v[18:21]
	v_mfma_f32_16x16x32_bf16 v[10:13], v[180:183], v[222:225], v[10:13]
	v_mfma_f32_16x16x32_bf16 v[54:57], v[226:229], v[184:187], v[54:57]
	v_mfma_f32_16x16x32_bf16 v[46:49], v[234:237], v[184:187], v[46:49]
	v_mfma_f32_16x16x32_bf16 v[38:41], v[226:229], v[196:199], v[38:41]
	v_mfma_f32_16x16x32_bf16 v[30:33], v[234:237], v[196:199], v[30:33]
	v_mfma_f32_16x16x32_bf16 v[22:25], v[226:229], v[204:207], v[22:25]
	v_mfma_f32_16x16x32_bf16 v[14:17], v[234:237], v[204:207], v[14:17]
	v_mfma_f32_16x16x32_bf16 v[6:9], v[226:229], v[212:215], v[6:9]
	v_mfma_f32_16x16x32_bf16 v[2:5], v[234:237], v[212:215], v[2:5]
	v_mfma_f32_16x16x32_bf16 v[54:57], v[230:233], v[188:191], v[54:57]
	v_mfma_f32_16x16x32_bf16 v[46:49], v[238:241], v[188:191], v[46:49]
	v_mfma_f32_16x16x32_bf16 v[38:41], v[230:233], v[200:203], v[38:41]
	v_mfma_f32_16x16x32_bf16 v[30:33], v[238:241], v[200:203], v[30:33]
	v_mfma_f32_16x16x32_bf16 v[22:25], v[230:233], v[208:211], v[22:25]
	v_mfma_f32_16x16x32_bf16 v[14:17], v[238:241], v[208:211], v[14:17]
	v_mfma_f32_16x16x32_bf16 v[6:9], v[230:233], v[222:225], v[6:9]
	v_mfma_f32_16x16x32_bf16 v[2:5], v[238:241], v[222:225], v[2:5]
	s_setprio 0
	s_add_u32 s92, s92, 0x100
	s_addc_u32 s93, s93, 0
	s_add_u32 s34, s34, 0x100
	s_addc_u32 s35, s35, 0
	s_cmp_ge_u32 s14, s73
	s_mov_b32 s66, s14
	s_barrier
	s_cbranch_scc0 .LBB0_400
	v_readfirstlane_b32 s98, v219
	s_nop 1
	s_bitcmp1_b32 s98, 8
	s_cbranch_scc1 .Lresync_x_400
	s_barrier
.Lresync_x_400:
	v_and_b32_e32 v144, 64, v220
	v_or_b32_e32 v144, v144, v150
	v_lshlrev_b32_e32 v172, 2, v144
	ds_bpermute_b32 v145, v172, v143
	ds_bpermute_b32 v144, v172, v143 offset:64
	s_mov_b32 s8, 0x3a000000
	v_mov_b32_e32 v232, 0x358637bd
	s_mov_b32 s97, 0x800000
	ds_bpermute_b32 v147, v172, v143 offset:128
	s_waitcnt lgkmcnt(0)
	v_pk_fma_f32 v[148:149], v[144:145], s[8:9], v[232:233] op_sel_hi:[1,0,0]
	ds_bpermute_b32 v146, v172, v143 offset:192
	v_mul_f32_e32 v143, 0x4b800000, v149
	v_cmp_gt_f32_e32 vcc, s97, v149
	v_max_f32_e32 v174, v128, v128
	v_max_f32_e32 v175, v124, v124
	v_cndmask_b32_e32 v143, v149, v143, vcc
	v_rsq_f32_e32 v149, v143
	v_max_f32_e32 v176, v116, v116
	ds_bpermute_b32 v145, v172, v142
	ds_bpermute_b32 v144, v172, v142 offset:64
	v_mul_f32_e32 v173, 0x45800000, v149
	v_cndmask_b32_e32 v149, v149, v173, vcc
	v_max_f32_e32 v173, v129, v129
	v_max_f32_e32 v173, v174, v173
	v_max_f32_e32 v174, v125, v125
	v_max_f32_e32 v174, v175, v174
	v_max3_f32 v173, v126, v127, v173
	v_max3_f32 v174, v122, v123, v174
	v_max3_f32 v173, v173, s72, v174
	v_max_f32_e32 v174, v121, v121
	v_max_f32_e32 v175, v120, v120
	v_max_f32_e32 v174, v175, v174
	v_max_f32_e32 v175, v117, v117
	v_max_f32_e32 v175, v176, v175
	v_cmp_lt_i32_e32 vcc, v221, v247
	v_max3_f32 v174, v118, v119, v174
	v_max3_f32 v175, v114, v115, v175
	v_cndmask_b32_e64 v177, v149, 1.0, s[80:81]
	v_cndmask_b32_e32 v149, v220, v221, vcc
	v_max3_f32 v173, v173, v174, v175
	v_lshlrev_b32_e32 v149, 2, v149
	v_mul_f32_e32 v173, v173, v177
	ds_bpermute_b32 v174, v149, v173
	v_cmp_lt_i32_e32 vcc, v248, v247
	ds_bpermute_b32 v143, v172, v142 offset:128
	ds_bpermute_b32 v142, v172, v142 offset:192
	v_cndmask_b32_e32 v172, v220, v248, vcc
	s_waitcnt lgkmcnt(0)
	v_max_f32_e32 v174, v174, v174
	v_lshlrev_b32_e32 v172, 2, v172
	v_max_f32_e32 v173, v173, v174
	ds_bpermute_b32 v174, v172, v173
	v_cmp_gt_f32_e32 vcc, s97, v148
	v_add_u32_e32 v178, s51, v154
	s_and_saveexec_b64 s[92:93], s[0:1]
	s_cbranch_execz .LBB0_403
	s_waitcnt lgkmcnt(0)
	v_max_f32_e32 v174, v174, v174
	v_max_f32_e32 v173, v173, v173
	v_max_f32_e32 v173, v173, v174
	ds_write_b32 v178, v173

; #define PG8_WAIT_V(n) asm volatile("s_waitcnt vmcnt(" #n ")" ::: "memory")
; #define PG8_BAR __builtin_amdgcn_s_barrier()
; template <class Epi>
; __device__ __forceinline__ void gemm_phase(LAS unsigned char* lds, const Gemm g, const Sched& S, const Epi& E) {
;     ...
;     PG8_WAIT_V(0);
;     if (wr == 0) PG8_BAR;
;     PG8_BAR;
.LBB0_434:
	s_waitcnt vmcnt(0)
	v_readlane_b32 s0, v254, 51
	v_readlane_b32 s84, v254, 49
	s_cmpk_gt_u32 s0, 0xff
	v_readlane_b32 s85, v254, 50
	v_readlane_b32 s48, v254, 53
	v_readlane_b32 s51, v254, 55
	v_readlane_b32 s53, v254, 57
	s_cbranch_scc1 .LBB0_436
.LBB0_436:
	v_readlane_b32 s38, v253, 30
	v_readlane_b32 s82, v254, 43
	v_readlane_b32 s66, v254, 45
	v_readlane_b32 s39, v253, 31
	v_readlane_b32 s83, v254, 44
	v_readlane_b32 s57, v254, 37
	v_readlane_b32 s67, v254, 46
	s_barrier

; #define LAS __attribute__((address_space(3)))
;     __device__ __forceinline__ bool next(int i, Unit& u) const {
;         const long L = (long)i * G + c; if (L >= total) return false;
;         const int z = (int)(L / per); int wgid = (int)(L % per);
;         { const int q = per / NXCD, r = per % NXCD, xcd = wgid % NXCD, off = wgid / NXCD; wgid = (xcd < r ? xcd * (q + 1) : r * (q + 1) + (xcd - r) * q) + off; }
;         const int nig = WGM * nN, gid = wgid / nig, fm = gid * WGM, gsz = (nM - fm) < WGM ? (nM - fm) : WGM;
;         u.pm = fm + ((wgid % nig) % gsz); u.pn = (wgid % nig) / gsz; u.zb = z / nh; u.zh = z % nh;
;         u.ao = u.zb * sAb + u.zh * sAh + u.pm * tA; u.bo = u.zb * sBb + u.zh * sBh + u.pn * tB; return true;
;     }
; template <class Epi>
; __device__ __forceinline__ void gemm_phase(LAS unsigned char* lds, const Gemm g, const Sched& S, const Epi& E) {
;     const int tid = otid(), wid = __builtin_amdgcn_readfirstlane(tid >> 6), lane = tid & 63, wr = wid >> 2, wc = wid & 3, fr = lane & 15, fq = lane >> 4;
;     const int nt = g.K / BK;
;     unsigned voffA[2], voffB[2];
; #pragma unroll
;     for (int i = 0; i < 2; ++i) { int R, C; stage_rc(tid * 16 + i * 8192, R, C); const int Rb = Epi::PERM ? ((R & ~31) + perm32(R & 31)) : R;
;         voffA[i] = (unsigned)(R * g.lda + C) * 2u; voffB[i] = (unsigned)(Rb * g.ldb + C) * 2u; }
;     const size_t kstep = (size_t)(BK * 2);
;     const size_t hstepA = (size_t)HALF * g.lda * 2, hstepB = (size_t)HALF * g.ldb * 2;
;     const unsigned ldsw = (unsigned)wid * 1024u;
;     const int aoff = lds_byte(wr * 64 + fr, fq * 8), boff = lds_byte(wc * 32 + fr, fq * 8);
;     ...
;     Unit cur, nxt; int ui = 0;
;     if (!S.next(0, cur)) return;
;     f32x4 acc[2][2][4][2];
; #pragma unroll
;     for (int a = 0; a < 2; ++a)
; #pragma unroll
;         for (int b = 0; b < 2; ++b)
; #pragma unroll
;             for (int m = 0; m < 4; ++m)
; #pragma unroll
;                 for (int n = 0; n < 2; ++n) acc[a][b][m][n] = (f32x4){0.f, 0.f, 0.f, 0.f};
;     bf16x8 At[4][2], B0[2][2], B1[2][2];
;     const char* cA = (const char*)g.A + cur.ao; const char* cB = (const char*)g.Bt + cur.bo;
;     PG8_STAGE(PG8_SB(0, 0), cB, voffB); PG8_STAGE(PG8_SA(0, 0), cA, voffA); PG8_STAGE(PG8_SB(0, 1), cB + hstepB, voffB); PG8_STAGE(PG8_SA(0, 1), cA + hstepA, voffA);
;     if (wr == 1) PG8_BAR;
;     PG8_WAIT_V(4); PG8_BAR;
.LBB0_446:
	s_andn2_b64 vcc, exec, s[0:1]
	s_cbranch_vccnz .LBB0_530
	v_bfe_i32 v3, v15, 27, 1
	v_lshlrev_b32_e32 v2, 4, v15
	v_lshrrev_b32_e32 v3, 22, v3
	v_add_u32_e32 v3, v2, v3
	v_and_b32_e32 v3, 0xfffffc00, v3
	v_ashrrev_i32_e32 v0, 31, v15
	v_sub_u32_e32 v3, v2, v3
	v_lshrrev_b32_e32 v0, 26, v0
	v_lshrrev_b32_e32 v4, 4, v3
	v_add_u32_e32 v0, v15, v0
	v_bitop3_b32 v4, v4, v3, 32 bitop3:0x6c
	v_ashrrev_i32_e32 v3, 31, v3
	v_ashrrev_i32_e32 v0, 6, v0
	v_lshrrev_b32_e32 v3, 26, v3
	v_lshlrev_b32_e32 v5, 3, v0
	v_add_u32_e32 v3, v4, v3
	v_and_b32_e32 v5, -16, v5
	v_ashrrev_i32_e32 v3, 6, v3
	v_lshlrev_b32_e32 v0, 5, v0
	v_add_u32_e32 v5, v3, v5
	v_and_b32_e32 v14, 32, v0
	v_mul_i32_i24_e32 v0, 64, v3
	v_sub_u32_e32 v0, v4, v0
	v_mov_b32_e32 v7, 1
	v_lshlrev_b32_e32 v4, 1, v5
	v_lshrrev_b32_e32 v6, 2, v5
	v_and_b32_e32 v3, 3, v3
	s_mov_b32 s1, 0x7fffffe0
	v_ashrrev_i16_sdwa v0, v7, sext(v0) dst_sel:DWORD dst_unused:UNUSED_PAD src0_sel:DWORD src1_sel:BYTE_0
	v_and_b32_e32 v4, 24, v4
	v_and_b32_e32 v6, 4, v6
	v_and_or_b32 v3, v5, s1, v3
	v_bfe_i32 v16, v0, 0, 16
	v_or3_b32 v3, v3, v6, v4
	s_mov_b64 s[8:9], s[94:95]
	v_add_u32_e32 v0, v14, v16
	v_mul_lo_u32 v17, v5, s82
	v_mul_lo_u32 v3, v3, s8
	v_add_u32_e32 v2, 0x2000, v2
	v_add_lshl_u32 v196, v0, v17, 1
	v_add_lshl_u32 v0, v3, v0, 1
	v_ashrrev_i32_e32 v3, 31, v2
	v_lshrrev_b32_e32 v3, 22, v3
	v_add_u32_e32 v3, v2, v3
	v_ashrrev_i32_e32 v3, 10, v3
	v_mul_i32_i24_e32 v4, 0x400, v3
	v_sub_u32_e32 v2, v2, v4
	v_lshrrev_b32_e32 v4, 4, v2
	v_writelane_b32 v254, s53, 57
	v_bitop3_b32 v2, v4, v2, 32 bitop3:0x6c
	v_writelane_b32 v254, s51, 55
	v_ashrrev_i32_e32 v5, 31, v2
	v_writelane_b32 v254, s48, 53
	v_lshrrev_b32_e32 v5, 26, v5
	v_writelane_b32 v254, s84, 49
	v_lshlrev_b32_e32 v4, 3, v3
	v_add_u32_e32 v5, v2, v5
	v_writelane_b32 v254, s85, 50
	v_and_b32_e32 v4, -16, v4
	v_ashrrev_i32_e32 v6, 6, v5
	v_writelane_b32 v254, s57, 37
	s_ashr_i32 s0, s2, 6
	v_add_u32_e32 v4, v6, v4
	v_lshlrev_b32_e32 v3, 5, v3
	v_and_b32_e32 v6, 3, v6
	v_and_b32_e32 v18, 32, v3
	v_and_b32_e32 v3, 0xc0, v5
	v_and_or_b32 v6, v4, s1, v6
	v_mul_lo_u32 v20, v4, s82
	s_ashr_i32 s1, s2, 8
	v_writelane_b32 v254, s82, 43
	s_lshl_b64 s[36:37], s[82:83], 8
	s_lshl_b64 s[78:79], s[94:95], 8
	s_lshl_b32 s3, s0, 10
	v_sub_u32_e32 v2, v2, v3
	v_lshlrev_b32_e32 v3, 1, v4
	v_lshrrev_b32_e32 v5, 2, v4
	s_add_u32 s88, s10, s80
	v_ashrrev_i16_sdwa v2, v7, sext(v2) dst_sel:DWORD dst_unused:UNUSED_PAD src0_sel:DWORD src1_sel:BYTE_0
	v_and_b32_e32 v3, 24, v3
	v_and_b32_e32 v5, 4, v5
	s_addc_u32 s89, s11, s81
	s_add_i32 s24, s3, 0
	v_bfe_i32 v19, v2, 0, 16
	v_or3_b32 v3, v6, v5, v3
	v_writelane_b32 v254, s83, 44
	s_add_i32 m0, s24, 0x10000
	v_add_u32_e32 v2, v18, v19
	v_mul_lo_u32 v3, v3, s8
	global_load_lds_dwordx4 v0, s[88:89]
	s_add_i32 m0, s24, 0x12000
	v_readlane_b32 s8, v254, 11
	v_add_lshl_u32 v200, v3, v2, 1
	v_readlane_b32 s9, v254, 12
	s_add_u32 s4, s8, s4
	global_load_lds_dwordx4 v200, s[88:89]
	s_addc_u32 s5, s9, s5
	s_mov_b32 m0, s24
	s_add_i32 s33, s24, 0x2000
	v_add_lshl_u32 v198, v2, v20, 1
	global_load_lds_dwordx4 v196, s[4:5]
	s_mov_b32 m0, s33
	s_add_u32 s14, s88, s78
	global_load_lds_dwordx4 v198, s[4:5]
	s_addc_u32 s15, s89, s79
	s_add_i32 m0, s24, 0x14000
	v_mov_b32_e32 v201, v1
	global_load_lds_dwordx4 v0, s[14:15]
	s_add_i32 m0, s24, 0x16000
	v_lshl_add_u64 v[10:11], s[14:15], 0, v[0:1]
	v_lshl_add_u64 v[12:13], s[14:15], 0, v[200:201]
	global_load_lds_dwordx4 v200, s[14:15]
	s_add_u32 s14, s4, s36
	s_addc_u32 s15, s5, s37
	s_add_i32 s38, s24, 0x4000
	s_mov_b32 m0, s38
	s_add_i32 s39, s24, 0x6000
	global_load_lds_dwordx4 v196, s[14:15]
	s_mov_b32 m0, s39
	v_mov_b32_e32 v197, v1
	global_load_lds_dwordx4 v198, s[14:15]
	v_mov_b32_e32 v199, v1
	v_lshl_add_u64 v[2:3], s[88:89], 0, v[0:1]
	v_lshl_add_u64 v[4:5], s[88:89], 0, v[200:201]
	v_lshl_add_u64 v[6:7], s[4:5], 0, v[196:197]
	v_lshl_add_u64 v[8:9], s[4:5], 0, v[198:199]
	s_cmp_lg_u32 s1, 1
	s_cbranch_scc1 .LBB0_449
.LBB0_449:
	s_add_i32 m0, s24, 0x18000
	v_lshl_add_u64 v[2:3], v[2:3], 0, s[60:61]
	s_waitcnt vmcnt(0)
	s_barrier
	global_load_lds_dwordx4 v[2:3], off
	v_lshl_add_u64 v[2:3], v[4:5], 0, s[60:61]
	s_add_i32 m0, s24, 0x1a000
	s_add_i32 s40, s24, 0x8000
	global_load_lds_dwordx4 v[2:3], off
	v_lshl_add_u64 v[2:3], v[6:7], 0, s[60:61]
	s_mov_b32 m0, s40
	s_add_i32 s41, s24, 0xa000
	global_load_lds_dwordx4 v[2:3], off
	v_lshl_add_u64 v[2:3], v[8:9], 0, s[60:61]
	s_mov_b32 m0, s41
	v_lshrrev_b32_e32 v22, 1, v15
	global_load_lds_dwordx4 v[2:3], off
	s_add_i32 m0, s24, 0x1c000
	v_lshl_add_u64 v[2:3], v[10:11], 0, s[60:61]
	global_load_lds_dwordx4 v[2:3], off
	v_lshl_add_u64 v[2:3], v[12:13], 0, s[60:61]
	s_add_i32 m0, s24, 0x1e000
	v_and_b32_e32 v22, 24, v22
	global_load_lds_dwordx4 v[2:3], off
	v_and_b32_e32 v21, 15, v15
	v_lshlrev_b32_e32 v23, 1, v22
	v_lshlrev_b32_e32 v15, 2, v15
	s_lshl_b32 s0, s0, 5
	v_lshl_or_b32 v210, s1, 6, v21
	v_lshl_or_b32 v21, v21, 6, v23
	s_lshl_b32 s1, s1, 13
	v_and_b32_e32 v15, 32, v15
	s_and_b32 s0, s0, 0x60
	v_bitop3_b32 v23, v21, s1, v15 bitop3:0xde
	s_lshl_b32 s1, s0, 7
	v_bitop3_b32 v211, v21, s1, v15 bitop3:0xde
	v_readlane_b32 s1, v254, 13
	v_readlane_b32 s8, v253, 30
	s_ashr_i32 s43, s1, 31
	v_readlane_b32 s1, v254, 5
	v_readlane_b32 s8, v254, 37
	s_mul_i32 s53, s1, s8
	v_cvt_f32_u32_e32 v2, s53
	v_or_b32_e32 v212, s0, v22
	s_sub_i32 s0, 0, s53
	v_mov_b32_e32 v3, v1
	v_rcp_iflag_f32_e32 v2, v2
	s_waitcnt vmcnt(6)
	v_readlane_b32 s9, v253, 31
	s_lshr_b32 s48, s54, 3
	v_mul_f32_e32 v2, 0x4f7ffffe, v2
	v_cvt_u32_f32_e32 v2, v2
	s_add_i32 s42, s73, -2
	s_mov_b32 s27, s9
	s_and_b32 s51, s54, 7
	v_readfirstlane_b32 s1, v2
	v_cvt_f32_u32_e32 v2, s25
	s_mul_i32 s0, s0, s1
	s_mul_hi_u32 s0, s1, s0
	s_add_i32 s58, s1, s0
	v_rcp_iflag_f32_e32 v2, v2
	s_sub_i32 s0, 0, s25
	s_add_i32 s52, s48, 1
	s_mov_b32 s56, 0
	v_mul_f32_e32 v2, 0x4f7ffffe, v2
	v_cvt_u32_f32_e32 v2, v2
	v_add_u32_e32 v213, 0, v23
	s_barrier
	v_readfirstlane_b32 s1, v2
	v_add_u32_e32 v2, v17, v14
	v_add_lshl_u32 v2, v2, v16, 1
	s_mul_i32 s0, s0, s1
	v_lshl_add_u64 v[202:203], s[36:37], 0, v[2:3]
	v_add_u32_e32 v2, v20, v18
	s_mul_hi_u32 s0, s1, s0
	v_add_lshl_u32 v2, v2, v19, 1
	s_add_i32 s64, s1, s0
	v_lshl_add_u64 v[204:205], s[36:37], 0, v[2:3]
	s_branch .LBB0_451

; #define PG8_STAGE(bufoff, gbase, voff) do { _Pragma("unroll") for (int _i = 0; _i < 2; ++_i) \
;         __builtin_amdgcn_global_load_lds((const unsigned*)((const char*)(gbase) + (voff)[_i]), (LAS unsigned*)(lds + (bufoff) + ldsw + _i * 8192), 16, 0, 0); } while (0)
; #define PG8_LDA(dst, b, h) do { _Pragma("unroll") for (int m = 0; m < 4; ++m) _Pragma("unroll") for (int k = 0; k < 2; ++k) dst[m][k] = *(const LAS bf16x8*)(lds + PG8_SA(b, h) + aoff + m * 2048 + k * 1024); } while (0)
; #define PG8_LDB(dst, b, h) do { _Pragma("unroll") for (int n = 0; n < 2; ++n) _Pragma("unroll") for (int k = 0; k < 2; ++k) dst[n][k] = *(const LAS bf16x8*)(lds + PG8_SB(b, h) + boff + n * 2048 + k * 1024); } while (0)
; #define PG8_MMA(ai, bj, At, Bt) do { __builtin_amdgcn_s_setprio(1); _Pragma("unroll") for (int m = 0; m < 4; ++m) _Pragma("unroll") for (int n = 0; n < 2; ++n) _Pragma("unroll") for (int k = 0; k < 2; ++k) \
;         acc[ai][bj][m][n] = __builtin_amdgcn_mfma_f32_16x16x32_bf16(Bt[n][k], At[m][k], acc[ai][bj][m][n], 0, 0, 0); __builtin_amdgcn_s_setprio(0); } while (0)
; #define PG8_WAIT_L(n) asm volatile("s_waitcnt lgkmcnt(" #n ")" ::: "memory")
; #define PG8_BAR __builtin_amdgcn_s_barrier()
; #define PG8_SCHED __builtin_amdgcn_sched_barrier(0)
; template <class Epi>
; __device__ __forceinline__ void gemm_phase(LAS unsigned char* lds, const Gemm g, const Sched& S, const Epi& E) {
;     ...
;         const bool has_next = S.next(ui + 1, nxt);
;         const char* nA = has_next ? (const char*)g.A + nxt.ao : cA; const char* nB = has_next ? (const char*)g.Bt + nxt.bo : cB;
;         for (int t = 0; t < nt; t += 2) {
;             const bool last = (t == nt - 2);
;             const char* a1 = cA + (size_t)(t + 1) * kstep;
;             const char* a2 = last ? nA : cA + (size_t)(t + 2) * kstep; const char* b2 = last ? nB : cB + (size_t)(t + 2) * kstep;
;             const char* a3 = a2 + kstep; const char* b3 = b2 + kstep;
;             PG8_LDB(B0, 0, 0); PG8_SCHED; PG8_LDA(At, 0, 0); PG8_STAGE(PG8_SA(1, 1), a1 + hstepA, voffA);
;             PG8_WAIT_L(8); PG8_BAR; PG8_WAIT_L(0); PG8_MMA(0, 0, At, B0); PG8_BAR; PG8_SCHED;
;             PG8_LDB(B1, 0, 1); PG8_STAGE(PG8_SB(0, 0), b2, voffB);
;             PG8_BAR; PG8_WAIT_L(0); PG8_MMA(0, 1, At, B1); PG8_BAR;
;     ...
;                     for (int n = 0; n < 2; ++n) acc[a][b][m][n] = (f32x4){0.f, 0.f, 0.f, 0.f};
.LBB0_460:
	v_mov_b64_e32 v[2:3], s[26:27]
	v_readlane_b32 s8, v254, 11
	v_cmp_lt_i64_e32 vcc, s[84:85], v[2:3]
	v_readlane_b32 s9, v254, 12
	s_add_u32 s84, s8, s80
	s_addc_u32 s85, s9, s81
	s_and_b64 s[14:15], vcc, exec
	s_cselect_b32 s71, s85, s5
	s_cselect_b32 s57, s84, s4
	s_add_u32 s86, s10, s82
	s_addc_u32 s87, s11, s83
	s_and_b64 s[14:15], vcc, exec
	s_cselect_b32 s59, s87, s89
	s_cselect_b32 s72, s86, s88
	s_add_u32 s4, s4, 0x80
	s_addc_u32 s5, s5, 0
	s_add_u32 s34, s88, 0x100
	v_mov_b32_e32 v2, 0
	s_addc_u32 s35, s89, 0
	s_mov_b32 s88, 0
	v_mov_b32_e32 v3, v2
	v_mov_b32_e32 v4, v2
	v_mov_b32_e32 v5, v2
	v_mov_b32_e32 v6, v2
	v_mov_b32_e32 v7, v2
	v_mov_b32_e32 v8, v2
	v_mov_b32_e32 v9, v2
	v_mov_b32_e32 v18, v2
	v_mov_b32_e32 v19, v2
	v_mov_b32_e32 v20, v2
	v_mov_b32_e32 v21, v2
	v_mov_b32_e32 v22, v2
	v_mov_b32_e32 v23, v2
	v_mov_b32_e32 v24, v2
	v_mov_b32_e32 v25, v2
	v_mov_b32_e32 v34, v2
	v_mov_b32_e32 v35, v2
	v_mov_b32_e32 v36, v2
	v_mov_b32_e32 v37, v2
	v_mov_b32_e32 v38, v2
	v_mov_b32_e32 v39, v2
	v_mov_b32_e32 v40, v2
	v_mov_b32_e32 v41, v2
	v_mov_b32_e32 v50, v2
	v_mov_b32_e32 v51, v2
	v_mov_b32_e32 v52, v2
	v_mov_b32_e32 v53, v2
	v_mov_b32_e32 v54, v2
	v_mov_b32_e32 v55, v2
	v_mov_b32_e32 v56, v2
	v_mov_b32_e32 v57, v2
	v_mov_b32_e32 v10, v2
	v_mov_b32_e32 v11, v2
	v_mov_b32_e32 v12, v2
	v_mov_b32_e32 v13, v2
	v_mov_b32_e32 v14, v2
	v_mov_b32_e32 v15, v2
	v_mov_b32_e32 v16, v2
	v_mov_b32_e32 v17, v2
	v_mov_b32_e32 v26, v2
	v_mov_b32_e32 v27, v2
	v_mov_b32_e32 v28, v2
	v_mov_b32_e32 v29, v2
	v_mov_b32_e32 v30, v2
	v_mov_b32_e32 v31, v2
	v_mov_b32_e32 v32, v2
	v_mov_b32_e32 v33, v2
	v_mov_b32_e32 v42, v2
	v_mov_b32_e32 v43, v2
	v_mov_b32_e32 v44, v2
	v_mov_b32_e32 v45, v2
	v_mov_b32_e32 v46, v2
	s_waitcnt lgkmcnt(0)
	v_mov_b32_e32 v47, v2
	v_mov_b32_e32 v48, v2
	v_mov_b32_e32 v49, v2
	v_mov_b32_e32 v58, v2
	v_mov_b32_e32 v59, v2
	v_mov_b32_e32 v60, v2
	v_mov_b32_e32 v61, v2
	v_mov_b32_e32 v62, v2
	v_mov_b32_e32 v63, v2
	v_mov_b32_e32 v64, v2
	v_mov_b32_e32 v65, v2
	v_mov_b32_e32 v66, v2
	v_mov_b32_e32 v67, v2
	v_mov_b32_e32 v68, v2
	v_mov_b32_e32 v69, v2
	v_mov_b32_e32 v70, v2
	v_mov_b32_e32 v71, v2
	v_mov_b32_e32 v72, v2
	v_mov_b32_e32 v73, v2
	v_mov_b32_e32 v86, v2
	v_mov_b32_e32 v87, v2
	v_mov_b32_e32 v88, v2
	v_mov_b32_e32 v89, v2
	v_mov_b32_e32 v90, v2
	v_mov_b32_e32 v91, v2
	v_mov_b32_e32 v92, v2
	v_mov_b32_e32 v93, v2
	v_mov_b32_e32 v110, v2
	v_mov_b32_e32 v111, v2
	v_mov_b32_e32 v112, v2
	v_mov_b32_e32 v113, v2
	v_mov_b32_e32 v118, v2
	v_mov_b32_e32 v119, v2
	v_mov_b32_e32 v120, v2
	v_mov_b32_e32 v121, v2
	v_mov_b32_e32 v138, v2
	v_mov_b32_e32 v139, v2
	v_mov_b32_e32 v140, v2
	v_mov_b32_e32 v141, v2
	v_mov_b32_e32 v142, v2
	v_mov_b32_e32 v143, v2
	v_mov_b32_e32 v144, v2
	v_mov_b32_e32 v145, v2
	v_mov_b32_e32 v74, v2
	v_mov_b32_e32 v75, v2
	v_mov_b32_e32 v76, v2
	v_mov_b32_e32 v77, v2
	v_mov_b32_e32 v78, v2
	v_mov_b32_e32 v79, v2
	v_mov_b32_e32 v80, v2
	v_mov_b32_e32 v81, v2
	v_mov_b32_e32 v102, v2
	v_mov_b32_e32 v103, v2
	v_mov_b32_e32 v104, v2
	v_mov_b32_e32 v105, v2
	v_mov_b32_e32 v106, v2
	v_mov_b32_e32 v107, v2
	v_mov_b32_e32 v108, v2
	v_mov_b32_e32 v109, v2
	v_mov_b32_e32 v126, v2
	v_mov_b32_e32 v127, v2
	v_mov_b32_e32 v128, v2
	v_mov_b32_e32 v129, v2
	v_mov_b32_e32 v134, v2
	v_mov_b32_e32 v135, v2
	v_mov_b32_e32 v136, v2
	v_mov_b32_e32 v137, v2
	v_mov_b32_e32 v154, v2
	v_mov_b32_e32 v155, v2
	v_mov_b32_e32 v156, v2
	v_mov_b32_e32 v157, v2
	v_mov_b32_e32 v158, v2
	v_mov_b32_e32 v159, v2
	v_mov_b32_e32 v160, v2
	v_mov_b32_e32 v161, v2
	v_readfirstlane_b32 s98, v219
	s_nop 1
	s_bitcmp1_b32 s98, 8
	s_cbranch_scc0 .Lresync_y_461
	s_barrier
.Lresync_y_461:
.LBB0_461:
	s_add_i32 s14, s88, 2
	s_add_u32 s8, s4, 0x80
	s_addc_u32 s9, s5, 0
	s_add_i32 s15, 0, 0x10000
	v_add_u32_e32 v114, s15, v211
	ds_read_b128 v[82:85], v114
	ds_read_b128 v[94:97], v114 offset:1024
	ds_read_b128 v[98:101], v114 offset:2048
	ds_read_b128 v[114:117], v114 offset:3072
	s_cmp_eq_u32 s42, s88
	s_cselect_b32 s88, s57, s8
	s_cselect_b32 s89, s71, s9
	s_cselect_b32 s91, s59, s35
	s_cselect_b32 s90, s72, s34
	v_lshl_add_u64 v[178:179], s[4:5], 0, v[202:203]
	s_add_i32 m0, s24, 0xc000
	ds_read_b128 v[122:125], v213
	ds_read_b128 v[130:133], v213 offset:1024
	ds_read_b128 v[146:149], v213 offset:2048
	ds_read_b128 v[150:153], v213 offset:3072
	ds_read_b128 v[162:165], v213 offset:4096
	ds_read_b128 v[166:169], v213 offset:5120
	ds_read_b128 v[170:173], v213 offset:6144
	ds_read_b128 v[174:177], v213 offset:7168
	global_load_lds_dwordx4 v[178:179], off
	v_lshl_add_u64 v[178:179], s[4:5], 0, v[204:205]
	s_add_i32 m0, s24, 0xe000
	s_nop 0
	global_load_lds_dwordx4 v[178:179], off
	s_add_i32 s8, 0, 0x14000
	v_add_u32_e32 v190, s8, v211
	ds_read_b128 v[178:181], v190
	ds_read_b128 v[182:185], v190 offset:1024
	ds_read_b128 v[186:189], v190 offset:2048
	ds_read_b128 v[190:193], v190 offset:3072
	s_waitcnt vmcnt(8)
	s_waitcnt lgkmcnt(0)
	v_mfma_f32_16x16x32_bf16 v[158:161], v[82:85], v[122:125], v[158:161]
	v_mfma_f32_16x16x32_bf16 v[154:157], v[98:101], v[122:125], v[154:157]
	v_mfma_f32_16x16x32_bf16 v[134:137], v[82:85], v[146:149], v[134:137]
	v_mfma_f32_16x16x32_bf16 v[126:129], v[98:101], v[146:149], v[126:129]
	s_barrier
; #define PG8_STAGE(bufoff, gbase, voff) do { _Pragma("unroll") for (int _i = 0; _i < 2; ++_i) \
;         __builtin_amdgcn_global_load_lds((const unsigned*)((const char*)(gbase) + (voff)[_i]), (LAS unsigned*)(lds + (bufoff) + ldsw + _i * 8192), 16, 0, 0); } while (0)
; #define PG8_LDA(dst, b, h) do { _Pragma("unroll") for (int m = 0; m < 4; ++m) _Pragma("unroll") for (int k = 0; k < 2; ++k) dst[m][k] = *(const LAS bf16x8*)(lds + PG8_SA(b, h) + aoff + m * 2048 + k * 1024); } while (0)
; #define PG8_LDB(dst, b, h) do { _Pragma("unroll") for (int n = 0; n < 2; ++n) _Pragma("unroll") for (int k = 0; k < 2; ++k) dst[n][k] = *(const LAS bf16x8*)(lds + PG8_SB(b, h) + boff + n * 2048 + k * 1024); } while (0)
; #define PG8_MMA(ai, bj, At, Bt) do { __builtin_amdgcn_s_setprio(1); _Pragma("unroll") for (int m = 0; m < 4; ++m) _Pragma("unroll") for (int n = 0; n < 2; ++n) _Pragma("unroll") for (int k = 0; k < 2; ++k) \
;         acc[ai][bj][m][n] = __builtin_amdgcn_mfma_f32_16x16x32_bf16(Bt[n][k], At[m][k], acc[ai][bj][m][n], 0, 0, 0); __builtin_amdgcn_s_setprio(0); } while (0)
; #define PG8_WAIT_V(n) asm volatile("s_waitcnt vmcnt(" #n ")" ::: "memory")
; #define PG8_WAIT_L(n) asm volatile("s_waitcnt lgkmcnt(" #n ")" ::: "memory")
; #define PG8_BAR __builtin_amdgcn_s_barrier()
; #define PG8_SCHED __builtin_amdgcn_sched_barrier(0)
; template <class Epi>
; __device__ __forceinline__ void gemm_phase(LAS unsigned char* lds, const Gemm g, const Sched& S, const Epi& E) {
;     ...
;             PG8_WAIT_L(8); PG8_BAR; PG8_WAIT_L(0); PG8_MMA(0, 0, At, B0); PG8_BAR; PG8_SCHED;
;             PG8_LDB(B1, 0, 1); PG8_STAGE(PG8_SB(0, 0), b2, voffB);
;             PG8_BAR; PG8_WAIT_L(0); PG8_MMA(0, 1, At, B1); PG8_BAR;
;             PG8_LDA(At, 0, 1); PG8_STAGE(PG8_SA(0, 0), a2, voffA);
;             PG8_BAR; PG8_WAIT_L(0); PG8_MMA(1, 0, At, B0); PG8_BAR; PG8_SCHED;
;             PG8_STAGE(PG8_SB(0, 1), b2 + hstepB, voffB);
;             PG8_WAIT_V(6); PG8_BAR; PG8_MMA(1, 1, At, B1); PG8_BAR;
	s_setprio 1
	v_mfma_f32_16x16x32_bf16 v[106:109], v[82:85], v[162:165], v[106:109]
	v_mfma_f32_16x16x32_bf16 v[102:105], v[98:101], v[162:165], v[102:105]
	v_mfma_f32_16x16x32_bf16 v[78:81], v[82:85], v[170:173], v[78:81]
	v_mfma_f32_16x16x32_bf16 v[74:77], v[98:101], v[170:173], v[74:77]
	v_mfma_f32_16x16x32_bf16 v[158:161], v[94:97], v[130:133], v[158:161]
	v_mfma_f32_16x16x32_bf16 v[154:157], v[114:117], v[130:133], v[154:157]
	v_mfma_f32_16x16x32_bf16 v[134:137], v[94:97], v[150:153], v[134:137]
	v_mfma_f32_16x16x32_bf16 v[126:129], v[114:117], v[150:153], v[126:129]
	v_mfma_f32_16x16x32_bf16 v[106:109], v[94:97], v[166:169], v[106:109]
	v_mfma_f32_16x16x32_bf16 v[102:105], v[114:117], v[166:169], v[102:105]
	v_mfma_f32_16x16x32_bf16 v[78:81], v[94:97], v[174:177], v[78:81]
	v_mfma_f32_16x16x32_bf16 v[74:77], v[114:117], v[174:177], v[74:77]
	v_mfma_f32_16x16x32_bf16 v[142:145], v[178:181], v[122:125], v[142:145]
	v_mfma_f32_16x16x32_bf16 v[118:121], v[178:181], v[146:149], v[118:121]
	v_mfma_f32_16x16x32_bf16 v[110:113], v[186:189], v[146:149], v[110:113]
	v_mfma_f32_16x16x32_bf16 v[90:93], v[178:181], v[162:165], v[90:93]
	v_mfma_f32_16x16x32_bf16 v[86:89], v[186:189], v[162:165], v[86:89]
	v_mfma_f32_16x16x32_bf16 v[70:73], v[178:181], v[170:173], v[70:73]
	v_mfma_f32_16x16x32_bf16 v[66:69], v[186:189], v[170:173], v[66:69]
	v_mfma_f32_16x16x32_bf16 v[142:145], v[182:185], v[130:133], v[142:145]
	v_mfma_f32_16x16x32_bf16 v[122:125], v[186:189], v[122:125], v[138:141]
	v_mfma_f32_16x16x32_bf16 v[118:121], v[182:185], v[150:153], v[118:121]
	v_mfma_f32_16x16x32_bf16 v[110:113], v[190:193], v[150:153], v[110:113]
	v_mfma_f32_16x16x32_bf16 v[90:93], v[182:185], v[166:169], v[90:93]
	v_mfma_f32_16x16x32_bf16 v[86:89], v[190:193], v[166:169], v[86:89]
	v_mfma_f32_16x16x32_bf16 v[70:73], v[182:185], v[174:177], v[70:73]
	v_mfma_f32_16x16x32_bf16 v[66:69], v[190:193], v[174:177], v[66:69]
	v_mfma_f32_16x16x32_bf16 v[122:125], v[190:193], v[130:133], v[122:125]
	s_setprio 0
	s_barrier
	s_add_i32 s9, s15, s3
	v_lshl_add_u64 v[194:195], s[90:91], 0, v[0:1]
	s_mov_b32 m0, s9
	s_nop 0
	global_load_lds_dwordx4 v[194:195], off
	v_lshl_add_u64 v[206:207], s[90:91], 0, v[200:201]
	s_add_i32 m0, s9, 0x2000
	s_nop 0
	global_load_lds_dwordx4 v[206:207], off
	s_mov_b32 m0, s24
	v_lshl_add_u64 v[208:209], s[88:89], 0, v[196:197]
	ds_read_b128 v[130:133], v213 offset:16384
	ds_read_b128 v[138:141], v213 offset:17408
	ds_read_b128 v[146:149], v213 offset:18432
	ds_read_b128 v[150:153], v213 offset:19456
	ds_read_b128 v[162:165], v213 offset:20480
	ds_read_b128 v[166:169], v213 offset:21504
	ds_read_b128 v[170:173], v213 offset:22528
	ds_read_b128 v[174:177], v213 offset:23552
	global_load_lds_dwordx4 v[208:209], off
	v_lshl_add_u64 v[214:215], s[88:89], 0, v[198:199]
	s_mov_b32 m0, s33
	s_nop 0
	global_load_lds_dwordx4 v[214:215], off
	s_add_u32 s90, s90, s78
	s_addc_u32 s91, s91, s79
	s_add_i32 s8, s8, s3
	v_lshl_add_u64 v[216:217], s[90:91], 0, v[0:1]
	s_mov_b32 m0, s8
	v_lshl_add_u64 v[222:223], s[90:91], 0, v[200:201]
	global_load_lds_dwordx4 v[216:217], off
	s_add_i32 m0, s8, 0x2000
	s_nop 0
	global_load_lds_dwordx4 v[222:223], off
	s_waitcnt vmcnt(8)
	s_waitcnt lgkmcnt(0)
	v_mfma_f32_16x16x32_bf16 v[62:65], v[82:85], v[130:133], v[62:65]
	v_mfma_f32_16x16x32_bf16 v[58:61], v[98:101], v[130:133], v[58:61]
	v_mfma_f32_16x16x32_bf16 v[46:49], v[82:85], v[146:149], v[46:49]
	v_mfma_f32_16x16x32_bf16 v[42:45], v[98:101], v[146:149], v[42:45]
	s_barrier
	s_setprio 1
	v_mfma_f32_16x16x32_bf16 v[30:33], v[82:85], v[162:165], v[30:33]
	v_mfma_f32_16x16x32_bf16 v[26:29], v[98:101], v[162:165], v[26:29]
	v_mfma_f32_16x16x32_bf16 v[14:17], v[82:85], v[170:173], v[14:17]
	v_mfma_f32_16x16x32_bf16 v[10:13], v[98:101], v[170:173], v[10:13]
	v_mfma_f32_16x16x32_bf16 v[62:65], v[94:97], v[138:141], v[62:65]
	v_mfma_f32_16x16x32_bf16 v[58:61], v[114:117], v[138:141], v[58:61]
	v_mfma_f32_16x16x32_bf16 v[46:49], v[94:97], v[150:153], v[46:49]
	v_mfma_f32_16x16x32_bf16 v[42:45], v[114:117], v[150:153], v[42:45]
	v_mfma_f32_16x16x32_bf16 v[30:33], v[94:97], v[166:169], v[30:33]
	v_mfma_f32_16x16x32_bf16 v[26:29], v[114:117], v[166:169], v[26:29]
	v_mfma_f32_16x16x32_bf16 v[14:17], v[94:97], v[174:177], v[14:17]
	v_mfma_f32_16x16x32_bf16 v[10:13], v[114:117], v[174:177], v[10:13]
	v_mfma_f32_16x16x32_bf16 v[54:57], v[178:181], v[130:133], v[54:57]
	v_mfma_f32_16x16x32_bf16 v[50:53], v[186:189], v[130:133], v[50:53]
	v_mfma_f32_16x16x32_bf16 v[38:41], v[178:181], v[146:149], v[38:41]
	v_mfma_f32_16x16x32_bf16 v[34:37], v[186:189], v[146:149], v[34:37]
	v_mfma_f32_16x16x32_bf16 v[22:25], v[178:181], v[162:165], v[22:25]
	v_mfma_f32_16x16x32_bf16 v[18:21], v[186:189], v[162:165], v[18:21]
	v_mfma_f32_16x16x32_bf16 v[6:9], v[178:181], v[170:173], v[6:9]
	v_mfma_f32_16x16x32_bf16 v[2:5], v[186:189], v[170:173], v[2:5]
	v_mfma_f32_16x16x32_bf16 v[54:57], v[182:185], v[138:141], v[54:57]
	v_mfma_f32_16x16x32_bf16 v[50:53], v[190:193], v[138:141], v[50:53]
	v_mfma_f32_16x16x32_bf16 v[38:41], v[182:185], v[150:153], v[38:41]
	v_mfma_f32_16x16x32_bf16 v[34:37], v[190:193], v[150:153], v[34:37]
	v_mfma_f32_16x16x32_bf16 v[22:25], v[182:185], v[166:169], v[22:25]
	v_mfma_f32_16x16x32_bf16 v[18:21], v[190:193], v[166:169], v[18:21]
	v_mfma_f32_16x16x32_bf16 v[6:9], v[182:185], v[174:177], v[6:9]
	v_mfma_f32_16x16x32_bf16 v[2:5], v[190:193], v[174:177], v[2:5]
	s_setprio 0
	s_barrier
; #define PG8_STAGE(bufoff, gbase, voff) do { _Pragma("unroll") for (int _i = 0; _i < 2; ++_i) \
;         __builtin_amdgcn_global_load_lds((const unsigned*)((const char*)(gbase) + (voff)[_i]), (LAS unsigned*)(lds + (bufoff) + ldsw + _i * 8192), 16, 0, 0); } while (0)
; #define PG8_LDA(dst, b, h) do { _Pragma("unroll") for (int m = 0; m < 4; ++m) _Pragma("unroll") for (int k = 0; k < 2; ++k) dst[m][k] = *(const LAS bf16x8*)(lds + PG8_SA(b, h) + aoff + m * 2048 + k * 1024); } while (0)
; #define PG8_LDB(dst, b, h) do { _Pragma("unroll") for (int n = 0; n < 2; ++n) _Pragma("unroll") for (int k = 0; k < 2; ++k) dst[n][k] = *(const LAS bf16x8*)(lds + PG8_SB(b, h) + boff + n * 2048 + k * 1024); } while (0)
; #define PG8_MMA(ai, bj, At, Bt) do { __builtin_amdgcn_s_setprio(1); _Pragma("unroll") for (int m = 0; m < 4; ++m) _Pragma("unroll") for (int n = 0; n < 2; ++n) _Pragma("unroll") for (int k = 0; k < 2; ++k) \
;         acc[ai][bj][m][n] = __builtin_amdgcn_mfma_f32_16x16x32_bf16(Bt[n][k], At[m][k], acc[ai][bj][m][n], 0, 0, 0); __builtin_amdgcn_s_setprio(0); } while (0)
; #define PG8_WAIT_L(n) asm volatile("s_waitcnt lgkmcnt(" #n ")" ::: "memory")
; #define PG8_BAR __builtin_amdgcn_s_barrier()
; #define PG8_SCHED __builtin_amdgcn_sched_barrier(0)
; template <class Epi>
; __device__ __forceinline__ void gemm_phase(LAS unsigned char* lds, const Gemm g, const Sched& S, const Epi& E) {
;     ...
;             PG8_LDB(B0, 1, 0); PG8_SCHED; PG8_LDA(At, 1, 0); PG8_STAGE(PG8_SA(0, 1), a2 + hstepA, voffA);
;             PG8_WAIT_L(8); PG8_BAR; PG8_WAIT_L(0); PG8_MMA(0, 0, At, B0); PG8_BAR; PG8_SCHED;
;             PG8_LDB(B1, 1, 1); PG8_STAGE(PG8_SB(1, 0), b3, voffB);
;             PG8_BAR; PG8_WAIT_L(0); PG8_MMA(0, 1, At, B1); PG8_BAR;
	s_add_i32 s8, 0, 0x18000
	v_add_u32_e32 v114, s8, v211
	ds_read_b128 v[82:85], v114
	ds_read_b128 v[94:97], v114 offset:1024
	ds_read_b128 v[98:101], v114 offset:2048
	ds_read_b128 v[114:117], v114 offset:3072
	s_add_u32 s88, s88, s36
	s_addc_u32 s89, s89, s37
	s_mov_b32 m0, s38
	v_lshl_add_u64 v[178:179], s[88:89], 0, v[196:197]
	ds_read_b128 v[130:133], v213 offset:32768
	ds_read_b128 v[138:141], v213 offset:33792
	ds_read_b128 v[146:149], v213 offset:34816
	ds_read_b128 v[150:153], v213 offset:35840
	ds_read_b128 v[162:165], v213 offset:36864
	ds_read_b128 v[166:169], v213 offset:37888
	ds_read_b128 v[170:173], v213 offset:38912
	ds_read_b128 v[174:177], v213 offset:39936
	global_load_lds_dwordx4 v[178:179], off
	v_lshl_add_u64 v[178:179], s[88:89], 0, v[198:199]
	s_mov_b32 m0, s39
	s_nop 0
	global_load_lds_dwordx4 v[178:179], off
	s_add_i32 s9, 0, 0x1c000
	v_add_u32_e32 v190, s9, v211
	ds_read_b128 v[178:181], v190
	ds_read_b128 v[182:185], v190 offset:1024
	ds_read_b128 v[186:189], v190 offset:2048
	ds_read_b128 v[190:193], v190 offset:3072
	s_waitcnt vmcnt(8)
	s_waitcnt lgkmcnt(0)
	v_mfma_f32_16x16x32_bf16 v[158:161], v[82:85], v[130:133], v[158:161]
	v_mfma_f32_16x16x32_bf16 v[154:157], v[98:101], v[130:133], v[154:157]
	v_mfma_f32_16x16x32_bf16 v[134:137], v[82:85], v[146:149], v[134:137]
	v_mfma_f32_16x16x32_bf16 v[126:129], v[98:101], v[146:149], v[126:129]
	s_barrier
	s_setprio 1
	v_mfma_f32_16x16x32_bf16 v[106:109], v[82:85], v[162:165], v[106:109]
	v_mfma_f32_16x16x32_bf16 v[102:105], v[98:101], v[162:165], v[102:105]
	v_mfma_f32_16x16x32_bf16 v[78:81], v[82:85], v[170:173], v[78:81]
	v_mfma_f32_16x16x32_bf16 v[74:77], v[98:101], v[170:173], v[74:77]
	v_mfma_f32_16x16x32_bf16 v[158:161], v[94:97], v[138:141], v[158:161]
	v_mfma_f32_16x16x32_bf16 v[154:157], v[114:117], v[138:141], v[154:157]
	v_mfma_f32_16x16x32_bf16 v[134:137], v[94:97], v[150:153], v[134:137]
	v_mfma_f32_16x16x32_bf16 v[126:129], v[114:117], v[150:153], v[126:129]
	v_mfma_f32_16x16x32_bf16 v[106:109], v[94:97], v[166:169], v[106:109]
	v_mfma_f32_16x16x32_bf16 v[102:105], v[114:117], v[166:169], v[102:105]
	v_mfma_f32_16x16x32_bf16 v[78:81], v[94:97], v[174:177], v[78:81]
	v_mfma_f32_16x16x32_bf16 v[74:77], v[114:117], v[174:177], v[74:77]
	v_mfma_f32_16x16x32_bf16 v[142:145], v[178:181], v[130:133], v[142:145]
	v_mfma_f32_16x16x32_bf16 v[122:125], v[186:189], v[130:133], v[122:125]
	v_mfma_f32_16x16x32_bf16 v[118:121], v[178:181], v[146:149], v[118:121]
	v_mfma_f32_16x16x32_bf16 v[110:113], v[186:189], v[146:149], v[110:113]
	v_mfma_f32_16x16x32_bf16 v[90:93], v[178:181], v[162:165], v[90:93]
	v_mfma_f32_16x16x32_bf16 v[86:89], v[186:189], v[162:165], v[86:89]
	v_mfma_f32_16x16x32_bf16 v[70:73], v[178:181], v[170:173], v[70:73]
	v_mfma_f32_16x16x32_bf16 v[66:69], v[186:189], v[170:173], v[66:69]
	v_mfma_f32_16x16x32_bf16 v[142:145], v[182:185], v[138:141], v[142:145]
	v_mfma_f32_16x16x32_bf16 v[138:141], v[190:193], v[138:141], v[122:125]
	v_mfma_f32_16x16x32_bf16 v[118:121], v[182:185], v[150:153], v[118:121]
	v_mfma_f32_16x16x32_bf16 v[110:113], v[190:193], v[150:153], v[110:113]
	v_mfma_f32_16x16x32_bf16 v[90:93], v[182:185], v[166:169], v[90:93]
	v_mfma_f32_16x16x32_bf16 v[86:89], v[190:193], v[166:169], v[86:89]
	v_mfma_f32_16x16x32_bf16 v[70:73], v[182:185], v[174:177], v[70:73]
	v_mfma_f32_16x16x32_bf16 v[66:69], v[190:193], v[174:177], v[66:69]
	s_setprio 0
	s_barrier
; #define PG8_STAGE(bufoff, gbase, voff) do { _Pragma("unroll") for (int _i = 0; _i < 2; ++_i) \
;         __builtin_amdgcn_global_load_lds((const unsigned*)((const char*)(gbase) + (voff)[_i]), (LAS unsigned*)(lds + (bufoff) + ldsw + _i * 8192), 16, 0, 0); } while (0)
; #define PG8_LDA(dst, b, h) do { _Pragma("unroll") for (int m = 0; m < 4; ++m) _Pragma("unroll") for (int k = 0; k < 2; ++k) dst[m][k] = *(const LAS bf16x8*)(lds + PG8_SA(b, h) + aoff + m * 2048 + k * 1024); } while (0)
; #define PG8_MMA(ai, bj, At, Bt) do { __builtin_amdgcn_s_setprio(1); _Pragma("unroll") for (int m = 0; m < 4; ++m) _Pragma("unroll") for (int n = 0; n < 2; ++n) _Pragma("unroll") for (int k = 0; k < 2; ++k) \
;         acc[ai][bj][m][n] = __builtin_amdgcn_mfma_f32_16x16x32_bf16(Bt[n][k], At[m][k], acc[ai][bj][m][n], 0, 0, 0); __builtin_amdgcn_s_setprio(0); } while (0)
; #define PG8_WAIT_V(n) asm volatile("s_waitcnt vmcnt(" #n ")" ::: "memory")
; #define PG8_WAIT_L(n) asm volatile("s_waitcnt lgkmcnt(" #n ")" ::: "memory")
; #define PG8_BAR __builtin_amdgcn_s_barrier()
; #define PG8_SCHED __builtin_amdgcn_sched_barrier(0)
; template <class Epi>
; __device__ __forceinline__ void gemm_phase(LAS unsigned char* lds, const Gemm g, const Sched& S, const Epi& E) {
;     ...
;             PG8_LDA(At, 1, 1); PG8_STAGE(PG8_SA(1, 0), a3, voffA);
;             PG8_BAR; PG8_WAIT_L(0); PG8_MMA(1, 0, At, B0); PG8_BAR; PG8_SCHED;
;             PG8_STAGE(PG8_SB(1, 1), b3 + hstepB, voffB);
;             PG8_WAIT_V(6); PG8_BAR; PG8_MMA(1, 1, At, B1); PG8_BAR;
;         }
;         E(acc, cur, wr, wc, fr, fq, pre);
;         if (!has_next) break;
;     __device__ __forceinline__ void operator()(const Acc& acc, const Unit& u, int wr, int wc, int fr, int fq, const Pre& pre) const {
;         const int row0 = u.pm * 256 + wr * 64 + fr, col0 = u.pn * 256 + wc * 32 + 8 * fq;
; #pragma unroll
;         for (int ai = 0; ai < 2; ++ai) {
;             u32x4 gw[4][2], pw[4][2];
; #pragma unroll
;             for (int m = 0; m < 4; ++m)
; #pragma unroll
;                 for (int bj = 0; bj < 2; ++bj) { const size_t off = (size_t)(row0 + ai * 128 + m * 16) * ldc + col0 + bj * 128;
;                     gw[m][bj] = *(const u32x4*)(gate + off); if (add) pw[m][bj] = *(const u32x4*)(O + off); }
	s_add_i32 s8, s8, s3
	v_lshl_add_u64 v[194:195], v[194:195], 0, s[60:61]
	s_mov_b32 m0, s8
	s_nop 0
	global_load_lds_dwordx4 v[194:195], off
	v_lshl_add_u64 v[194:195], v[206:207], 0, s[60:61]
	s_add_i32 m0, s8, 0x2000
	s_nop 0
	global_load_lds_dwordx4 v[194:195], off
	s_mov_b32 m0, s40
	v_lshl_add_u64 v[194:195], v[208:209], 0, s[60:61]
	ds_read_b128 v[122:125], v213 offset:49152
	ds_read_b128 v[130:133], v213 offset:50176
	ds_read_b128 v[146:149], v213 offset:51200
	ds_read_b128 v[150:153], v213 offset:52224
	ds_read_b128 v[162:165], v213 offset:53248
	ds_read_b128 v[166:169], v213 offset:54272
	ds_read_b128 v[170:173], v213 offset:55296
	ds_read_b128 v[174:177], v213 offset:56320
	global_load_lds_dwordx4 v[194:195], off
	v_lshl_add_u64 v[194:195], v[214:215], 0, s[60:61]
	s_mov_b32 m0, s41
	s_nop 0
	global_load_lds_dwordx4 v[194:195], off
	s_add_i32 s8, s9, s3
	v_lshl_add_u64 v[194:195], v[216:217], 0, s[60:61]
	s_mov_b32 m0, s8
	s_nop 0
	global_load_lds_dwordx4 v[194:195], off
	v_lshl_add_u64 v[194:195], v[222:223], 0, s[60:61]
	s_add_i32 m0, s8, 0x2000
	s_nop 0
	global_load_lds_dwordx4 v[194:195], off
	s_waitcnt vmcnt(8)
	s_waitcnt lgkmcnt(0)
	v_mfma_f32_16x16x32_bf16 v[62:65], v[82:85], v[122:125], v[62:65]
	v_mfma_f32_16x16x32_bf16 v[58:61], v[98:101], v[122:125], v[58:61]
	v_mfma_f32_16x16x32_bf16 v[46:49], v[82:85], v[146:149], v[46:49]
	v_mfma_f32_16x16x32_bf16 v[42:45], v[98:101], v[146:149], v[42:45]
	s_barrier
	s_setprio 1
	v_mfma_f32_16x16x32_bf16 v[30:33], v[82:85], v[162:165], v[30:33]
	v_mfma_f32_16x16x32_bf16 v[26:29], v[98:101], v[162:165], v[26:29]
	v_mfma_f32_16x16x32_bf16 v[14:17], v[82:85], v[170:173], v[14:17]
	v_mfma_f32_16x16x32_bf16 v[10:13], v[98:101], v[170:173], v[10:13]
	v_mfma_f32_16x16x32_bf16 v[62:65], v[94:97], v[130:133], v[62:65]
	v_mfma_f32_16x16x32_bf16 v[58:61], v[114:117], v[130:133], v[58:61]
	v_mfma_f32_16x16x32_bf16 v[46:49], v[94:97], v[150:153], v[46:49]
	v_mfma_f32_16x16x32_bf16 v[42:45], v[114:117], v[150:153], v[42:45]
	v_mfma_f32_16x16x32_bf16 v[30:33], v[94:97], v[166:169], v[30:33]
	v_mfma_f32_16x16x32_bf16 v[26:29], v[114:117], v[166:169], v[26:29]
	v_mfma_f32_16x16x32_bf16 v[14:17], v[94:97], v[174:177], v[14:17]
	v_mfma_f32_16x16x32_bf16 v[10:13], v[114:117], v[174:177], v[10:13]
	v_mfma_f32_16x16x32_bf16 v[54:57], v[178:181], v[122:125], v[54:57]
	v_mfma_f32_16x16x32_bf16 v[50:53], v[186:189], v[122:125], v[50:53]
	v_mfma_f32_16x16x32_bf16 v[38:41], v[178:181], v[146:149], v[38:41]
	v_mfma_f32_16x16x32_bf16 v[34:37], v[186:189], v[146:149], v[34:37]
	v_mfma_f32_16x16x32_bf16 v[22:25], v[178:181], v[162:165], v[22:25]
	v_mfma_f32_16x16x32_bf16 v[18:21], v[186:189], v[162:165], v[18:21]
	v_mfma_f32_16x16x32_bf16 v[6:9], v[178:181], v[170:173], v[6:9]
	v_mfma_f32_16x16x32_bf16 v[2:5], v[186:189], v[170:173], v[2:5]
	v_mfma_f32_16x16x32_bf16 v[54:57], v[182:185], v[130:133], v[54:57]
	v_mfma_f32_16x16x32_bf16 v[50:53], v[190:193], v[130:133], v[50:53]
	v_mfma_f32_16x16x32_bf16 v[38:41], v[182:185], v[150:153], v[38:41]
	v_mfma_f32_16x16x32_bf16 v[34:37], v[190:193], v[150:153], v[34:37]
	v_mfma_f32_16x16x32_bf16 v[22:25], v[182:185], v[166:169], v[22:25]
	v_mfma_f32_16x16x32_bf16 v[18:21], v[190:193], v[166:169], v[18:21]
	v_mfma_f32_16x16x32_bf16 v[6:9], v[182:185], v[174:177], v[6:9]
	v_mfma_f32_16x16x32_bf16 v[2:5], v[190:193], v[174:177], v[2:5]
	s_setprio 0
	s_add_u32 s4, s4, 0x100
	s_addc_u32 s5, s5, 0
	s_add_u32 s34, s34, 0x100
	s_addc_u32 s35, s35, 0
	s_cmp_ge_u32 s14, s73
	s_mov_b32 s88, s14
	s_barrier
	s_cbranch_scc0 .LBB0_461
	v_readfirstlane_b32 s98, v219
	s_nop 1
	s_bitcmp1_b32 s98, 8
	s_cbranch_scc1 .Lresync_x_461
	s_barrier
.Lresync_x_461:
	v_lshl_add_u32 v214, s67, 8, v210
	v_lshl_or_b32 v206, s55, 8, v212
	v_ashrrev_i32_e32 v207, 31, v206
	v_ashrrev_i32_e32 v82, 31, v214
	v_mul_lo_u32 v215, s12, v82
	v_mul_lo_u32 v238, s13, v214
	v_mad_u64_u32 v[82:83], s[4:5], s12, v214, v[206:207]
	v_add3_u32 v83, v238, v83, v215
	v_lshl_add_u64 v[84:85], v[82:83], 1, s[6:7]
	global_load_dwordx4 v[190:193], v[84:85], off
	v_cndmask_b32_e64 v94, 0, 1, s[76:77]
	v_cmp_ne_u32_e64 s[4:5], 1, v94
	s_andn2_b64 vcc, exec, s[76:77]
	v_lshl_add_u64 v[82:83], v[82:83], 1, s[62:63]
	s_cbranch_vccnz .LBB0_464
	global_load_dwordx4 v[150:153], v[82:83], off

; #define PG8_WAIT_V(n) asm volatile("s_waitcnt vmcnt(" #n ")" ::: "memory")
; #define PG8_BAR __builtin_amdgcn_s_barrier()
; template <class Epi>
; __device__ __forceinline__ void gemm_phase(LAS unsigned char* lds, const Gemm g, const Sched& S, const Epi& E) {
;     ...
;     PG8_WAIT_V(0);
;     if (wr == 0) PG8_BAR;
;     PG8_BAR;
.LBB0_527:
	s_waitcnt vmcnt(0)
	s_cmpk_gt_u32 s2, 0xff
	v_readlane_b32 s58, v253, 45
	v_readlane_b32 s64, v253, 47
	v_readlane_b32 s48, v254, 53
	v_readlane_b32 s51, v254, 55
	v_readlane_b32 s53, v254, 57
	v_readlane_b32 s59, v253, 46
	s_cbranch_scc1 .LBB0_529
.LBB0_529:
	v_readlane_b32 s38, v253, 30
	v_readlane_b32 s82, v254, 43
	v_readlane_b32 s84, v254, 49
	v_readlane_b32 s39, v253, 31
	v_readlane_b32 s83, v254, 44
	v_readlane_b32 s57, v254, 37
	v_readlane_b32 s85, v254, 50
	s_barrier

; #define LAS __attribute__((address_space(3)))
;     __device__ __forceinline__ bool next(int i, Unit& u) const {
;         const long L = (long)i * G + c; if (L >= total) return false;
;         const int z = (int)(L / per); int wgid = (int)(L % per);
;         { const int q = per / NXCD, r = per % NXCD, xcd = wgid % NXCD, off = wgid / NXCD; wgid = (xcd < r ? xcd * (q + 1) : r * (q + 1) + (xcd - r) * q) + off; }
;         const int nig = WGM * nN, gid = wgid / nig, fm = gid * WGM, gsz = (nM - fm) < WGM ? (nM - fm) : WGM;
;         u.pm = fm + ((wgid % nig) % gsz); u.pn = (wgid % nig) / gsz; u.zb = z / nh; u.zh = z % nh;
;         u.ao = u.zb * sAb + u.zh * sAh + u.pm * tA; u.bo = u.zb * sBb + u.zh * sBh + u.pn * tB; return true;
;     }
; template <class Epi>
; __device__ __forceinline__ void gemm_phase(LAS unsigned char* lds, const Gemm g, const Sched& S, const Epi& E) {
;     const int tid = otid(), wid = __builtin_amdgcn_readfirstlane(tid >> 6), lane = tid & 63, wr = wid >> 2, wc = wid & 3, fr = lane & 15, fq = lane >> 4;
;     const int nt = g.K / BK;
;     unsigned voffA[2], voffB[2];
; #pragma unroll
;     for (int i = 0; i < 2; ++i) { int R, C; stage_rc(tid * 16 + i * 8192, R, C); const int Rb = Epi::PERM ? ((R & ~31) + perm32(R & 31)) : R;
;         voffA[i] = (unsigned)(R * g.lda + C) * 2u; voffB[i] = (unsigned)(Rb * g.ldb + C) * 2u; }
;     const size_t kstep = (size_t)(BK * 2);
;     const size_t hstepA = (size_t)HALF * g.lda * 2, hstepB = (size_t)HALF * g.ldb * 2;
;     const unsigned ldsw = (unsigned)wid * 1024u;
;     const int aoff = lds_byte(wr * 64 + fr, fq * 8), boff = lds_byte(wc * 32 + fr, fq * 8);
;     ...
;     Unit cur, nxt; int ui = 0;
;     if (!S.next(0, cur)) return;
;     f32x4 acc[2][2][4][2];
; #pragma unroll
;     for (int a = 0; a < 2; ++a)
; #pragma unroll
;         for (int b = 0; b < 2; ++b)
; #pragma unroll
;             for (int m = 0; m < 4; ++m)
; #pragma unroll
;                 for (int n = 0; n < 2; ++n) acc[a][b][m][n] = (f32x4){0.f, 0.f, 0.f, 0.f};
;     bf16x8 At[4][2], B0[2][2], B1[2][2];
;     const char* cA = (const char*)g.A + cur.ao; const char* cB = (const char*)g.Bt + cur.bo;
;     PG8_STAGE(PG8_SB(0, 0), cB, voffB); PG8_STAGE(PG8_SA(0, 0), cA, voffA); PG8_STAGE(PG8_SB(0, 1), cB + hstepB, voffB); PG8_STAGE(PG8_SA(0, 1), cA + hstepA, voffA);
;     if (wr == 1) PG8_BAR;
;     PG8_WAIT_V(4); PG8_BAR;
.LBB0_538:
	s_andn2_b64 vcc, exec, s[0:1]
	s_cbranch_vccnz .LBB0_624
	v_bfe_i32 v3, v16, 27, 1
	v_lshlrev_b32_e32 v2, 4, v16
	v_lshrrev_b32_e32 v3, 22, v3
	v_add_u32_e32 v3, v2, v3
	v_and_b32_e32 v3, 0xfffffc00, v3
	v_ashrrev_i32_e32 v0, 31, v16
	v_sub_u32_e32 v3, v2, v3
	v_lshrrev_b32_e32 v0, 26, v0
	v_lshrrev_b32_e32 v4, 4, v3
	v_add_u32_e32 v0, v16, v0
	v_bitop3_b32 v4, v4, v3, 32 bitop3:0x6c
	v_ashrrev_i32_e32 v3, 31, v3
	v_ashrrev_i32_e32 v0, 6, v0
	v_lshrrev_b32_e32 v3, 26, v3
	v_lshlrev_b32_e32 v5, 3, v0
	v_add_u32_e32 v3, v4, v3
	v_and_b32_e32 v5, -16, v5
	v_ashrrev_i32_e32 v3, 6, v3
	v_lshlrev_b32_e32 v0, 5, v0
	v_add_u32_e32 v5, v3, v5
	v_and_b32_e32 v14, 32, v0
	v_mul_i32_i24_e32 v0, 64, v3
	v_sub_u32_e32 v0, v4, v0
	v_mov_b32_e32 v7, 1
	v_lshlrev_b32_e32 v4, 1, v5
	v_lshrrev_b32_e32 v6, 2, v5
	v_and_b32_e32 v3, 3, v3
	s_mov_b32 s1, 0x7fffffe0
	v_ashrrev_i16_sdwa v0, v7, sext(v0) dst_sel:DWORD dst_unused:UNUSED_PAD src0_sel:DWORD src1_sel:BYTE_0
	v_and_b32_e32 v4, 24, v4
	v_and_b32_e32 v6, 4, v6
	v_and_or_b32 v3, v5, s1, v3
	v_bfe_i32 v15, v0, 0, 16
	v_or3_b32 v3, v3, v6, v4
	v_add_u32_e32 v0, v14, v15
	v_mul_lo_u32 v17, v5, s82
	v_mul_lo_u32 v3, v3, s66
	v_add_u32_e32 v2, 0x2000, v2
	v_add_lshl_u32 v130, v0, v17, 1
	v_add_lshl_u32 v0, v3, v0, 1
	v_ashrrev_i32_e32 v3, 31, v2
	v_lshrrev_b32_e32 v3, 22, v3
	v_add_u32_e32 v3, v2, v3
	v_ashrrev_i32_e32 v3, 10, v3
	v_mul_i32_i24_e32 v4, 0x400, v3
	v_sub_u32_e32 v2, v2, v4
	v_lshrrev_b32_e32 v4, 4, v2
	v_bitop3_b32 v2, v4, v2, 32 bitop3:0x6c
	v_writelane_b32 v254, s84, 49
	v_ashrrev_i32_e32 v5, 31, v2
	v_lshrrev_b32_e32 v5, 26, v5
	v_writelane_b32 v254, s85, 50
	v_writelane_b32 v254, s57, 37
	v_lshlrev_b32_e32 v4, 3, v3
	v_add_u32_e32 v5, v2, v5
	v_writelane_b32 v254, s90, 39
	v_and_b32_e32 v4, -16, v4
	v_ashrrev_i32_e32 v6, 6, v5
	v_lshlrev_b32_e32 v3, 5, v3
	v_writelane_b32 v254, s91, 40
	v_add_u32_e32 v4, v6, v4
	v_and_b32_e32 v18, 32, v3
	v_and_b32_e32 v3, 0xc0, v5
	v_sub_u32_e32 v2, v2, v3
	v_lshlrev_b32_e32 v3, 1, v4
	v_lshrrev_b32_e32 v5, 2, v4
	v_and_b32_e32 v6, 3, v6
	v_writelane_b32 v254, s38, 35
	v_and_b32_e32 v3, 24, v3
	v_and_b32_e32 v5, 4, v5
	v_and_or_b32 v6, v4, s1, v6
	v_mul_lo_u32 v20, v4, s82
	v_writelane_b32 v254, s82, 43
	s_ashr_i32 s0, s38, 6
	v_or3_b32 v3, v6, v5, v3
	v_writelane_b32 v254, s83, 44
	v_mul_lo_u32 v3, v3, s66
	s_ashr_i32 s1, s38, 8
	s_lshl_b64 s[36:37], s[82:83], 8
	v_writelane_b32 v254, s66, 45
	s_lshl_b64 s[76:77], s[66:67], 8
	s_lshl_b32 s3, s0, 10
	s_add_u32 s6, s10, s6
	v_ashrrev_i16_sdwa v2, v7, sext(v2) dst_sel:DWORD dst_unused:UNUSED_PAD src0_sel:DWORD src1_sel:BYTE_0
	s_addc_u32 s7, s11, s7
	s_add_i32 s33, s3, 0
	v_bfe_i32 v19, v2, 0, 16
	v_writelane_b32 v254, s67, 46
	s_add_i32 m0, s33, 0x10000
	v_add_u32_e32 v2, v18, v19
	global_load_lds_dwordx4 v0, s[6:7]
	s_add_i32 m0, s33, 0x12000
	v_readlane_b32 s8, v254, 11
	v_add_lshl_u32 v134, v3, v2, 1
	v_readlane_b32 s9, v254, 12
	s_add_u32 s4, s8, s4
	global_load_lds_dwordx4 v134, s[6:7]
	s_addc_u32 s5, s9, s5
	s_mov_b32 m0, s33
	s_add_i32 s38, s33, 0x2000
	v_add_lshl_u32 v132, v2, v20, 1
	global_load_lds_dwordx4 v130, s[4:5]
	s_mov_b32 m0, s38
	s_add_u32 s14, s6, s76
	global_load_lds_dwordx4 v132, s[4:5]
	s_addc_u32 s15, s7, s77
	s_add_i32 m0, s33, 0x14000
	v_mov_b32_e32 v135, v1
	global_load_lds_dwordx4 v0, s[14:15]
	s_add_i32 m0, s33, 0x16000
	v_lshl_add_u64 v[10:11], s[14:15], 0, v[0:1]
	v_lshl_add_u64 v[12:13], s[14:15], 0, v[134:135]
	global_load_lds_dwordx4 v134, s[14:15]
	s_add_u32 s14, s4, s36
	s_addc_u32 s15, s5, s37
	s_add_i32 s39, s33, 0x4000
	s_mov_b32 m0, s39
	s_add_i32 s40, s33, 0x6000
	global_load_lds_dwordx4 v130, s[14:15]
	s_mov_b32 m0, s40
	v_mov_b32_e32 v131, v1
	global_load_lds_dwordx4 v132, s[14:15]
	v_mov_b32_e32 v133, v1
	s_mov_b32 s2, s48
	v_lshl_add_u64 v[2:3], s[6:7], 0, v[0:1]
	v_lshl_add_u64 v[4:5], s[6:7], 0, v[134:135]
	v_lshl_add_u64 v[6:7], s[4:5], 0, v[130:131]
	v_lshl_add_u64 v[8:9], s[4:5], 0, v[132:133]
	s_cmp_lg_u32 s1, 1
	s_cbranch_scc1 .LBB0_541
.LBB0_541:
	s_add_i32 m0, s33, 0x18000
	v_lshl_add_u64 v[2:3], v[2:3], 0, s[60:61]
	s_waitcnt vmcnt(0)
	s_barrier
	global_load_lds_dwordx4 v[2:3], off
	v_lshl_add_u64 v[2:3], v[4:5], 0, s[60:61]
	s_add_i32 m0, s33, 0x1a000
	s_add_i32 s41, s33, 0x8000
	global_load_lds_dwordx4 v[2:3], off
	v_lshl_add_u64 v[2:3], v[6:7], 0, s[60:61]
	s_mov_b32 m0, s41
	s_add_i32 s42, s33, 0xa000
	global_load_lds_dwordx4 v[2:3], off
	v_lshl_add_u64 v[2:3], v[8:9], 0, s[60:61]
	s_mov_b32 m0, s42
	v_lshrrev_b32_e32 v21, 1, v16
	global_load_lds_dwordx4 v[2:3], off
	s_add_i32 m0, s33, 0x1c000
	v_lshl_add_u64 v[2:3], v[10:11], 0, s[60:61]
	global_load_lds_dwordx4 v[2:3], off
	v_lshl_add_u64 v[2:3], v[12:13], 0, s[60:61]
	s_add_i32 m0, s33, 0x1e000
	v_and_b32_e32 v21, 24, v21
	global_load_lds_dwordx4 v[2:3], off
	v_and_b32_e32 v154, 15, v16
	s_lshl_b32 s8, s1, 6
	v_lshlrev_b32_e32 v22, 1, v21
	v_lshlrev_b32_e32 v16, 2, v16
	s_lshl_b32 s0, s0, 5
	v_and_b32_e32 v2, 63, v219
	v_or_b32_e32 v155, s8, v154
	v_lshl_or_b32 v22, v154, 6, v22
	s_lshl_b32 s1, s1, 13
	v_and_b32_e32 v16, 32, v16
	s_and_b32 s0, s0, 0x60
	v_or_b32_e32 v157, s8, v2
	v_readlane_b32 s8, v253, 61
	v_bitop3_b32 v23, v22, s1, v16 bitop3:0xde
	s_lshl_b32 s1, s0, 7
	s_add_i32 s43, s73, -2
	v_readlane_b32 s9, v253, 62
	s_cmp_eq_u64 s[8:9], 0
	v_bitop3_b32 v156, v22, s1, v16 bitop3:0xde
	s_cselect_b64 s[78:79], -1, 0
	s_cmp_lg_u64 s[8:9], 0
	v_readlane_b32 s1, v254, 13
	s_cselect_b64 s[80:81], -1, 0
	s_ashr_i32 s48, s1, 31
	s_lshr_b32 s1, s54, 3
	v_writelane_b32 v254, s1, 33
	s_add_i32 s1, s1, 1
	v_readlane_b32 s8, v253, 30
	v_writelane_b32 v254, s1, 31
	v_or_b32_e32 v158, s0, v21
	v_readlane_b32 s1, v254, 5
	v_readlane_b32 s8, v254, 37
	s_mul_i32 s24, s1, s8
	v_cvt_f32_u32_e32 v2, s24
	s_sub_i32 s0, 0, s24
	v_mov_b32_e32 v3, v1
	s_waitcnt vmcnt(6)
	v_rcp_iflag_f32_e32 v2, v2
	v_readlane_b32 s9, v253, 31
	s_mov_b32 s27, s9
	s_and_b32 s52, s54, 7
	v_mul_f32_e32 v2, 0x4f7ffffe, v2
	v_cvt_u32_f32_e32 v2, v2
	s_mov_b32 s56, 0
	v_add_u32_e32 v159, 0, v23
	s_barrier
	v_readfirstlane_b32 s1, v2
	v_cvt_f32_u32_e32 v2, s25
	s_mul_i32 s0, s0, s1
	s_mul_hi_u32 s0, s1, s0
	s_add_i32 s58, s1, s0
	v_rcp_iflag_f32_e32 v2, v2
	s_sub_i32 s0, 0, s25
	v_mul_f32_e32 v2, 0x4f7ffffe, v2
	v_cvt_u32_f32_e32 v2, v2
	s_nop 0
	v_readfirstlane_b32 s1, v2
	v_add_u32_e32 v2, v17, v14
	v_add_lshl_u32 v2, v2, v15, 1
	s_mul_i32 s0, s0, s1
	v_lshl_add_u64 v[136:137], s[36:37], 0, v[2:3]
	v_add_u32_e32 v2, v20, v18
	s_mul_hi_u32 s0, s1, s0
	v_add_lshl_u32 v2, v2, v19, 1
	s_add_i32 s64, s1, s0
	v_lshl_add_u64 v[138:139], s[36:37], 0, v[2:3]
	s_branch .LBB0_543

; #define PG8_STAGE(bufoff, gbase, voff) do { _Pragma("unroll") for (int _i = 0; _i < 2; ++_i) \
;         __builtin_amdgcn_global_load_lds((const unsigned*)((const char*)(gbase) + (voff)[_i]), (LAS unsigned*)(lds + (bufoff) + ldsw + _i * 8192), 16, 0, 0); } while (0)
; #define PG8_LDA(dst, b, h) do { _Pragma("unroll") for (int m = 0; m < 4; ++m) _Pragma("unroll") for (int k = 0; k < 2; ++k) dst[m][k] = *(const LAS bf16x8*)(lds + PG8_SA(b, h) + aoff + m * 2048 + k * 1024); } while (0)
; #define PG8_LDB(dst, b, h) do { _Pragma("unroll") for (int n = 0; n < 2; ++n) _Pragma("unroll") for (int k = 0; k < 2; ++k) dst[n][k] = *(const LAS bf16x8*)(lds + PG8_SB(b, h) + boff + n * 2048 + k * 1024); } while (0)
; #define PG8_MMA(ai, bj, At, Bt) do { __builtin_amdgcn_s_setprio(1); _Pragma("unroll") for (int m = 0; m < 4; ++m) _Pragma("unroll") for (int n = 0; n < 2; ++n) _Pragma("unroll") for (int k = 0; k < 2; ++k) \
;         acc[ai][bj][m][n] = __builtin_amdgcn_mfma_f32_16x16x32_bf16(Bt[n][k], At[m][k], acc[ai][bj][m][n], 0, 0, 0); __builtin_amdgcn_s_setprio(0); } while (0)
; #define PG8_WAIT_L(n) asm volatile("s_waitcnt lgkmcnt(" #n ")" ::: "memory")
; #define PG8_BAR __builtin_amdgcn_s_barrier()
; #define PG8_SCHED __builtin_amdgcn_sched_barrier(0)
; template <class Epi>
; __device__ __forceinline__ void gemm_phase(LAS unsigned char* lds, const Gemm g, const Sched& S, const Epi& E) {
;     ...
;         const bool has_next = S.next(ui + 1, nxt);
;         const char* nA = has_next ? (const char*)g.A + nxt.ao : cA; const char* nB = has_next ? (const char*)g.Bt + nxt.bo : cB;
;         for (int t = 0; t < nt; t += 2) {
;             const bool last = (t == nt - 2);
;             const char* a1 = cA + (size_t)(t + 1) * kstep;
;             const char* a2 = last ? nA : cA + (size_t)(t + 2) * kstep; const char* b2 = last ? nB : cB + (size_t)(t + 2) * kstep;
;             const char* a3 = a2 + kstep; const char* b3 = b2 + kstep;
;             PG8_LDB(B0, 0, 0); PG8_SCHED; PG8_LDA(At, 0, 0); PG8_STAGE(PG8_SA(1, 1), a1 + hstepA, voffA);
;             PG8_WAIT_L(8); PG8_BAR; PG8_WAIT_L(0); PG8_MMA(0, 0, At, B0); PG8_BAR; PG8_SCHED;
;     ...
;                     for (int n = 0; n < 2; ++n) acc[a][b][m][n] = (f32x4){0.f, 0.f, 0.f, 0.f};
.LBB0_554:
	v_mov_b64_e32 v[2:3], s[26:27]
	v_readlane_b32 s8, v254, 11
	v_cmp_lt_i64_e32 vcc, s[86:87], v[2:3]
	v_readlane_b32 s9, v254, 12
	s_add_u32 s86, s8, s82
	s_addc_u32 s87, s9, s83
	s_and_b64 s[14:15], vcc, exec
	s_cselect_b32 s55, s87, s5
	s_cselect_b32 s57, s86, s4
	s_add_u32 s88, s10, s84
	s_addc_u32 s89, s11, s85
	s_and_b64 s[14:15], vcc, exec
	s_cselect_b32 s59, s89, s7
	s_cselect_b32 s95, s88, s6
	s_add_u32 s4, s4, 0x80
	s_addc_u32 s5, s5, 0
	s_add_u32 s34, s6, 0x100
	v_mov_b32_e32 v2, 0
	s_addc_u32 s35, s7, 0
	s_mov_b32 s6, 0
	v_mov_b32_e32 v3, v2
	v_mov_b32_e32 v4, v2
	v_mov_b32_e32 v5, v2
	v_mov_b32_e32 v6, v2
	v_mov_b32_e32 v7, v2
	v_mov_b32_e32 v8, v2
	v_mov_b32_e32 v9, v2
	v_mov_b32_e32 v18, v2
	v_mov_b32_e32 v19, v2
	v_mov_b32_e32 v20, v2
	v_mov_b32_e32 v21, v2
	v_mov_b32_e32 v22, v2
	v_mov_b32_e32 v23, v2
	v_mov_b32_e32 v24, v2
	v_mov_b32_e32 v25, v2
	v_mov_b32_e32 v34, v2
	v_mov_b32_e32 v35, v2
	v_mov_b32_e32 v36, v2
	v_mov_b32_e32 v37, v2
	v_mov_b32_e32 v38, v2
	v_mov_b32_e32 v39, v2
	v_mov_b32_e32 v40, v2
	v_mov_b32_e32 v41, v2
	v_mov_b32_e32 v50, v2
	v_mov_b32_e32 v51, v2
	v_mov_b32_e32 v52, v2
	v_mov_b32_e32 v53, v2
	v_mov_b32_e32 v54, v2
	v_mov_b32_e32 v55, v2
	v_mov_b32_e32 v56, v2
	v_mov_b32_e32 v57, v2
	v_mov_b32_e32 v10, v2
	v_mov_b32_e32 v11, v2
	v_mov_b32_e32 v12, v2
	v_mov_b32_e32 v13, v2
	v_mov_b32_e32 v14, v2
	v_mov_b32_e32 v15, v2
	v_mov_b32_e32 v16, v2
	v_mov_b32_e32 v17, v2
	v_mov_b32_e32 v26, v2
	v_mov_b32_e32 v27, v2
	v_mov_b32_e32 v28, v2
	v_mov_b32_e32 v29, v2
	v_mov_b32_e32 v30, v2
	v_mov_b32_e32 v31, v2
	v_mov_b32_e32 v32, v2
	v_mov_b32_e32 v33, v2
	v_mov_b32_e32 v42, v2
	v_mov_b32_e32 v43, v2
	v_mov_b32_e32 v44, v2
	v_mov_b32_e32 v45, v2
	v_mov_b32_e32 v46, v2
	s_waitcnt lgkmcnt(0)
	v_mov_b32_e32 v47, v2
	v_mov_b32_e32 v48, v2
	v_mov_b32_e32 v49, v2
	v_mov_b32_e32 v58, v2
	v_mov_b32_e32 v59, v2
	v_mov_b32_e32 v60, v2
	v_mov_b32_e32 v61, v2
	v_mov_b32_e32 v62, v2
	v_mov_b32_e32 v63, v2
	v_mov_b32_e32 v64, v2
	v_mov_b32_e32 v65, v2
	v_mov_b32_e32 v66, v2
	v_mov_b32_e32 v67, v2
	v_mov_b32_e32 v68, v2
	v_mov_b32_e32 v69, v2
	v_mov_b32_e32 v70, v2
	v_mov_b32_e32 v71, v2
	v_mov_b32_e32 v72, v2
	v_mov_b32_e32 v73, v2
	v_mov_b32_e32 v82, v2
	v_mov_b32_e32 v83, v2
	v_mov_b32_e32 v84, v2
	v_mov_b32_e32 v85, v2
	v_mov_b32_e32 v86, v2
	v_mov_b32_e32 v87, v2
	v_mov_b32_e32 v88, v2
	v_mov_b32_e32 v89, v2
	v_mov_b32_e32 v98, v2
	v_mov_b32_e32 v99, v2
	v_mov_b32_e32 v100, v2
	v_mov_b32_e32 v101, v2
	v_mov_b32_e32 v102, v2
	v_mov_b32_e32 v103, v2
	v_mov_b32_e32 v104, v2
	v_mov_b32_e32 v105, v2
	v_mov_b32_e32 v114, v2
	v_mov_b32_e32 v115, v2
	v_mov_b32_e32 v116, v2
	v_mov_b32_e32 v117, v2
	v_mov_b32_e32 v118, v2
	v_mov_b32_e32 v119, v2
	v_mov_b32_e32 v120, v2
	v_mov_b32_e32 v121, v2
	v_mov_b32_e32 v74, v2
	v_mov_b32_e32 v75, v2
	v_mov_b32_e32 v76, v2
	v_mov_b32_e32 v77, v2
	v_mov_b32_e32 v78, v2
	v_mov_b32_e32 v79, v2
	v_mov_b32_e32 v80, v2
	v_mov_b32_e32 v81, v2
	v_mov_b32_e32 v90, v2
	v_mov_b32_e32 v91, v2
	v_mov_b32_e32 v92, v2
	v_mov_b32_e32 v93, v2
	v_mov_b32_e32 v94, v2
	v_mov_b32_e32 v95, v2
	v_mov_b32_e32 v96, v2
	v_mov_b32_e32 v97, v2
	v_mov_b32_e32 v106, v2
	v_mov_b32_e32 v107, v2
	v_mov_b32_e32 v108, v2
	v_mov_b32_e32 v109, v2
	v_mov_b32_e32 v110, v2
	v_mov_b32_e32 v111, v2
	v_mov_b32_e32 v112, v2
	v_mov_b32_e32 v113, v2
	v_mov_b32_e32 v122, v2
	v_mov_b32_e32 v123, v2
	v_mov_b32_e32 v124, v2
	v_mov_b32_e32 v125, v2
	v_mov_b32_e32 v126, v2
	v_mov_b32_e32 v127, v2
	v_mov_b32_e32 v128, v2
	v_mov_b32_e32 v129, v2
	v_readfirstlane_b32 s98, v219
	s_nop 1
	s_bitcmp1_b32 s98, 8
	s_cbranch_scc0 .Lresync_y_555
	s_barrier
.Lresync_y_555:
.LBB0_555:
	s_add_i32 s14, s6, 2
	s_add_u32 s8, s4, 0x80
	s_addc_u32 s7, s5, 0
	s_add_i32 s9, 0, 0x10000
	v_add_u32_e32 v160, s9, v156
	ds_read_b128 v[142:145], v160
	ds_read_b128 v[146:149], v160 offset:1024
	ds_read_b128 v[150:153], v160 offset:2048
	ds_read_b128 v[160:163], v160 offset:3072
	s_cmp_eq_u32 s43, s6
	s_cselect_b32 s6, s57, s8
	s_cselect_b32 s7, s55, s7
	s_cselect_b32 s91, s59, s35
	s_cselect_b32 s90, s95, s34
	v_lshl_add_u64 v[192:193], s[4:5], 0, v[136:137]
	s_add_i32 m0, s33, 0xc000
	ds_read_b128 v[164:167], v159
	ds_read_b128 v[168:171], v159 offset:1024
	ds_read_b128 v[172:175], v159 offset:2048
	ds_read_b128 v[176:179], v159 offset:3072
	ds_read_b128 v[180:183], v159 offset:4096
	ds_read_b128 v[184:187], v159 offset:5120
	ds_read_b128 v[188:191], v159 offset:6144
	ds_read_b128 v[196:199], v159 offset:7168
	global_load_lds_dwordx4 v[192:193], off
	v_lshl_add_u64 v[192:193], s[4:5], 0, v[138:139]
	s_add_i32 m0, s33, 0xe000
	s_nop 0
	global_load_lds_dwordx4 v[192:193], off
	s_add_i32 s8, 0, 0x14000
	v_add_u32_e32 v192, s8, v156
	ds_read_b128 v[200:203], v192
	ds_read_b128 v[204:207], v192 offset:1024
	ds_read_b128 v[208:211], v192 offset:2048
	ds_read_b128 v[212:215], v192 offset:3072
	s_waitcnt vmcnt(8)
	s_waitcnt lgkmcnt(0)
	v_mfma_f32_16x16x32_bf16 v[126:129], v[142:145], v[164:167], v[126:129]
	v_mfma_f32_16x16x32_bf16 v[122:125], v[150:153], v[164:167], v[122:125]
	v_mfma_f32_16x16x32_bf16 v[110:113], v[142:145], v[172:175], v[110:113]
	v_mfma_f32_16x16x32_bf16 v[106:109], v[150:153], v[172:175], v[106:109]
	s_barrier
; #define PG8_STAGE(bufoff, gbase, voff) do { _Pragma("unroll") for (int _i = 0; _i < 2; ++_i) \
;         __builtin_amdgcn_global_load_lds((const unsigned*)((const char*)(gbase) + (voff)[_i]), (LAS unsigned*)(lds + (bufoff) + ldsw + _i * 8192), 16, 0, 0); } while (0)
; #define PG8_LDA(dst, b, h) do { _Pragma("unroll") for (int m = 0; m < 4; ++m) _Pragma("unroll") for (int k = 0; k < 2; ++k) dst[m][k] = *(const LAS bf16x8*)(lds + PG8_SA(b, h) + aoff + m * 2048 + k * 1024); } while (0)
; #define PG8_LDB(dst, b, h) do { _Pragma("unroll") for (int n = 0; n < 2; ++n) _Pragma("unroll") for (int k = 0; k < 2; ++k) dst[n][k] = *(const LAS bf16x8*)(lds + PG8_SB(b, h) + boff + n * 2048 + k * 1024); } while (0)
; #define PG8_MMA(ai, bj, At, Bt) do { __builtin_amdgcn_s_setprio(1); _Pragma("unroll") for (int m = 0; m < 4; ++m) _Pragma("unroll") for (int n = 0; n < 2; ++n) _Pragma("unroll") for (int k = 0; k < 2; ++k) \
;         acc[ai][bj][m][n] = __builtin_amdgcn_mfma_f32_16x16x32_bf16(Bt[n][k], At[m][k], acc[ai][bj][m][n], 0, 0, 0); __builtin_amdgcn_s_setprio(0); } while (0)
; #define PG8_WAIT_V(n) asm volatile("s_waitcnt vmcnt(" #n ")" ::: "memory")
; #define PG8_WAIT_L(n) asm volatile("s_waitcnt lgkmcnt(" #n ")" ::: "memory")
; #define PG8_BAR __builtin_amdgcn_s_barrier()
; #define PG8_SCHED __builtin_amdgcn_sched_barrier(0)
; template <class Epi>
; __device__ __forceinline__ void gemm_phase(LAS unsigned char* lds, const Gemm g, const Sched& S, const Epi& E) {
;     ...
;             PG8_LDB(B0, 0, 0); PG8_SCHED; PG8_LDA(At, 0, 0); PG8_STAGE(PG8_SA(1, 1), a1 + hstepA, voffA);
;             PG8_WAIT_L(8); PG8_BAR; PG8_WAIT_L(0); PG8_MMA(0, 0, At, B0); PG8_BAR; PG8_SCHED;
;             PG8_LDB(B1, 0, 1); PG8_STAGE(PG8_SB(0, 0), b2, voffB);
;             PG8_BAR; PG8_WAIT_L(0); PG8_MMA(0, 1, At, B1); PG8_BAR;
;             PG8_LDA(At, 0, 1); PG8_STAGE(PG8_SA(0, 0), a2, voffA);
;             PG8_BAR; PG8_WAIT_L(0); PG8_MMA(1, 0, At, B0); PG8_BAR; PG8_SCHED;
;             PG8_STAGE(PG8_SB(0, 1), b2 + hstepB, voffB);
;             PG8_WAIT_V(6); PG8_BAR; PG8_MMA(1, 1, At, B1); PG8_BAR;
	s_setprio 1
	v_mfma_f32_16x16x32_bf16 v[94:97], v[142:145], v[180:183], v[94:97]
	v_mfma_f32_16x16x32_bf16 v[90:93], v[150:153], v[180:183], v[90:93]
	v_mfma_f32_16x16x32_bf16 v[78:81], v[142:145], v[188:191], v[78:81]
	v_mfma_f32_16x16x32_bf16 v[74:77], v[150:153], v[188:191], v[74:77]
	v_mfma_f32_16x16x32_bf16 v[126:129], v[146:149], v[168:171], v[126:129]
	v_mfma_f32_16x16x32_bf16 v[122:125], v[160:163], v[168:171], v[122:125]
	v_mfma_f32_16x16x32_bf16 v[110:113], v[146:149], v[176:179], v[110:113]
	v_mfma_f32_16x16x32_bf16 v[106:109], v[160:163], v[176:179], v[106:109]
	v_mfma_f32_16x16x32_bf16 v[94:97], v[146:149], v[184:187], v[94:97]
	v_mfma_f32_16x16x32_bf16 v[90:93], v[160:163], v[184:187], v[90:93]
	v_mfma_f32_16x16x32_bf16 v[78:81], v[146:149], v[196:199], v[78:81]
	v_mfma_f32_16x16x32_bf16 v[74:77], v[160:163], v[196:199], v[74:77]
	v_mfma_f32_16x16x32_bf16 v[118:121], v[200:203], v[164:167], v[118:121]
	v_mfma_f32_16x16x32_bf16 v[114:117], v[208:211], v[164:167], v[114:117]
	v_mfma_f32_16x16x32_bf16 v[102:105], v[200:203], v[172:175], v[102:105]
	v_mfma_f32_16x16x32_bf16 v[98:101], v[208:211], v[172:175], v[98:101]
	v_mfma_f32_16x16x32_bf16 v[86:89], v[200:203], v[180:183], v[86:89]
	v_mfma_f32_16x16x32_bf16 v[82:85], v[208:211], v[180:183], v[82:85]
	v_mfma_f32_16x16x32_bf16 v[70:73], v[200:203], v[188:191], v[70:73]
	v_mfma_f32_16x16x32_bf16 v[66:69], v[208:211], v[188:191], v[66:69]
	v_mfma_f32_16x16x32_bf16 v[118:121], v[204:207], v[168:171], v[118:121]
	v_mfma_f32_16x16x32_bf16 v[114:117], v[212:215], v[168:171], v[114:117]
	v_mfma_f32_16x16x32_bf16 v[102:105], v[204:207], v[176:179], v[102:105]
	v_mfma_f32_16x16x32_bf16 v[98:101], v[212:215], v[176:179], v[98:101]
	v_mfma_f32_16x16x32_bf16 v[86:89], v[204:207], v[184:187], v[86:89]
	v_mfma_f32_16x16x32_bf16 v[82:85], v[212:215], v[184:187], v[82:85]
	v_mfma_f32_16x16x32_bf16 v[70:73], v[204:207], v[196:199], v[70:73]
	v_mfma_f32_16x16x32_bf16 v[66:69], v[212:215], v[196:199], v[66:69]
	s_setprio 0
	s_barrier
	s_add_i32 s9, s9, s3
	v_lshl_add_u64 v[192:193], s[90:91], 0, v[0:1]
	s_mov_b32 m0, s9
	v_lshl_add_u64 v[194:195], s[90:91], 0, v[134:135]
	global_load_lds_dwordx4 v[192:193], off
	s_add_i32 m0, s9, 0x2000
	s_nop 0
	global_load_lds_dwordx4 v[194:195], off
	s_mov_b32 m0, s33
	v_lshl_add_u64 v[216:217], s[6:7], 0, v[130:131]
	ds_read_b128 v[164:167], v159 offset:16384
	ds_read_b128 v[168:171], v159 offset:17408
	ds_read_b128 v[172:175], v159 offset:18432
	ds_read_b128 v[176:179], v159 offset:19456
	ds_read_b128 v[180:183], v159 offset:20480
	ds_read_b128 v[184:187], v159 offset:21504
	ds_read_b128 v[188:191], v159 offset:22528
	ds_read_b128 v[196:199], v159 offset:23552
	global_load_lds_dwordx4 v[216:217], off
	v_lshl_add_u64 v[222:223], s[6:7], 0, v[132:133]
	s_mov_b32 m0, s38
	s_nop 0
	global_load_lds_dwordx4 v[222:223], off
	s_add_u32 s90, s90, s76
	s_addc_u32 s91, s91, s77
	s_add_i32 s8, s8, s3
	v_lshl_add_u64 v[224:225], s[90:91], 0, v[0:1]
	s_mov_b32 m0, s8
	v_lshl_add_u64 v[226:227], s[90:91], 0, v[134:135]
	global_load_lds_dwordx4 v[224:225], off
	s_add_i32 m0, s8, 0x2000
	s_nop 0
	global_load_lds_dwordx4 v[226:227], off
	s_waitcnt vmcnt(8)
	s_waitcnt lgkmcnt(0)
	v_mfma_f32_16x16x32_bf16 v[62:65], v[142:145], v[164:167], v[62:65]
	v_mfma_f32_16x16x32_bf16 v[58:61], v[150:153], v[164:167], v[58:61]
	v_mfma_f32_16x16x32_bf16 v[46:49], v[142:145], v[172:175], v[46:49]
	v_mfma_f32_16x16x32_bf16 v[42:45], v[150:153], v[172:175], v[42:45]
	s_barrier
	s_setprio 1
	v_mfma_f32_16x16x32_bf16 v[30:33], v[142:145], v[180:183], v[30:33]
	v_mfma_f32_16x16x32_bf16 v[26:29], v[150:153], v[180:183], v[26:29]
	v_mfma_f32_16x16x32_bf16 v[14:17], v[142:145], v[188:191], v[14:17]
	v_mfma_f32_16x16x32_bf16 v[10:13], v[150:153], v[188:191], v[10:13]
	v_mfma_f32_16x16x32_bf16 v[62:65], v[146:149], v[168:171], v[62:65]
	v_mfma_f32_16x16x32_bf16 v[58:61], v[160:163], v[168:171], v[58:61]
	v_mfma_f32_16x16x32_bf16 v[46:49], v[146:149], v[176:179], v[46:49]
	v_mfma_f32_16x16x32_bf16 v[42:45], v[160:163], v[176:179], v[42:45]
	v_mfma_f32_16x16x32_bf16 v[30:33], v[146:149], v[184:187], v[30:33]
	v_mfma_f32_16x16x32_bf16 v[26:29], v[160:163], v[184:187], v[26:29]
	v_mfma_f32_16x16x32_bf16 v[14:17], v[146:149], v[196:199], v[14:17]
	v_mfma_f32_16x16x32_bf16 v[10:13], v[160:163], v[196:199], v[10:13]
	v_mfma_f32_16x16x32_bf16 v[54:57], v[200:203], v[164:167], v[54:57]
	v_mfma_f32_16x16x32_bf16 v[50:53], v[208:211], v[164:167], v[50:53]
	v_mfma_f32_16x16x32_bf16 v[38:41], v[200:203], v[172:175], v[38:41]
	v_mfma_f32_16x16x32_bf16 v[34:37], v[208:211], v[172:175], v[34:37]
	v_mfma_f32_16x16x32_bf16 v[22:25], v[200:203], v[180:183], v[22:25]
	v_mfma_f32_16x16x32_bf16 v[18:21], v[208:211], v[180:183], v[18:21]
	v_mfma_f32_16x16x32_bf16 v[6:9], v[200:203], v[188:191], v[6:9]
	v_mfma_f32_16x16x32_bf16 v[2:5], v[208:211], v[188:191], v[2:5]
	v_mfma_f32_16x16x32_bf16 v[54:57], v[204:207], v[168:171], v[54:57]
	v_mfma_f32_16x16x32_bf16 v[50:53], v[212:215], v[168:171], v[50:53]
	v_mfma_f32_16x16x32_bf16 v[38:41], v[204:207], v[176:179], v[38:41]
	v_mfma_f32_16x16x32_bf16 v[34:37], v[212:215], v[176:179], v[34:37]
	v_mfma_f32_16x16x32_bf16 v[22:25], v[204:207], v[184:187], v[22:25]
	v_mfma_f32_16x16x32_bf16 v[18:21], v[212:215], v[184:187], v[18:21]
	v_mfma_f32_16x16x32_bf16 v[6:9], v[204:207], v[196:199], v[6:9]
	v_mfma_f32_16x16x32_bf16 v[2:5], v[212:215], v[196:199], v[2:5]
	s_setprio 0
	s_barrier
; #define PG8_STAGE(bufoff, gbase, voff) do { _Pragma("unroll") for (int _i = 0; _i < 2; ++_i) \
;         __builtin_amdgcn_global_load_lds((const unsigned*)((const char*)(gbase) + (voff)[_i]), (LAS unsigned*)(lds + (bufoff) + ldsw + _i * 8192), 16, 0, 0); } while (0)
; #define PG8_LDA(dst, b, h) do { _Pragma("unroll") for (int m = 0; m < 4; ++m) _Pragma("unroll") for (int k = 0; k < 2; ++k) dst[m][k] = *(const LAS bf16x8*)(lds + PG8_SA(b, h) + aoff + m * 2048 + k * 1024); } while (0)
; #define PG8_LDB(dst, b, h) do { _Pragma("unroll") for (int n = 0; n < 2; ++n) _Pragma("unroll") for (int k = 0; k < 2; ++k) dst[n][k] = *(const LAS bf16x8*)(lds + PG8_SB(b, h) + boff + n * 2048 + k * 1024); } while (0)
; #define PG8_MMA(ai, bj, At, Bt) do { __builtin_amdgcn_s_setprio(1); _Pragma("unroll") for (int m = 0; m < 4; ++m) _Pragma("unroll") for (int n = 0; n < 2; ++n) _Pragma("unroll") for (int k = 0; k < 2; ++k) \
;         acc[ai][bj][m][n] = __builtin_amdgcn_mfma_f32_16x16x32_bf16(Bt[n][k], At[m][k], acc[ai][bj][m][n], 0, 0, 0); __builtin_amdgcn_s_setprio(0); } while (0)
; #define PG8_WAIT_V(n) asm volatile("s_waitcnt vmcnt(" #n ")" ::: "memory")
; #define PG8_WAIT_L(n) asm volatile("s_waitcnt lgkmcnt(" #n ")" ::: "memory")
; #define PG8_BAR __builtin_amdgcn_s_barrier()
; #define PG8_SCHED __builtin_amdgcn_sched_barrier(0)
; template <class Epi>
; __device__ __forceinline__ void gemm_phase(LAS unsigned char* lds, const Gemm g, const Sched& S, const Epi& E) {
;     ...
;             PG8_WAIT_V(6); PG8_BAR; PG8_MMA(1, 1, At, B1); PG8_BAR;
;             PG8_LDB(B0, 1, 0); PG8_SCHED; PG8_LDA(At, 1, 0); PG8_STAGE(PG8_SA(0, 1), a2 + hstepA, voffA);
;             PG8_WAIT_L(8); PG8_BAR; PG8_WAIT_L(0); PG8_MMA(0, 0, At, B0); PG8_BAR; PG8_SCHED;
;             PG8_LDB(B1, 1, 1); PG8_STAGE(PG8_SB(1, 0), b3, voffB);
;             PG8_BAR; PG8_WAIT_L(0); PG8_MMA(0, 1, At, B1); PG8_BAR;
;             PG8_LDA(At, 1, 1); PG8_STAGE(PG8_SA(1, 0), a3, voffA);
;             PG8_BAR; PG8_WAIT_L(0); PG8_MMA(1, 0, At, B0); PG8_BAR; PG8_SCHED;
;             PG8_STAGE(PG8_SB(1, 1), b3 + hstepB, voffB);
	s_add_i32 s8, 0, 0x18000
	v_add_u32_e32 v160, s8, v156
	ds_read_b128 v[142:145], v160
	ds_read_b128 v[146:149], v160 offset:1024
	ds_read_b128 v[150:153], v160 offset:2048
	ds_read_b128 v[160:163], v160 offset:3072
	s_add_u32 s6, s6, s36
	s_addc_u32 s7, s7, s37
	s_mov_b32 m0, s39
	v_lshl_add_u64 v[200:201], s[6:7], 0, v[130:131]
	ds_read_b128 v[164:167], v159 offset:32768
	ds_read_b128 v[168:171], v159 offset:33792
	ds_read_b128 v[172:175], v159 offset:34816
	ds_read_b128 v[176:179], v159 offset:35840
	ds_read_b128 v[180:183], v159 offset:36864
	ds_read_b128 v[184:187], v159 offset:37888
	ds_read_b128 v[188:191], v159 offset:38912
	ds_read_b128 v[196:199], v159 offset:39936
	global_load_lds_dwordx4 v[200:201], off
	v_lshl_add_u64 v[200:201], s[6:7], 0, v[132:133]
	s_mov_b32 m0, s40
	s_nop 0
	global_load_lds_dwordx4 v[200:201], off
	s_add_i32 s6, 0, 0x1c000
	v_add_u32_e32 v212, s6, v156
	ds_read_b128 v[200:203], v212
	ds_read_b128 v[204:207], v212 offset:1024
	ds_read_b128 v[208:211], v212 offset:2048
	ds_read_b128 v[212:215], v212 offset:3072
	s_waitcnt vmcnt(8)
	s_waitcnt lgkmcnt(0)
	v_mfma_f32_16x16x32_bf16 v[126:129], v[142:145], v[164:167], v[126:129]
	v_mfma_f32_16x16x32_bf16 v[122:125], v[150:153], v[164:167], v[122:125]
	v_mfma_f32_16x16x32_bf16 v[110:113], v[142:145], v[172:175], v[110:113]
	v_mfma_f32_16x16x32_bf16 v[106:109], v[150:153], v[172:175], v[106:109]
	s_barrier
	s_setprio 1
	v_mfma_f32_16x16x32_bf16 v[94:97], v[142:145], v[180:183], v[94:97]
	v_mfma_f32_16x16x32_bf16 v[90:93], v[150:153], v[180:183], v[90:93]
	v_mfma_f32_16x16x32_bf16 v[78:81], v[142:145], v[188:191], v[78:81]
	v_mfma_f32_16x16x32_bf16 v[74:77], v[150:153], v[188:191], v[74:77]
	v_mfma_f32_16x16x32_bf16 v[126:129], v[146:149], v[168:171], v[126:129]
	v_mfma_f32_16x16x32_bf16 v[122:125], v[160:163], v[168:171], v[122:125]
	v_mfma_f32_16x16x32_bf16 v[110:113], v[146:149], v[176:179], v[110:113]
	v_mfma_f32_16x16x32_bf16 v[106:109], v[160:163], v[176:179], v[106:109]
	v_mfma_f32_16x16x32_bf16 v[94:97], v[146:149], v[184:187], v[94:97]
	v_mfma_f32_16x16x32_bf16 v[90:93], v[160:163], v[184:187], v[90:93]
	v_mfma_f32_16x16x32_bf16 v[78:81], v[146:149], v[196:199], v[78:81]
	v_mfma_f32_16x16x32_bf16 v[74:77], v[160:163], v[196:199], v[74:77]
	v_mfma_f32_16x16x32_bf16 v[118:121], v[200:203], v[164:167], v[118:121]
	v_mfma_f32_16x16x32_bf16 v[114:117], v[208:211], v[164:167], v[114:117]
	v_mfma_f32_16x16x32_bf16 v[102:105], v[200:203], v[172:175], v[102:105]
	v_mfma_f32_16x16x32_bf16 v[98:101], v[208:211], v[172:175], v[98:101]
	v_mfma_f32_16x16x32_bf16 v[86:89], v[200:203], v[180:183], v[86:89]
	v_mfma_f32_16x16x32_bf16 v[82:85], v[208:211], v[180:183], v[82:85]
	v_mfma_f32_16x16x32_bf16 v[70:73], v[200:203], v[188:191], v[70:73]
	v_mfma_f32_16x16x32_bf16 v[66:69], v[208:211], v[188:191], v[66:69]
	v_mfma_f32_16x16x32_bf16 v[118:121], v[204:207], v[168:171], v[118:121]
	v_mfma_f32_16x16x32_bf16 v[114:117], v[212:215], v[168:171], v[114:117]
	v_mfma_f32_16x16x32_bf16 v[102:105], v[204:207], v[176:179], v[102:105]
	v_mfma_f32_16x16x32_bf16 v[98:101], v[212:215], v[176:179], v[98:101]
	v_mfma_f32_16x16x32_bf16 v[86:89], v[204:207], v[184:187], v[86:89]
	v_mfma_f32_16x16x32_bf16 v[82:85], v[212:215], v[184:187], v[82:85]
	v_mfma_f32_16x16x32_bf16 v[70:73], v[204:207], v[196:199], v[70:73]
	v_mfma_f32_16x16x32_bf16 v[66:69], v[212:215], v[196:199], v[66:69]
	s_setprio 0
	s_barrier
	s_add_i32 s7, s8, s3
	v_lshl_add_u64 v[192:193], v[192:193], 0, s[60:61]
	s_mov_b32 m0, s7
	s_nop 0
	global_load_lds_dwordx4 v[192:193], off
	v_lshl_add_u64 v[192:193], v[194:195], 0, s[60:61]
	s_add_i32 m0, s7, 0x2000
	s_nop 0
	global_load_lds_dwordx4 v[192:193], off
	s_mov_b32 m0, s41
	v_lshl_add_u64 v[192:193], v[216:217], 0, s[60:61]
	ds_read_b128 v[164:167], v159 offset:49152
	ds_read_b128 v[168:171], v159 offset:50176
	ds_read_b128 v[172:175], v159 offset:51200
	ds_read_b128 v[176:179], v159 offset:52224
	ds_read_b128 v[180:183], v159 offset:53248
	ds_read_b128 v[184:187], v159 offset:54272
	ds_read_b128 v[188:191], v159 offset:55296
	ds_read_b128 v[196:199], v159 offset:56320
	global_load_lds_dwordx4 v[192:193], off
	v_lshl_add_u64 v[192:193], v[222:223], 0, s[60:61]
	s_mov_b32 m0, s42
	s_nop 0
	global_load_lds_dwordx4 v[192:193], off
	s_add_i32 s6, s6, s3
	v_lshl_add_u64 v[192:193], v[224:225], 0, s[60:61]
	s_mov_b32 m0, s6
	s_nop 0
	global_load_lds_dwordx4 v[192:193], off
	v_lshl_add_u64 v[192:193], v[226:227], 0, s[60:61]
	s_add_i32 m0, s6, 0x2000
	s_nop 0
	global_load_lds_dwordx4 v[192:193], off
	s_waitcnt vmcnt(8)
	s_waitcnt lgkmcnt(0)
	v_mfma_f32_16x16x32_bf16 v[62:65], v[142:145], v[164:167], v[62:65]
	v_mfma_f32_16x16x32_bf16 v[58:61], v[150:153], v[164:167], v[58:61]
	v_mfma_f32_16x16x32_bf16 v[46:49], v[142:145], v[172:175], v[46:49]
	v_mfma_f32_16x16x32_bf16 v[42:45], v[150:153], v[172:175], v[42:45]
	s_barrier
; __device__ __forceinline__ float pre_get(const Pre& p, int ai, int m, int fr) { return __shfl(p.v[ai], m * 16 + fr); }
; __device__ __forceinline__ float rstd_pre(const float* ss, float v) { return ss ? rsqrtf(v * (1.0f / 2048.0f) + 1e-6f) : 1.0f; }
; #define PG8_MMA(ai, bj, At, Bt) do { __builtin_amdgcn_s_setprio(1); _Pragma("unroll") for (int m = 0; m < 4; ++m) _Pragma("unroll") for (int n = 0; n < 2; ++n) _Pragma("unroll") for (int k = 0; k < 2; ++k) \
;         acc[ai][bj][m][n] = __builtin_amdgcn_mfma_f32_16x16x32_bf16(Bt[n][k], At[m][k], acc[ai][bj][m][n], 0, 0, 0); __builtin_amdgcn_s_setprio(0); } while (0)
; #define PG8_WAIT_V(n) asm volatile("s_waitcnt vmcnt(" #n ")" ::: "memory")
; #define PG8_BAR __builtin_amdgcn_s_barrier()
; template <class Epi>
; __device__ __forceinline__ void gemm_phase(LAS unsigned char* lds, const Gemm g, const Sched& S, const Epi& E) {
;     ...
;             PG8_WAIT_V(6); PG8_BAR; PG8_MMA(1, 1, At, B1); PG8_BAR;
;         }
;         E(acc, cur, wr, wc, fr, fq, pre);
;     __device__ __forceinline__ void operator()(const Acc& acc, const Unit& u, int wr, int wc, int fr, int fq, const Pre& pre) const {
;     ...
;         float rsq[2][4];
; #pragma unroll
;         for (int ai = 0; ai < 2; ++ai)
; #pragma unroll
;             for (int m = 0; m < 4; ++m) rsq[ai][m] = rstd_pre(ss, pre_get(pre, ai, m, fr));
; #pragma unroll
;         for (int ai = 0; ai < 2; ++ai)
; #pragma unroll
;             for (int m = 0; m < 4; ++m) { const float rs = scale * rsq[ai][m];
; #pragma unroll
;                 for (int bj = 0; bj < 2; ++bj) { f32x4 v0 = acc[ai][bj][m][0] * rs, v1 = acc[ai][bj][m][1] * rs;
;                     if (act == 1) {
	s_setprio 1
	v_mfma_f32_16x16x32_bf16 v[30:33], v[142:145], v[180:183], v[30:33]
	v_mfma_f32_16x16x32_bf16 v[26:29], v[150:153], v[180:183], v[26:29]
	v_mfma_f32_16x16x32_bf16 v[14:17], v[142:145], v[188:191], v[14:17]
	v_mfma_f32_16x16x32_bf16 v[10:13], v[150:153], v[188:191], v[10:13]
	v_mfma_f32_16x16x32_bf16 v[62:65], v[146:149], v[168:171], v[62:65]
	v_mfma_f32_16x16x32_bf16 v[58:61], v[160:163], v[168:171], v[58:61]
	v_mfma_f32_16x16x32_bf16 v[46:49], v[146:149], v[176:179], v[46:49]
	v_mfma_f32_16x16x32_bf16 v[42:45], v[160:163], v[176:179], v[42:45]
	v_mfma_f32_16x16x32_bf16 v[30:33], v[146:149], v[184:187], v[30:33]
	v_mfma_f32_16x16x32_bf16 v[26:29], v[160:163], v[184:187], v[26:29]
	v_mfma_f32_16x16x32_bf16 v[14:17], v[146:149], v[196:199], v[14:17]
	v_mfma_f32_16x16x32_bf16 v[10:13], v[160:163], v[196:199], v[10:13]
	v_mfma_f32_16x16x32_bf16 v[54:57], v[200:203], v[164:167], v[54:57]
	v_mfma_f32_16x16x32_bf16 v[50:53], v[208:211], v[164:167], v[50:53]
	v_mfma_f32_16x16x32_bf16 v[38:41], v[200:203], v[172:175], v[38:41]
	v_mfma_f32_16x16x32_bf16 v[34:37], v[208:211], v[172:175], v[34:37]
	v_mfma_f32_16x16x32_bf16 v[22:25], v[200:203], v[180:183], v[22:25]
	v_mfma_f32_16x16x32_bf16 v[18:21], v[208:211], v[180:183], v[18:21]
	v_mfma_f32_16x16x32_bf16 v[6:9], v[200:203], v[188:191], v[6:9]
	v_mfma_f32_16x16x32_bf16 v[2:5], v[208:211], v[188:191], v[2:5]
	v_mfma_f32_16x16x32_bf16 v[54:57], v[204:207], v[168:171], v[54:57]
	v_mfma_f32_16x16x32_bf16 v[50:53], v[212:215], v[168:171], v[50:53]
	v_mfma_f32_16x16x32_bf16 v[38:41], v[204:207], v[176:179], v[38:41]
	v_mfma_f32_16x16x32_bf16 v[34:37], v[212:215], v[176:179], v[34:37]
	v_mfma_f32_16x16x32_bf16 v[22:25], v[204:207], v[184:187], v[22:25]
	v_mfma_f32_16x16x32_bf16 v[18:21], v[212:215], v[184:187], v[18:21]
	v_mfma_f32_16x16x32_bf16 v[6:9], v[204:207], v[196:199], v[6:9]
	v_mfma_f32_16x16x32_bf16 v[2:5], v[212:215], v[196:199], v[2:5]
	s_setprio 0
	s_add_u32 s4, s4, 0x100
	s_addc_u32 s5, s5, 0
	s_add_u32 s34, s34, 0x100
	s_addc_u32 s35, s35, 0
	s_cmp_ge_u32 s14, s73
	s_mov_b32 s6, s14
	s_barrier
	s_cbranch_scc0 .LBB0_555
	v_readfirstlane_b32 s98, v219
	s_nop 1
	s_bitcmp1_b32 s98, 8
	s_cbranch_scc1 .Lresync_x_555
	s_barrier
.Lresync_x_555:
	v_and_or_b32 v142, v220, 64, v154
	v_lshlrev_b32_e32 v148, 2, v142
	ds_bpermute_b32 v143, v148, v141
	ds_bpermute_b32 v142, v148, v141 offset:64
	s_mov_b32 s4, 0x3a000000
	ds_bpermute_b32 v145, v148, v141 offset:128
	ds_bpermute_b32 v144, v148, v141 offset:192
	v_readlane_b32 s8, v254, 29
	s_waitcnt lgkmcnt(0)
	v_pk_fma_f32 v[146:147], v[142:143], s[4:5], v[232:233] op_sel_hi:[1,0,0]
	ds_bpermute_b32 v143, v148, v140
	v_mul_f32_e32 v141, 0x4b800000, v147
	v_cmp_gt_f32_e32 vcc, s97, v147
	ds_bpermute_b32 v142, v148, v140 offset:64
	v_readlane_b32 s9, v254, 30
	v_cndmask_b32_e32 v141, v147, v141, vcc
	v_rsq_f32_e32 v141, v141
	v_cmp_gt_f32_e64 s[4:5], s97, v146
	s_mov_b64 s[90:91], -1
	v_mul_f32_e32 v147, 0x45800000, v141
	v_cndmask_b32_e32 v141, v141, v147, vcc
	v_cndmask_b32_e64 v147, v141, 1.0, s[78:79]
	ds_bpermute_b32 v141, v148, v140 offset:128
	ds_bpermute_b32 v140, v148, v140 offset:192
	v_mul_f32_e32 v148, s70, v147
	v_pk_mul_f32 v[152:153], v[122:123], v[148:149] op_sel_hi:[1,0]
	v_cndmask_b32_e64 v122, 0, 1, s[8:9]
	v_pk_mul_f32 v[128:129], v[128:129], v[148:149] op_sel_hi:[1,0]
	v_pk_mul_f32 v[150:151], v[126:127], v[148:149] op_sel_hi:[1,0]
	v_pk_mul_f32 v[126:127], v[124:125], v[148:149] op_sel_hi:[1,0]
	v_cmp_ne_u32_e64 s[6:7], 1, v122
	s_andn2_b64 vcc, exec, s[8:9]
	s_cbranch_vccnz .LBB0_558
	s_mov_b64 s[90:91], 0

; #define PG8_WAIT_V(n) asm volatile("s_waitcnt vmcnt(" #n ")" ::: "memory")
; #define PG8_BAR __builtin_amdgcn_s_barrier()
; template <class Epi>
; __device__ __forceinline__ void gemm_phase(LAS unsigned char* lds, const Gemm g, const Sched& S, const Epi& E) {
;     ...
;     PG8_WAIT_V(0);
;     if (wr == 0) PG8_BAR;
;     PG8_BAR;
.LBB0_621:
	s_waitcnt vmcnt(0)
	v_readlane_b32 s0, v254, 35
	v_readlane_b32 s90, v254, 39
	v_readlane_b32 s84, v254, 49
	s_cmpk_gt_u32 s0, 0xff
	v_readlane_b32 s58, v253, 45
	v_readlane_b32 s64, v253, 47
	v_readlane_b32 s91, v254, 40
	v_readlane_b32 s85, v254, 50
	v_readlane_b32 s59, v253, 46
	s_cbranch_scc1 .LBB0_623
.LBB0_623:
	v_readlane_b32 s38, v253, 30
	v_readlane_b32 s82, v254, 43
	v_readlane_b32 s66, v254, 45
	s_barrier
	v_readlane_b32 s39, v253, 31
	v_readlane_b32 s83, v254, 44
	v_readlane_b32 s57, v254, 37
	v_readlane_b32 s67, v254, 46

; __device__ __forceinline__ int otid() { int t = threadIdx.x; asm volatile("" : "+v"(t)); return t; }
; #define PG8_STAGE(bufoff, gbase, voff) do { _Pragma("unroll") for (int _i = 0; _i < 2; ++_i) \
;         __builtin_amdgcn_global_load_lds((const unsigned*)((const char*)(gbase) + (voff)[_i]), (LAS unsigned*)(lds + (bufoff) + ldsw + _i * 8192), 16, 0, 0); } while (0)
; #define PG8_WAIT_V(n) asm volatile("s_waitcnt vmcnt(" #n ")" ::: "memory")
; #define PG8_BAR __builtin_amdgcn_s_barrier()
; template <class Epi>
; __device__ __forceinline__ void gemm_phase(LAS unsigned char* lds, const Gemm g, const Sched& S, const Epi& E) {
;     const int tid = otid(), wid = __builtin_amdgcn_readfirstlane(tid >> 6), lane = tid & 63, wr = wid >> 2, wc = wid & 3, fr = lane & 15, fq = lane >> 4;
;     const int nt = g.K / BK;
;     unsigned voffA[2], voffB[2];
; #pragma unroll
;     for (int i = 0; i < 2; ++i) { int R, C; stage_rc(tid * 16 + i * 8192, R, C); const int Rb = Epi::PERM ? ((R & ~31) + perm32(R & 31)) : R;
;         voffA[i] = (unsigned)(R * g.lda + C) * 2u; voffB[i] = (unsigned)(Rb * g.ldb + C) * 2u; }
;     const size_t kstep = (size_t)(BK * 2);
;     const size_t hstepA = (size_t)HALF * g.lda * 2, hstepB = (size_t)HALF * g.ldb * 2;
;     const unsigned ldsw = (unsigned)wid * 1024u;
;     const int aoff = lds_byte(wr * 64 + fr, fq * 8), boff = lds_byte(wc * 32 + fr, fq * 8);
;     ...
;     Unit cur, nxt; int ui = 0;
;     if (!S.next(0, cur)) return;
;     f32x4 acc[2][2][4][2];
; #pragma unroll
;     for (int a = 0; a < 2; ++a)
; #pragma unroll
;         for (int b = 0; b < 2; ++b)
; #pragma unroll
;             for (int m = 0; m < 4; ++m)
; #pragma unroll
;                 for (int n = 0; n < 2; ++n) acc[a][b][m][n] = (f32x4){0.f, 0.f, 0.f, 0.f};
;     bf16x8 At[4][2], B0[2][2], B1[2][2];
;     const char* cA = (const char*)g.A + cur.ao; const char* cB = (const char*)g.Bt + cur.bo;
;     PG8_STAGE(PG8_SB(0, 0), cB, voffB); PG8_STAGE(PG8_SA(0, 0), cA, voffA); PG8_STAGE(PG8_SB(0, 1), cB + hstepB, voffB); PG8_STAGE(PG8_SA(0, 1), cA + hstepA, voffA);
;     if (wr == 1) PG8_BAR;
;     PG8_WAIT_V(4); PG8_BAR;
;     PG8_STAGE(PG8_SB(1, 0), cB + kstep, voffB); PG8_STAGE(PG8_SA(1, 0), cA + kstep, voffA); PG8_STAGE(PG8_SB(1, 1), cB + hstepB + kstep, voffB);
;     PG8_WAIT_V(6); PG8_BAR;
.LBB0_703:
	s_andn2_b64 vcc, exec, s[0:1]
	s_cbranch_vccnz .LBB0_803
	v_bfe_i32 v3, v16, 27, 1
	v_lshlrev_b32_e32 v2, 4, v16
	v_lshrrev_b32_e32 v3, 22, v3
	v_add_u32_e32 v3, v2, v3
	v_and_b32_e32 v3, 0xfffffc00, v3
	v_ashrrev_i32_e32 v0, 31, v16
	v_sub_u32_e32 v3, v2, v3
	v_lshrrev_b32_e32 v0, 26, v0
	v_lshrrev_b32_e32 v4, 4, v3
	v_add_u32_e32 v0, v16, v0
	v_bitop3_b32 v4, v4, v3, 32 bitop3:0x6c
	v_ashrrev_i32_e32 v3, 31, v3
	v_ashrrev_i32_e32 v0, 6, v0
	v_lshrrev_b32_e32 v3, 26, v3
	v_lshlrev_b32_e32 v5, 3, v0
	v_add_u32_e32 v3, v4, v3
	v_and_b32_e32 v5, -16, v5
	v_ashrrev_i32_e32 v3, 6, v3
	v_lshlrev_b32_e32 v0, 5, v0
	v_add_u32_e32 v5, v3, v5
	v_and_b32_e32 v14, 32, v0
	v_mul_i32_i24_e32 v0, 64, v3
	v_sub_u32_e32 v0, v4, v0
	v_mov_b32_e32 v7, 1
	v_lshlrev_b32_e32 v4, 1, v5
	v_lshrrev_b32_e32 v6, 2, v5
	v_and_b32_e32 v3, 3, v3
	s_mov_b32 s0, 0x7fffffe0
	v_ashrrev_i16_sdwa v0, v7, sext(v0) dst_sel:DWORD dst_unused:UNUSED_PAD src0_sel:DWORD src1_sel:BYTE_0
	v_and_b32_e32 v4, 24, v4
	v_and_b32_e32 v6, 4, v6
	v_and_or_b32 v3, v5, s0, v3
	v_bfe_i32 v15, v0, 0, 16
	v_or3_b32 v3, v3, v6, v4
	v_add_u32_e32 v0, v14, v15
	v_mul_lo_u32 v17, v5, s82
	v_mul_lo_u32 v3, v3, s66
	v_add_u32_e32 v2, 0x2000, v2
	v_add_lshl_u32 v196, v0, v17, 1
	v_add_lshl_u32 v0, v3, v0, 1
	v_ashrrev_i32_e32 v3, 31, v2
	v_lshrrev_b32_e32 v3, 22, v3
	v_add_u32_e32 v3, v2, v3
	v_ashrrev_i32_e32 v3, 10, v3
	v_mul_i32_i24_e32 v4, 0x400, v3
	v_sub_u32_e32 v2, v2, v4
	v_lshrrev_b32_e32 v4, 4, v2
	v_bitop3_b32 v2, v4, v2, 32 bitop3:0x6c
	v_ashrrev_i32_e32 v5, 31, v2
	v_lshrrev_b32_e32 v5, 26, v5
	v_writelane_b32 v254, s90, 39
	v_lshlrev_b32_e32 v4, 3, v3
	v_add_u32_e32 v5, v2, v5
	v_writelane_b32 v254, s91, 40
	v_and_b32_e32 v4, -16, v4
	v_ashrrev_i32_e32 v6, 6, v5
	v_lshlrev_b32_e32 v3, 5, v3
	v_writelane_b32 v254, s72, 41
	v_add_u32_e32 v4, v6, v4
	v_and_b32_e32 v18, 32, v3
	v_and_b32_e32 v3, 0xc0, v5
	v_sub_u32_e32 v2, v2, v3
	v_lshlrev_b32_e32 v3, 1, v4
	v_lshrrev_b32_e32 v5, 2, v4
	v_and_b32_e32 v6, 3, v6
	v_writelane_b32 v254, s8, 35
	v_and_b32_e32 v3, 24, v3
	v_and_b32_e32 v5, 4, v5
	v_and_or_b32 v6, v4, s0, v6
	v_mul_lo_u32 v20, v4, s82
	v_writelane_b32 v254, s82, 43
	v_or3_b32 v3, v6, v5, v3
	s_ashr_i32 s3, s8, 6
	v_writelane_b32 v254, s83, 44
	s_ashr_i32 s2, s8, 8
	v_mul_lo_u32 v3, v3, s66
	s_lshl_b64 s[40:41], s[82:83], 8
	v_writelane_b32 v254, s66, 45
	s_lshl_b64 s[76:77], s[66:67], 8
	s_lshl_b32 s43, s3, 10
	s_add_u32 s4, s10, s4
	v_ashrrev_i16_sdwa v2, v7, sext(v2) dst_sel:DWORD dst_unused:UNUSED_PAD src0_sel:DWORD src1_sel:BYTE_0
	s_addc_u32 s5, s11, s5
	s_add_i32 s52, s43, 0
	v_bfe_i32 v19, v2, 0, 16
	v_writelane_b32 v254, s67, 46
	s_add_i32 m0, s52, 0x10000
	v_add_u32_e32 v2, v18, v19
	global_load_lds_dwordx4 v0, s[4:5]
	s_add_i32 m0, s52, 0x12000
	v_readlane_b32 s0, v254, 11
	v_add_lshl_u32 v200, v3, v2, 1
	v_readlane_b32 s1, v254, 12
	s_add_u32 s0, s0, s6
	global_load_lds_dwordx4 v200, s[4:5]
	s_addc_u32 s1, s1, s7
	s_mov_b32 m0, s52
	s_add_i32 s53, s52, 0x2000
	v_add_lshl_u32 v198, v2, v20, 1
	global_load_lds_dwordx4 v196, s[0:1]
	s_mov_b32 m0, s53
	s_add_u32 s6, s4, s76
	global_load_lds_dwordx4 v198, s[0:1]
	s_addc_u32 s7, s5, s77
	s_add_i32 m0, s52, 0x14000
	v_mov_b32_e32 v201, v1
	global_load_lds_dwordx4 v0, s[6:7]
	s_add_i32 m0, s52, 0x16000
	v_lshl_add_u64 v[10:11], s[6:7], 0, v[0:1]
	v_lshl_add_u64 v[12:13], s[6:7], 0, v[200:201]
	global_load_lds_dwordx4 v200, s[6:7]
	s_add_u32 s6, s0, s40
	s_addc_u32 s7, s1, s41
	s_add_i32 s56, s52, 0x4000
	s_mov_b32 m0, s56
	s_add_i32 s67, s52, 0x6000
	global_load_lds_dwordx4 v196, s[6:7]
	s_mov_b32 m0, s67
	v_mov_b32_e32 v197, v1
	global_load_lds_dwordx4 v198, s[6:7]
	v_mov_b32_e32 v199, v1
	v_lshl_add_u64 v[2:3], s[4:5], 0, v[0:1]
	v_lshl_add_u64 v[4:5], s[4:5], 0, v[200:201]
	v_lshl_add_u64 v[6:7], s[0:1], 0, v[196:197]
	v_lshl_add_u64 v[8:9], s[0:1], 0, v[198:199]
	s_cmp_lg_u32 s2, 1
	s_cbranch_scc1 .LBB0_706
.LBB0_706:
	v_bfe_u32 v21, v16, 4, 2
	v_and_b32_e32 v22, 15, v16
	v_lshlrev_b32_e32 v23, 4, v21
	v_lshlrev_b32_e32 v16, 2, v16
	v_lshl_or_b32 v216, s2, 6, v22
	v_lshl_or_b32 v22, v22, 6, v23
	s_lshl_b32 s2, s2, 13
	v_and_b32_e32 v16, 32, v16
	v_bitop3_b32 v23, v22, s2, v16 bitop3:0xde
	s_lshl_b32 s2, s3, 5
	s_and_b32 s3, s2, 0x60
	s_add_i32 m0, s52, 0x18000
	v_lshl_add_u64 v[2:3], v[2:3], 0, s[60:61]
	s_lshl_b32 s2, s3, 7
	s_waitcnt vmcnt(4)
	s_barrier
	global_load_lds_dwordx4 v[2:3], off
	v_lshl_add_u64 v[2:3], v[4:5], 0, s[60:61]
	s_add_i32 m0, s52, 0x1a000
	s_add_i32 s51, s52, 0x8000
	v_bitop3_b32 v217, v22, s2, v16 bitop3:0xde
	global_load_lds_dwordx4 v[2:3], off
	v_lshl_add_u64 v[2:3], v[6:7], 0, s[60:61]
	s_mov_b32 m0, s51
	s_add_i32 s2, s52, 0xa000
	global_load_lds_dwordx4 v[2:3], off
	v_lshl_add_u64 v[2:3], v[8:9], 0, s[60:61]
	s_mov_b32 m0, s2
	v_readlane_b32 s8, v254, 13
	global_load_lds_dwordx4 v[2:3], off
	s_add_i32 m0, s52, 0x1c000
	v_lshl_add_u64 v[2:3], v[10:11], 0, s[60:61]
	global_load_lds_dwordx4 v[2:3], off
	v_lshl_add_u64 v[2:3], v[12:13], 0, s[60:61]
	s_add_i32 m0, s52, 0x1e000
	s_ashr_i32 s72, s8, 31
	global_load_lds_dwordx4 v[2:3], off
	v_readlane_b32 s8, v253, 30
	s_lshr_b32 s8, s54, 3
	v_readlane_b32 s9, v253, 31
	v_writelane_b32 v254, s8, 33
	s_add_i32 s8, s8, 1
	v_writelane_b32 v254, s8, 9
	s_mov_b32 s27, s9
	v_readlane_b32 s8, v254, 5
	s_mul_i32 s58, s8, s57
	v_cvt_f32_u32_e32 v2, s58
	v_writelane_b32 v254, s57, 37
	s_add_i32 s48, s73, -2
	v_readlane_b32 s8, v254, 7
	v_rcp_iflag_f32_e32 v2, v2
	s_and_b32 s64, s54, 7
	v_readlane_b32 s9, v254, 8
	s_cmp_eq_u64 s[8:9], 0
	v_mul_f32_e32 v2, 0x4f7ffffe, v2
	v_cvt_u32_f32_e32 v2, v2
	s_cselect_b64 s[36:37], -1, 0
	s_cmp_lg_u64 s[8:9], 0
	v_readlane_b32 s8, v254, 1
	v_readfirstlane_b32 s14, v2
	v_cvt_f32_u32_e32 v2, s25
	s_cselect_b64 s[78:79], -1, 0
	s_cmp_lg_u64 s[68:69], 0
	v_readlane_b32 s9, v254, 2
	v_rcp_iflag_f32_e32 v2, v2
	s_cselect_b64 s[82:83], -1, 0
	s_cmp_lg_u64 s[8:9], 0
	s_cselect_b64 s[84:85], -1, 0
	v_mul_f32_e32 v2, 0x4f7ffffe, v2
	v_lshl_or_b32 v234, v21, 3, s3
	s_sub_i32 s3, 0, s58
	v_cvt_u32_f32_e32 v2, v2
	s_mul_i32 s3, s3, s14
	s_mul_hi_u32 s3, s14, s3
	s_add_i32 s3, s14, s3
	v_writelane_b32 v254, s3, 29
	s_sub_i32 s3, 0, s25
	v_readfirstlane_b32 s14, v2
	v_add_u32_e32 v2, v17, v14
	s_mul_i32 s3, s3, s14
	v_add_lshl_u32 v2, v2, v15, 1
	v_mov_b32_e32 v3, v1
	s_waitcnt vmcnt(6)
	s_mul_hi_u32 s3, s14, s3
	v_lshl_add_u64 v[202:203], s[40:41], 0, v[2:3]
	v_add_u32_e32 v2, v20, v18
	s_add_i32 s3, s14, s3
	v_add_lshl_u32 v2, v2, v19, 1
	s_mov_b32 s33, 0
	v_cmp_eq_u32_e64 s[6:7], 0, v21
	s_mov_b32 s71, s70
	s_mov_b32 s80, s70
	s_mov_b32 s81, s70
	v_writelane_b32 v254, s3, 31
	v_lshl_add_u64 v[204:205], s[40:41], 0, v[2:3]
	v_add_u32_e32 v235, 0, v23
	s_barrier
	s_branch .LBB0_709

; #define PG8_STAGE(bufoff, gbase, voff) do { _Pragma("unroll") for (int _i = 0; _i < 2; ++_i) \
;         __builtin_amdgcn_global_load_lds((const unsigned*)((const char*)(gbase) + (voff)[_i]), (LAS unsigned*)(lds + (bufoff) + ldsw + _i * 8192), 16, 0, 0); } while (0)
; #define PG8_LDA(dst, b, h) do { _Pragma("unroll") for (int m = 0; m < 4; ++m) _Pragma("unroll") for (int k = 0; k < 2; ++k) dst[m][k] = *(const LAS bf16x8*)(lds + PG8_SA(b, h) + aoff + m * 2048 + k * 1024); } while (0)
; #define PG8_LDB(dst, b, h) do { _Pragma("unroll") for (int n = 0; n < 2; ++n) _Pragma("unroll") for (int k = 0; k < 2; ++k) dst[n][k] = *(const LAS bf16x8*)(lds + PG8_SB(b, h) + boff + n * 2048 + k * 1024); } while (0)
; #define PG8_MMA(ai, bj, At, Bt) do { __builtin_amdgcn_s_setprio(1); _Pragma("unroll") for (int m = 0; m < 4; ++m) _Pragma("unroll") for (int n = 0; n < 2; ++n) _Pragma("unroll") for (int k = 0; k < 2; ++k) \
;         acc[ai][bj][m][n] = __builtin_amdgcn_mfma_f32_16x16x32_bf16(Bt[n][k], At[m][k], acc[ai][bj][m][n], 0, 0, 0); __builtin_amdgcn_s_setprio(0); } while (0)
; template <class Epi>
; __device__ __forceinline__ void gemm_phase(LAS unsigned char* lds, const Gemm g, const Sched& S, const Epi& E) {
;     ...
;         const char* nA = has_next ? (const char*)g.A + nxt.ao : cA; const char* nB = has_next ? (const char*)g.Bt + nxt.bo : cB;
;         for (int t = 0; t < nt; t += 2) {
;             const bool last = (t == nt - 2);
;             const char* a1 = cA + (size_t)(t + 1) * kstep;
;             const char* a2 = last ? nA : cA + (size_t)(t + 2) * kstep; const char* b2 = last ? nB : cB + (size_t)(t + 2) * kstep;
;             const char* a3 = a2 + kstep; const char* b3 = b2 + kstep;
;             PG8_LDB(B0, 0, 0); PG8_SCHED; PG8_LDA(At, 0, 0); PG8_STAGE(PG8_SA(1, 1), a1 + hstepA, voffA);
;             PG8_WAIT_L(8); PG8_BAR; PG8_WAIT_L(0); PG8_MMA(0, 0, At, B0); PG8_BAR; PG8_SCHED;
;             PG8_LDB(B1, 0, 1); PG8_STAGE(PG8_SB(0, 0), b2, voffB);
;             PG8_BAR; PG8_WAIT_L(0); PG8_MMA(0, 1, At, B1); PG8_BAR;
;     ...
; #pragma unroll
;         for (int a = 0; a < 2; ++a)
; #pragma unroll
;             for (int b = 0; b < 2; ++b)
; #pragma unroll
;                 for (int m = 0; m < 4; ++m)
; #pragma unroll
;                     for (int n = 0; n < 2; ++n) acc[a][b][m][n] = (f32x4){0.f, 0.f, 0.f, 0.f};
;         cur = nxt; cA = nA; cB = nB; ++ui;
.LBB0_718:
	v_mov_b64_e32 v[2:3], s[26:27]
	v_readlane_b32 s8, v254, 11
	v_cmp_lt_i64_e32 vcc, s[90:91], v[2:3]
	v_readlane_b32 s9, v254, 12
	s_add_u32 s90, s8, s86
	s_addc_u32 s91, s9, s87
	s_and_b64 s[14:15], vcc, exec
	s_cselect_b32 s57, s91, s1
	s_cselect_b32 s59, s90, s0
	s_add_u32 s92, s10, s88
	s_addc_u32 s93, s11, s89
	s_and_b64 s[14:15], vcc, exec
	s_cselect_b32 vcc_lo, s93, s5
	s_cselect_b32 vcc_hi, s92, s4
	s_add_u32 s0, s0, 0x80
	s_addc_u32 s1, s1, 0
	s_add_u32 s34, s4, 0x100
	v_mov_b32_e32 v2, 0
	s_addc_u32 s35, s5, 0
	s_mov_b32 s4, 0
	v_mov_b32_e32 v3, v2
	v_mov_b32_e32 v4, v2
	v_mov_b32_e32 v5, v2
	v_mov_b32_e32 v6, v2
	v_mov_b32_e32 v7, v2
	v_mov_b32_e32 v8, v2
	v_mov_b32_e32 v9, v2
	v_mov_b32_e32 v18, v2
	v_mov_b32_e32 v19, v2
	v_mov_b32_e32 v20, v2
	v_mov_b32_e32 v21, v2
	v_mov_b32_e32 v22, v2
	v_mov_b32_e32 v23, v2
	v_mov_b32_e32 v24, v2
	v_mov_b32_e32 v25, v2
	v_mov_b32_e32 v34, v2
	v_mov_b32_e32 v35, v2
	v_mov_b32_e32 v36, v2
	v_mov_b32_e32 v37, v2
	v_mov_b32_e32 v38, v2
	v_mov_b32_e32 v39, v2
	v_mov_b32_e32 v40, v2
	v_mov_b32_e32 v41, v2
	v_mov_b32_e32 v50, v2
	v_mov_b32_e32 v51, v2
	v_mov_b32_e32 v52, v2
	v_mov_b32_e32 v53, v2
	v_mov_b32_e32 v54, v2
	v_mov_b32_e32 v55, v2
	v_mov_b32_e32 v56, v2
	v_mov_b32_e32 v57, v2
	v_mov_b32_e32 v10, v2
	v_mov_b32_e32 v11, v2
	v_mov_b32_e32 v12, v2
	v_mov_b32_e32 v13, v2
	v_mov_b32_e32 v14, v2
	v_mov_b32_e32 v15, v2
	v_mov_b32_e32 v16, v2
	v_mov_b32_e32 v17, v2
	v_mov_b32_e32 v26, v2
	v_mov_b32_e32 v27, v2
	v_mov_b32_e32 v28, v2
	v_mov_b32_e32 v29, v2
	v_mov_b32_e32 v30, v2
	v_mov_b32_e32 v31, v2
	v_mov_b32_e32 v32, v2
	v_mov_b32_e32 v33, v2
	v_mov_b32_e32 v42, v2
	v_mov_b32_e32 v43, v2
	v_mov_b32_e32 v44, v2
	v_mov_b32_e32 v45, v2
	v_mov_b32_e32 v46, v2
	v_mov_b32_e32 v47, v2
	v_mov_b32_e32 v48, v2
	v_mov_b32_e32 v49, v2
	v_mov_b32_e32 v58, v2
	v_mov_b32_e32 v59, v2
	v_mov_b32_e32 v60, v2
	v_mov_b32_e32 v61, v2
	v_mov_b32_e32 v62, v2
	v_mov_b32_e32 v63, v2
	v_mov_b32_e32 v64, v2
	v_mov_b32_e32 v65, v2
	v_mov_b32_e32 v66, v2
	v_mov_b32_e32 v67, v2
	v_mov_b32_e32 v68, v2
	v_mov_b32_e32 v69, v2
	v_mov_b32_e32 v70, v2
	v_mov_b32_e32 v71, v2
	v_mov_b32_e32 v72, v2
	v_mov_b32_e32 v73, v2
	v_mov_b32_e32 v82, v2
	v_mov_b32_e32 v83, v2
	v_mov_b32_e32 v84, v2
	v_mov_b32_e32 v85, v2
	v_mov_b32_e32 v86, v2
	v_mov_b32_e32 v87, v2
	v_mov_b32_e32 v88, v2
	v_mov_b32_e32 v89, v2
	v_mov_b32_e32 v98, v2
	v_mov_b32_e32 v99, v2
	v_mov_b32_e32 v100, v2
	v_mov_b32_e32 v101, v2
	v_mov_b32_e32 v102, v2
	v_mov_b32_e32 v103, v2
	v_mov_b32_e32 v104, v2
	v_mov_b32_e32 v105, v2
	v_mov_b32_e32 v178, v2
	v_mov_b32_e32 v179, v2
	v_mov_b32_e32 v180, v2
	v_mov_b32_e32 v181, v2
	v_mov_b32_e32 v182, v2
	v_mov_b32_e32 v183, v2
	v_mov_b32_e32 v184, v2
	v_mov_b32_e32 v185, v2
	v_mov_b32_e32 v74, v2
	v_mov_b32_e32 v75, v2
	v_mov_b32_e32 v76, v2
	v_mov_b32_e32 v77, v2
	v_mov_b32_e32 v78, v2
	v_mov_b32_e32 v79, v2
	v_mov_b32_e32 v80, v2
	v_mov_b32_e32 v81, v2
	v_mov_b32_e32 v90, v2
	v_mov_b32_e32 v91, v2
	v_mov_b32_e32 v92, v2
	v_mov_b32_e32 v93, v2
	v_mov_b32_e32 v94, v2
	v_mov_b32_e32 v95, v2
	v_mov_b32_e32 v96, v2
	v_mov_b32_e32 v97, v2
	v_mov_b32_e32 v162, v2
	v_mov_b32_e32 v163, v2
	v_mov_b32_e32 v164, v2
	v_mov_b32_e32 v165, v2
	v_mov_b32_e32 v174, v2
	v_mov_b32_e32 v175, v2
	v_mov_b32_e32 v176, v2
	v_mov_b32_e32 v177, v2
	v_mov_b32_e32 v186, v2
	v_mov_b32_e32 v187, v2
	v_mov_b32_e32 v188, v2
	v_mov_b32_e32 v189, v2
	v_mov_b32_e32 v190, v2
	v_mov_b32_e32 v191, v2
	v_mov_b32_e32 v192, v2
	v_mov_b32_e32 v193, v2
	v_readfirstlane_b32 s98, v219
	s_nop 1
	s_bitcmp1_b32 s98, 8
	s_cbranch_scc0 .Lresync_y_719
	s_barrier
.Lresync_y_719:
.LBB0_719:
	s_add_i32 s14, s4, 2
	s_add_u32 s15, s0, 0x80
	s_addc_u32 s5, s1, 0
	s_add_i32 s8, 0, 0x10000
	v_add_u32_e32 v118, s8, v217
	ds_read_b128 v[106:109], v118
	ds_read_b128 v[110:113], v118 offset:1024
	ds_read_b128 v[114:117], v118 offset:2048
	ds_read_b128 v[118:121], v118 offset:3072
	s_cmp_eq_u32 s48, s4
	s_cselect_b32 s4, s59, s15
	s_cselect_b32 s5, s57, s5
	s_cselect_b32 s95, vcc_lo, s35
	s_cselect_b32 s94, vcc_hi, s34
	v_lshl_add_u64 v[154:155], s[0:1], 0, v[202:203]
	s_add_i32 m0, s52, 0xc000
	ds_read_b128 v[122:125], v235
	ds_read_b128 v[126:129], v235 offset:1024
	ds_read_b128 v[130:133], v235 offset:2048
	ds_read_b128 v[134:137], v235 offset:3072
	ds_read_b128 v[138:141], v235 offset:4096
	ds_read_b128 v[142:145], v235 offset:5120
	ds_read_b128 v[146:149], v235 offset:6144
	ds_read_b128 v[150:153], v235 offset:7168
	global_load_lds_dwordx4 v[154:155], off
	v_lshl_add_u64 v[154:155], s[0:1], 0, v[204:205]
	s_add_i32 m0, s52, 0xe000
	s_nop 0
	global_load_lds_dwordx4 v[154:155], off
	s_waitcnt lgkmcnt(8)
	s_waitcnt lgkmcnt(0)
	v_mfma_f32_16x16x32_bf16 v[162:165], v[114:117], v[130:133], v[162:165]
	v_mfma_f32_16x16x32_bf16 v[94:97], v[106:109], v[138:141], v[94:97]
	v_mfma_f32_16x16x32_bf16 v[90:93], v[114:117], v[138:141], v[90:93]
	v_mfma_f32_16x16x32_bf16 v[78:81], v[106:109], v[146:149], v[78:81]
	s_barrier
	s_waitcnt lgkmcnt(0)
	s_setprio 1
	s_waitcnt lgkmcnt(0)
	v_mfma_f32_16x16x32_bf16 v[74:77], v[114:117], v[146:149], v[74:77]
	v_mfma_f32_16x16x32_bf16 v[154:157], v[106:109], v[122:125], v[190:193]
	v_mfma_f32_16x16x32_bf16 v[158:161], v[114:117], v[122:125], v[186:189]
	v_mfma_f32_16x16x32_bf16 v[166:169], v[106:109], v[130:133], v[174:177]
	v_mfma_f32_16x16x32_bf16 v[162:165], v[118:121], v[134:137], v[162:165]
	v_mfma_f32_16x16x32_bf16 v[94:97], v[110:113], v[142:145], v[94:97]
	v_mfma_f32_16x16x32_bf16 v[90:93], v[118:121], v[142:145], v[90:93]
	v_mfma_f32_16x16x32_bf16 v[78:81], v[110:113], v[150:153], v[78:81]
	v_mfma_f32_16x16x32_bf16 v[74:77], v[118:121], v[150:153], v[74:77]
	v_mfma_f32_16x16x32_bf16 v[154:157], v[110:113], v[126:129], v[154:157]
	v_mfma_f32_16x16x32_bf16 v[158:161], v[118:121], v[126:129], v[158:161]
	v_mfma_f32_16x16x32_bf16 v[166:169], v[110:113], v[134:137], v[166:169]
	s_setprio 0
	s_barrier
; #define PG8_STAGE(bufoff, gbase, voff) do { _Pragma("unroll") for (int _i = 0; _i < 2; ++_i) \
;         __builtin_amdgcn_global_load_lds((const unsigned*)((const char*)(gbase) + (voff)[_i]), (LAS unsigned*)(lds + (bufoff) + ldsw + _i * 8192), 16, 0, 0); } while (0)
; #define PG8_LDA(dst, b, h) do { _Pragma("unroll") for (int m = 0; m < 4; ++m) _Pragma("unroll") for (int k = 0; k < 2; ++k) dst[m][k] = *(const LAS bf16x8*)(lds + PG8_SA(b, h) + aoff + m * 2048 + k * 1024); } while (0)
; #define PG8_LDB(dst, b, h) do { _Pragma("unroll") for (int n = 0; n < 2; ++n) _Pragma("unroll") for (int k = 0; k < 2; ++k) dst[n][k] = *(const LAS bf16x8*)(lds + PG8_SB(b, h) + boff + n * 2048 + k * 1024); } while (0)
; #define PG8_MMA(ai, bj, At, Bt) do { __builtin_amdgcn_s_setprio(1); _Pragma("unroll") for (int m = 0; m < 4; ++m) _Pragma("unroll") for (int n = 0; n < 2; ++n) _Pragma("unroll") for (int k = 0; k < 2; ++k) \
;         acc[ai][bj][m][n] = __builtin_amdgcn_mfma_f32_16x16x32_bf16(Bt[n][k], At[m][k], acc[ai][bj][m][n], 0, 0, 0); __builtin_amdgcn_s_setprio(0); } while (0)
; #define PG8_WAIT_V(n) asm volatile("s_waitcnt vmcnt(" #n ")" ::: "memory")
; #define PG8_WAIT_L(n) asm volatile("s_waitcnt lgkmcnt(" #n ")" ::: "memory")
; #define PG8_BAR __builtin_amdgcn_s_barrier()
; #define PG8_SCHED __builtin_amdgcn_sched_barrier(0)
; template <class Epi>
; __device__ __forceinline__ void gemm_phase(LAS unsigned char* lds, const Gemm g, const Sched& S, const Epi& E) {
;     ...
;             PG8_LDB(B1, 0, 1); PG8_STAGE(PG8_SB(0, 0), b2, voffB);
;             PG8_BAR; PG8_WAIT_L(0); PG8_MMA(0, 1, At, B1); PG8_BAR;
;             PG8_LDA(At, 0, 1); PG8_STAGE(PG8_SA(0, 0), a2, voffA);
;             PG8_BAR; PG8_WAIT_L(0); PG8_MMA(1, 0, At, B0); PG8_BAR; PG8_SCHED;
;             PG8_STAGE(PG8_SB(0, 1), b2 + hstepB, voffB);
;             PG8_WAIT_V(6); PG8_BAR; PG8_MMA(1, 1, At, B1); PG8_BAR;
;             PG8_LDB(B0, 1, 0); PG8_SCHED; PG8_LDA(At, 1, 0); PG8_STAGE(PG8_SA(0, 1), a2 + hstepA, voffA);
;             PG8_WAIT_L(8); PG8_BAR; PG8_WAIT_L(0); PG8_MMA(0, 0, At, B0); PG8_BAR; PG8_SCHED;
;             PG8_LDB(B1, 1, 1); PG8_STAGE(PG8_SB(1, 0), b3, voffB);
	s_add_i32 s9, 0, 0x14000
	s_add_i32 s8, s8, s43
	v_add_u32_e32 v190, s9, v217
	v_lshl_add_u64 v[210:211], s[94:95], 0, v[0:1]
	s_mov_b32 m0, s8
	ds_read_b128 v[170:173], v190
	ds_read_b128 v[174:177], v190 offset:1024
	ds_read_b128 v[186:189], v190 offset:2048
	ds_read_b128 v[190:193], v190 offset:3072
	global_load_lds_dwordx4 v[210:211], off
	v_lshl_add_u64 v[212:213], s[94:95], 0, v[200:201]
	s_add_i32 m0, s8, 0x2000
	s_nop 0
	global_load_lds_dwordx4 v[212:213], off
	s_waitcnt lgkmcnt(0)
	v_mfma_f32_16x16x32_bf16 v[182:185], v[170:173], v[122:125], v[182:185]
	v_mfma_f32_16x16x32_bf16 v[102:105], v[170:173], v[130:133], v[102:105]
	v_mfma_f32_16x16x32_bf16 v[98:101], v[186:189], v[130:133], v[98:101]
	v_mfma_f32_16x16x32_bf16 v[86:89], v[170:173], v[138:141], v[86:89]
	s_barrier
	s_waitcnt lgkmcnt(0)
	s_setprio 1
	s_waitcnt lgkmcnt(0)
	v_mfma_f32_16x16x32_bf16 v[82:85], v[186:189], v[138:141], v[82:85]
	v_mfma_f32_16x16x32_bf16 v[70:73], v[170:173], v[146:149], v[70:73]
	v_mfma_f32_16x16x32_bf16 v[66:69], v[186:189], v[146:149], v[66:69]
	v_mfma_f32_16x16x32_bf16 v[182:185], v[174:177], v[126:129], v[182:185]
	v_mfma_f32_16x16x32_bf16 v[122:125], v[186:189], v[122:125], v[178:181]
	v_mfma_f32_16x16x32_bf16 v[102:105], v[174:177], v[134:137], v[102:105]
	v_mfma_f32_16x16x32_bf16 v[98:101], v[190:193], v[134:137], v[98:101]
	v_mfma_f32_16x16x32_bf16 v[86:89], v[174:177], v[142:145], v[86:89]
	v_mfma_f32_16x16x32_bf16 v[82:85], v[190:193], v[142:145], v[82:85]
	v_mfma_f32_16x16x32_bf16 v[70:73], v[174:177], v[150:153], v[70:73]
	v_mfma_f32_16x16x32_bf16 v[66:69], v[190:193], v[150:153], v[66:69]
	v_mfma_f32_16x16x32_bf16 v[122:125], v[190:193], v[126:129], v[122:125]
	s_setprio 0
	s_mov_b32 m0, s52
	v_lshl_add_u64 v[214:215], s[4:5], 0, v[196:197]
	s_barrier
	ds_read_b128 v[126:129], v235 offset:16384
	ds_read_b128 v[130:133], v235 offset:17408
	ds_read_b128 v[134:137], v235 offset:18432
	ds_read_b128 v[138:141], v235 offset:19456
	ds_read_b128 v[142:145], v235 offset:20480
	ds_read_b128 v[146:149], v235 offset:21504
	ds_read_b128 v[150:153], v235 offset:22528
	ds_read_b128 v[178:181], v235 offset:23552
	global_load_lds_dwordx4 v[214:215], off
	v_lshl_add_u64 v[222:223], s[4:5], 0, v[198:199]
	s_mov_b32 m0, s53
	s_nop 0
	global_load_lds_dwordx4 v[222:223], off
	s_waitcnt lgkmcnt(0)
	v_mfma_f32_16x16x32_bf16 v[62:65], v[106:109], v[126:129], v[62:65]
	v_mfma_f32_16x16x32_bf16 v[58:61], v[114:117], v[126:129], v[58:61]
	v_mfma_f32_16x16x32_bf16 v[46:49], v[106:109], v[134:137], v[46:49]
	v_mfma_f32_16x16x32_bf16 v[42:45], v[114:117], v[134:137], v[42:45]
	s_barrier
	s_waitcnt lgkmcnt(0)
	s_setprio 1
	s_waitcnt lgkmcnt(0)
	v_mfma_f32_16x16x32_bf16 v[30:33], v[106:109], v[142:145], v[30:33]
	v_mfma_f32_16x16x32_bf16 v[26:29], v[114:117], v[142:145], v[26:29]
	v_mfma_f32_16x16x32_bf16 v[14:17], v[106:109], v[150:153], v[14:17]
	v_mfma_f32_16x16x32_bf16 v[10:13], v[114:117], v[150:153], v[10:13]
	v_mfma_f32_16x16x32_bf16 v[62:65], v[110:113], v[130:133], v[62:65]
	v_mfma_f32_16x16x32_bf16 v[58:61], v[118:121], v[130:133], v[58:61]
	v_mfma_f32_16x16x32_bf16 v[46:49], v[110:113], v[138:141], v[46:49]
	v_mfma_f32_16x16x32_bf16 v[42:45], v[118:121], v[138:141], v[42:45]
	v_mfma_f32_16x16x32_bf16 v[30:33], v[110:113], v[146:149], v[30:33]
	v_mfma_f32_16x16x32_bf16 v[26:29], v[118:121], v[146:149], v[26:29]
	v_mfma_f32_16x16x32_bf16 v[14:17], v[110:113], v[178:181], v[14:17]
	v_mfma_f32_16x16x32_bf16 v[10:13], v[118:121], v[178:181], v[10:13]
	s_setprio 0
	s_barrier
	s_add_u32 s94, s94, s76
	s_addc_u32 s95, s95, s77
	s_add_i32 s8, s9, s43
	v_lshl_add_u64 v[224:225], s[94:95], 0, v[0:1]
	s_mov_b32 m0, s8
	v_lshl_add_u64 v[226:227], s[94:95], 0, v[200:201]
	global_load_lds_dwordx4 v[224:225], off
	s_add_i32 m0, s8, 0x2000
	s_nop 0
	global_load_lds_dwordx4 v[226:227], off
	s_waitcnt vmcnt(6)
	s_waitcnt lgkmcnt(0)
	v_mfma_f32_16x16x32_bf16 v[54:57], v[170:173], v[126:129], v[54:57]
	v_mfma_f32_16x16x32_bf16 v[50:53], v[186:189], v[126:129], v[50:53]
	v_mfma_f32_16x16x32_bf16 v[38:41], v[170:173], v[134:137], v[38:41]
	v_mfma_f32_16x16x32_bf16 v[34:37], v[186:189], v[134:137], v[34:37]
	s_barrier
	s_setprio 1
	v_mfma_f32_16x16x32_bf16 v[22:25], v[170:173], v[142:145], v[22:25]
	v_mfma_f32_16x16x32_bf16 v[18:21], v[186:189], v[142:145], v[18:21]
	v_mfma_f32_16x16x32_bf16 v[6:9], v[170:173], v[150:153], v[6:9]
	v_mfma_f32_16x16x32_bf16 v[2:5], v[186:189], v[150:153], v[2:5]
	v_mfma_f32_16x16x32_bf16 v[54:57], v[174:177], v[130:133], v[54:57]
	v_mfma_f32_16x16x32_bf16 v[50:53], v[190:193], v[130:133], v[50:53]
	v_mfma_f32_16x16x32_bf16 v[38:41], v[174:177], v[138:141], v[38:41]
	v_mfma_f32_16x16x32_bf16 v[34:37], v[190:193], v[138:141], v[34:37]
	v_mfma_f32_16x16x32_bf16 v[22:25], v[174:177], v[146:149], v[22:25]
	v_mfma_f32_16x16x32_bf16 v[18:21], v[190:193], v[146:149], v[18:21]
	v_mfma_f32_16x16x32_bf16 v[6:9], v[174:177], v[178:181], v[6:9]
	v_mfma_f32_16x16x32_bf16 v[2:5], v[190:193], v[178:181], v[2:5]
	s_setprio 0
	s_add_i32 s8, 0, 0x18000
	v_add_u32_e32 v118, s8, v217
	s_barrier
	ds_read_b128 v[106:109], v118
	ds_read_b128 v[110:113], v118 offset:1024
	ds_read_b128 v[114:117], v118 offset:2048
	ds_read_b128 v[118:121], v118 offset:3072
	s_add_u32 s4, s4, s40
	s_addc_u32 s5, s5, s41
	s_mov_b32 m0, s56
	v_lshl_add_u64 v[174:175], s[4:5], 0, v[196:197]
	ds_read_b128 v[126:129], v235 offset:32768
	ds_read_b128 v[130:133], v235 offset:33792
	ds_read_b128 v[134:137], v235 offset:34816
	ds_read_b128 v[138:141], v235 offset:35840
	ds_read_b128 v[142:145], v235 offset:36864
	ds_read_b128 v[146:149], v235 offset:37888
	ds_read_b128 v[150:153], v235 offset:38912
	ds_read_b128 v[170:173], v235 offset:39936
	global_load_lds_dwordx4 v[174:175], off
	v_lshl_add_u64 v[174:175], s[4:5], 0, v[198:199]
	s_mov_b32 m0, s67
	s_nop 0
	global_load_lds_dwordx4 v[174:175], off
	s_waitcnt lgkmcnt(8)
	s_waitcnt lgkmcnt(0)
	v_mfma_f32_16x16x32_bf16 v[154:157], v[106:109], v[126:129], v[154:157]
	v_mfma_f32_16x16x32_bf16 v[190:193], v[110:113], v[130:133], v[154:157]
	v_mfma_f32_16x16x32_bf16 v[154:157], v[114:117], v[126:129], v[158:161]
	v_mfma_f32_16x16x32_bf16 v[186:189], v[118:121], v[130:133], v[154:157]
	s_barrier
; #define PG8_STAGE(bufoff, gbase, voff) do { _Pragma("unroll") for (int _i = 0; _i < 2; ++_i) \
;         __builtin_amdgcn_global_load_lds((const unsigned*)((const char*)(gbase) + (voff)[_i]), (LAS unsigned*)(lds + (bufoff) + ldsw + _i * 8192), 16, 0, 0); } while (0)
; #define PG8_LDA(dst, b, h) do { _Pragma("unroll") for (int m = 0; m < 4; ++m) _Pragma("unroll") for (int k = 0; k < 2; ++k) dst[m][k] = *(const LAS bf16x8*)(lds + PG8_SA(b, h) + aoff + m * 2048 + k * 1024); } while (0)
; #define PG8_LDB(dst, b, h) do { _Pragma("unroll") for (int n = 0; n < 2; ++n) _Pragma("unroll") for (int k = 0; k < 2; ++k) dst[n][k] = *(const LAS bf16x8*)(lds + PG8_SB(b, h) + boff + n * 2048 + k * 1024); } while (0)
; #define PG8_MMA(ai, bj, At, Bt) do { __builtin_amdgcn_s_setprio(1); _Pragma("unroll") for (int m = 0; m < 4; ++m) _Pragma("unroll") for (int n = 0; n < 2; ++n) _Pragma("unroll") for (int k = 0; k < 2; ++k) \
;         acc[ai][bj][m][n] = __builtin_amdgcn_mfma_f32_16x16x32_bf16(Bt[n][k], At[m][k], acc[ai][bj][m][n], 0, 0, 0); __builtin_amdgcn_s_setprio(0); } while (0)
; #define PG8_WAIT_V(n) asm volatile("s_waitcnt vmcnt(" #n ")" ::: "memory")
; #define PG8_WAIT_L(n) asm volatile("s_waitcnt lgkmcnt(" #n ")" ::: "memory")
; #define PG8_BAR __builtin_amdgcn_s_barrier()
; #define PG8_SCHED __builtin_amdgcn_sched_barrier(0)
; template <class Epi>
; __device__ __forceinline__ void gemm_phase(LAS unsigned char* lds, const Gemm g, const Sched& S, const Epi& E) {
;     ...
;             PG8_LDB(B1, 1, 1); PG8_STAGE(PG8_SB(1, 0), b3, voffB);
;             PG8_BAR; PG8_WAIT_L(0); PG8_MMA(0, 1, At, B1); PG8_BAR;
;             PG8_LDA(At, 1, 1); PG8_STAGE(PG8_SA(1, 0), a3, voffA);
;             PG8_BAR; PG8_WAIT_L(0); PG8_MMA(1, 0, At, B0); PG8_BAR; PG8_SCHED;
;             PG8_STAGE(PG8_SB(1, 1), b3 + hstepB, voffB);
;             PG8_WAIT_V(6); PG8_BAR; PG8_MMA(1, 1, At, B1); PG8_BAR;
;         }
	s_waitcnt lgkmcnt(0)
	s_setprio 1
	s_waitcnt lgkmcnt(0)
	v_mfma_f32_16x16x32_bf16 v[154:157], v[106:109], v[134:137], v[166:169]
	v_mfma_f32_16x16x32_bf16 v[174:177], v[110:113], v[138:141], v[154:157]
	v_mfma_f32_16x16x32_bf16 v[154:157], v[114:117], v[134:137], v[162:165]
	v_mfma_f32_16x16x32_bf16 v[94:97], v[106:109], v[142:145], v[94:97]
	v_mfma_f32_16x16x32_bf16 v[90:93], v[114:117], v[142:145], v[90:93]
	v_mfma_f32_16x16x32_bf16 v[78:81], v[106:109], v[150:153], v[78:81]
	v_mfma_f32_16x16x32_bf16 v[74:77], v[114:117], v[150:153], v[74:77]
	v_mfma_f32_16x16x32_bf16 v[162:165], v[118:121], v[138:141], v[154:157]
	v_mfma_f32_16x16x32_bf16 v[94:97], v[110:113], v[146:149], v[94:97]
	v_mfma_f32_16x16x32_bf16 v[90:93], v[118:121], v[146:149], v[90:93]
	v_mfma_f32_16x16x32_bf16 v[78:81], v[110:113], v[170:173], v[78:81]
	v_mfma_f32_16x16x32_bf16 v[74:77], v[118:121], v[170:173], v[74:77]
	s_setprio 0
	s_barrier
	s_add_i32 s4, 0, 0x1c000
	v_add_u32_e32 v178, s4, v217
	s_add_i32 s5, s8, s43
	ds_read_b128 v[154:157], v178
	ds_read_b128 v[158:161], v178 offset:1024
	ds_read_b128 v[166:169], v178 offset:2048
	ds_read_b128 v[206:209], v178 offset:3072
	v_lshl_add_u64 v[178:179], v[210:211], 0, s[60:61]
	s_mov_b32 m0, s5
	s_nop 0
	global_load_lds_dwordx4 v[178:179], off
	v_lshl_add_u64 v[178:179], v[212:213], 0, s[60:61]
	s_add_i32 m0, s5, 0x2000
	s_nop 0
	global_load_lds_dwordx4 v[178:179], off
	s_waitcnt lgkmcnt(0)
	v_mfma_f32_16x16x32_bf16 v[178:181], v[154:157], v[126:129], v[182:185]
	v_mfma_f32_16x16x32_bf16 v[122:125], v[166:169], v[126:129], v[122:125]
	v_mfma_f32_16x16x32_bf16 v[102:105], v[154:157], v[134:137], v[102:105]
	v_mfma_f32_16x16x32_bf16 v[98:101], v[166:169], v[134:137], v[98:101]
	s_barrier
	s_waitcnt lgkmcnt(0)
	s_setprio 1
	s_waitcnt lgkmcnt(0)
	v_mfma_f32_16x16x32_bf16 v[86:89], v[154:157], v[142:145], v[86:89]
	v_mfma_f32_16x16x32_bf16 v[82:85], v[166:169], v[142:145], v[82:85]
	v_mfma_f32_16x16x32_bf16 v[70:73], v[154:157], v[150:153], v[70:73]
	v_mfma_f32_16x16x32_bf16 v[66:69], v[166:169], v[150:153], v[66:69]
	v_mfma_f32_16x16x32_bf16 v[182:185], v[158:161], v[130:133], v[178:181]
	v_mfma_f32_16x16x32_bf16 v[178:181], v[206:209], v[130:133], v[122:125]
	v_mfma_f32_16x16x32_bf16 v[102:105], v[158:161], v[138:141], v[102:105]
	v_mfma_f32_16x16x32_bf16 v[98:101], v[206:209], v[138:141], v[98:101]
	v_mfma_f32_16x16x32_bf16 v[86:89], v[158:161], v[146:149], v[86:89]
	v_mfma_f32_16x16x32_bf16 v[82:85], v[206:209], v[146:149], v[82:85]
	v_mfma_f32_16x16x32_bf16 v[70:73], v[158:161], v[170:173], v[70:73]
	v_mfma_f32_16x16x32_bf16 v[66:69], v[206:209], v[170:173], v[66:69]
	s_setprio 0
	s_mov_b32 m0, s51
	v_lshl_add_u64 v[170:171], v[214:215], 0, s[60:61]
	s_barrier
	ds_read_b128 v[122:125], v235 offset:49152
	ds_read_b128 v[126:129], v235 offset:50176
	ds_read_b128 v[130:133], v235 offset:51200
	ds_read_b128 v[134:137], v235 offset:52224
	ds_read_b128 v[138:141], v235 offset:53248
	ds_read_b128 v[142:145], v235 offset:54272
	ds_read_b128 v[146:149], v235 offset:55296
	ds_read_b128 v[150:153], v235 offset:56320
	global_load_lds_dwordx4 v[170:171], off
	v_lshl_add_u64 v[170:171], v[222:223], 0, s[60:61]
	s_mov_b32 m0, s2
	s_nop 0
	global_load_lds_dwordx4 v[170:171], off
	s_waitcnt lgkmcnt(0)
	v_mfma_f32_16x16x32_bf16 v[62:65], v[106:109], v[122:125], v[62:65]
	v_mfma_f32_16x16x32_bf16 v[58:61], v[114:117], v[122:125], v[58:61]
	v_mfma_f32_16x16x32_bf16 v[46:49], v[106:109], v[130:133], v[46:49]
	v_mfma_f32_16x16x32_bf16 v[42:45], v[114:117], v[130:133], v[42:45]
	s_barrier
	s_waitcnt lgkmcnt(0)
	s_setprio 1
	s_waitcnt lgkmcnt(0)
	v_mfma_f32_16x16x32_bf16 v[30:33], v[106:109], v[138:141], v[30:33]
	v_mfma_f32_16x16x32_bf16 v[26:29], v[114:117], v[138:141], v[26:29]
	v_mfma_f32_16x16x32_bf16 v[14:17], v[106:109], v[146:149], v[14:17]
	v_mfma_f32_16x16x32_bf16 v[10:13], v[114:117], v[146:149], v[10:13]
	v_mfma_f32_16x16x32_bf16 v[62:65], v[110:113], v[126:129], v[62:65]
	v_mfma_f32_16x16x32_bf16 v[58:61], v[118:121], v[126:129], v[58:61]
	v_mfma_f32_16x16x32_bf16 v[46:49], v[110:113], v[134:137], v[46:49]
	v_mfma_f32_16x16x32_bf16 v[42:45], v[118:121], v[134:137], v[42:45]
	v_mfma_f32_16x16x32_bf16 v[30:33], v[110:113], v[142:145], v[30:33]
	v_mfma_f32_16x16x32_bf16 v[26:29], v[118:121], v[142:145], v[26:29]
	v_mfma_f32_16x16x32_bf16 v[14:17], v[110:113], v[150:153], v[14:17]
	v_mfma_f32_16x16x32_bf16 v[10:13], v[118:121], v[150:153], v[10:13]
	s_setprio 0
	s_barrier
	s_add_i32 s4, s4, s43
	v_lshl_add_u64 v[106:107], v[224:225], 0, s[60:61]
	s_mov_b32 m0, s4
	s_nop 0
	global_load_lds_dwordx4 v[106:107], off
	v_lshl_add_u64 v[106:107], v[226:227], 0, s[60:61]
	s_add_i32 m0, s4, 0x2000
	s_nop 0
	global_load_lds_dwordx4 v[106:107], off
	s_waitcnt vmcnt(6)
	s_waitcnt lgkmcnt(0)
	v_mfma_f32_16x16x32_bf16 v[54:57], v[154:157], v[122:125], v[54:57]
	v_mfma_f32_16x16x32_bf16 v[50:53], v[166:169], v[122:125], v[50:53]
	v_mfma_f32_16x16x32_bf16 v[38:41], v[154:157], v[130:133], v[38:41]
	v_mfma_f32_16x16x32_bf16 v[34:37], v[166:169], v[130:133], v[34:37]
	s_barrier
	s_setprio 1
	v_mfma_f32_16x16x32_bf16 v[22:25], v[154:157], v[138:141], v[22:25]
	v_mfma_f32_16x16x32_bf16 v[18:21], v[166:169], v[138:141], v[18:21]
	v_mfma_f32_16x16x32_bf16 v[6:9], v[154:157], v[146:149], v[6:9]
	v_mfma_f32_16x16x32_bf16 v[2:5], v[166:169], v[146:149], v[2:5]
	v_mfma_f32_16x16x32_bf16 v[54:57], v[158:161], v[126:129], v[54:57]
	v_mfma_f32_16x16x32_bf16 v[50:53], v[206:209], v[126:129], v[50:53]
	v_mfma_f32_16x16x32_bf16 v[38:41], v[158:161], v[134:137], v[38:41]
	v_mfma_f32_16x16x32_bf16 v[34:37], v[206:209], v[134:137], v[34:37]
	v_mfma_f32_16x16x32_bf16 v[22:25], v[158:161], v[142:145], v[22:25]
	v_mfma_f32_16x16x32_bf16 v[18:21], v[206:209], v[142:145], v[18:21]
	v_mfma_f32_16x16x32_bf16 v[6:9], v[158:161], v[150:153], v[6:9]
	v_mfma_f32_16x16x32_bf16 v[2:5], v[206:209], v[150:153], v[2:5]
	s_setprio 0
	s_add_u32 s0, s0, 0x100
	s_addc_u32 s1, s1, 0
	s_add_u32 s34, s34, 0x100
	s_addc_u32 s35, s35, 0
	s_cmp_ge_u32 s14, s73
	s_mov_b32 s4, s14
	s_barrier
	s_cbranch_scc0 .LBB0_719
	v_readfirstlane_b32 s98, v219
	s_nop 1
	s_bitcmp1_b32 s98, 8
	s_cbranch_scc1 .Lresync_x_719
	s_barrier
;     __device__ __forceinline__ void operator()(const Acc& acc, const Unit& u, int wr, int wc, int fr, int fq, const Pre& pre) const {
;         const int row0 = u.pm * 256 + wr * 64 + fr, col0 = u.pn * 256 + wc * 32 + 8 * fq;
;         const size_t zo = (size_t)(u.zb * sOb + u.zh * sOh);
; #pragma unroll
;         for (int ai = 0; ai < 2; ++ai) {
;             f32x4 bv[4][2][2];
;             if (base) {
; #pragma unroll
;                 for (int m = 0; m < 4; ++m) { const size_t off = zo + (size_t)(row0 + ai * 128 + m * 16) * ldc + col0;
; #pragma unroll
;                     for (int bj = 0; bj < 2; ++bj)
; #pragma unroll
;                         for (int n = 0; n < 2; ++n) bv[m][bj][n] = *(const f32x4*)(base + off + bj * 128 + n * 4); }
.Lresync_x_719:
	s_ashr_i32 s0, s42, 31
	s_ashr_i32 s4, s24, 31
	v_readlane_b32 s8, v253, 59
	s_mul_hi_u32 s1, s74, s42
	s_mul_i32 s0, s74, s0
	v_readlane_b32 s9, v253, 60
	s_mul_hi_u32 s5, s8, s24
	s_mul_i32 s4, s8, s4
	s_add_i32 s0, s1, s0
	s_mul_i32 s1, s75, s42
	s_add_i32 s4, s5, s4
	s_mul_i32 s5, s9, s24
	v_lshl_add_u32 v206, s97, 8, v216
	s_add_i32 s0, s0, s1
	s_mul_i32 s1, s74, s42
	s_add_i32 s4, s4, s5
	s_mul_i32 s5, s8, s24
	v_lshl_or_b32 v210, s96, 8, v234
	s_add_u32 s94, s1, s5
	v_ashrrev_i32_e32 v207, 31, v206
	s_addc_u32 s95, s0, s4
	v_ashrrev_i32_e32 v211, 31, v210
	s_mov_b64 s[0:1], -1
	s_and_b64 vcc, exec, s[78:79]
	v_mul_lo_u32 v208, s13, v206
	v_mul_lo_u32 v236, s12, v207
	v_or_b32_e32 v239, 16, v206
	v_or_b32_e32 v238, 32, v206
	v_or_b32_e32 v237, 48, v206
	s_cbranch_vccz .LBB0_722
	s_lshl_b64 s[0:1], s[94:95], 2
	v_readlane_b32 s4, v254, 7
	v_readlane_b32 s5, v254, 8
	s_add_u32 s0, s4, s0
	s_addc_u32 s1, s5, s1
	v_lshl_add_u64 v[154:155], v[210:211], 2, s[0:1]
	v_mad_u64_u32 v[212:213], s[0:1], s12, v206, 0
	v_mul_lo_u32 v124, s13, v239
	v_mad_u64_u32 v[122:123], s[0:1], s12, v239, 0
	v_mul_lo_u32 v140, s13, v238
	v_mad_u64_u32 v[138:139], s[0:1], s12, v238, 0
	v_mul_lo_u32 v158, s13, v237
	v_mad_u64_u32 v[156:157], s[0:1], s12, v237, 0
	v_add3_u32 v213, v213, v236, v208
	v_add3_u32 v123, v123, v236, v124
	v_add3_u32 v139, v139, v236, v140
	v_add3_u32 v157, v157, v236, v158
	v_lshl_add_u64 v[118:119], v[212:213], 2, v[154:155]
	v_lshl_add_u64 v[134:135], v[122:123], 2, v[154:155]
	v_lshl_add_u64 v[150:151], v[138:139], 2, v[154:155]
	v_lshl_add_u64 v[170:171], v[156:157], 2, v[154:155]
	flat_load_dwordx4 v[106:109], v[118:119]
	flat_load_dwordx4 v[110:113], v[118:119] offset:16
	flat_load_dwordx4 v[114:117], v[118:119] offset:512
	s_nop 0
	flat_load_dwordx4 v[118:121], v[118:119] offset:528
	s_nop 0
	flat_load_dwordx4 v[122:125], v[134:135]
	flat_load_dwordx4 v[126:129], v[134:135] offset:16
	flat_load_dwordx4 v[130:133], v[134:135] offset:512
	s_nop 0
	flat_load_dwordx4 v[134:137], v[134:135] offset:528
	s_nop 0
	flat_load_dwordx4 v[138:141], v[150:151]
	flat_load_dwordx4 v[142:145], v[150:151] offset:16
	flat_load_dwordx4 v[146:149], v[150:151] offset:512
	s_nop 0
	flat_load_dwordx4 v[150:153], v[150:151] offset:528
	s_nop 0
	flat_load_dwordx4 v[154:157], v[170:171]
	flat_load_dwordx4 v[158:161], v[170:171] offset:16
	flat_load_dwordx4 v[166:169], v[170:171] offset:512
	s_nop 0
	flat_load_dwordx4 v[170:173], v[170:171] offset:528
	s_mov_b64 s[0:1], 0

; #define PG8_WAIT_V(n) asm volatile("s_waitcnt vmcnt(" #n ")" ::: "memory")
; #define PG8_BAR __builtin_amdgcn_s_barrier()
; template <class Epi>
; __device__ __forceinline__ void gemm_phase(LAS unsigned char* lds, const Gemm g, const Sched& S, const Epi& E) {
;     ...
;     PG8_WAIT_V(0);
;     if (wr == 0) PG8_BAR;
;     PG8_BAR;
.LBB0_800:
	s_waitcnt vmcnt(0)
	v_readlane_b32 s0, v254, 35
	v_readlane_b32 s90, v254, 39
	s_cmpk_gt_u32 s0, 0xff
	v_readlane_b32 s58, v253, 45
	v_readlane_b32 s64, v253, 47
	v_readlane_b32 s72, v254, 41
	v_readlane_b32 s91, v254, 40
	v_readlane_b32 s59, v253, 46
	s_cbranch_scc1 .LBB0_802
.LBB0_802:
	v_readlane_b32 s82, v254, 43
	v_readlane_b32 s66, v254, 45
	s_barrier
	v_readlane_b32 s83, v254, 44
	v_readlane_b32 s57, v254, 37
	v_readlane_b32 s67, v254, 46
